# remove compiler vmcnt(0) before ds_read in 12 GEMM K-loops (restores source counted vmcnt(8) pipelining)
# speedup vs baseline: 1.0306x; 1.0306x over previous
.LBB0_435:
	ds_read_b128 v[164:167], v147
	ds_read_b128 v[168:171], v148
	ds_read_b128 v[172:175], v149
	ds_read_b128 v[176:179], v150
	ds_read_b128 v[180:183], v151
	ds_read_b128 v[184:187], v152
	ds_read_b128 v[188:191], v153
	ds_read_b128 v[192:195], v154
	s_add_i32 vcc_hi, s94, 2
	s_add_u32 s52, s92, 0x80
	s_addc_u32 s53, s93, 0
	s_cmp_eq_u32 s33, s94
	s_cselect_b32 s94, s0, s52
	s_cselect_b32 s95, s1, s53
	s_cselect_b32 s53, s83, vcc_lo
	s_cselect_b32 s52, s82, s91
	s_mov_b32 m0, s69
	v_lshl_add_u64 v[228:229], s[92:93], 0, v[136:137]
	ds_read_b128 v[196:199], v146
	ds_read_b128 v[200:203], v146 offset:1024
	ds_read_b128 v[204:207], v146 offset:2048
	ds_read_b128 v[208:211], v146 offset:3072
	ds_read_b128 v[212:215], v146 offset:4096
	ds_read_b128 v[216:219], v146 offset:5120
	ds_read_b128 v[220:223], v146 offset:6144
	ds_read_b128 v[224:227], v146 offset:7168
	global_load_lds_dwordx4 v[228:229], off
	v_lshl_add_u64 v[228:229], s[92:93], 0, v[138:139]
	s_mov_b32 m0, s72
	s_nop 0
	global_load_lds_dwordx4 v[228:229], off
	s_waitcnt vmcnt(8)
	s_waitcnt lgkmcnt(0)
	s_barrier
	s_setprio 1
	s_waitcnt lgkmcnt(0)
	v_mfma_f32_16x16x32_bf16 v[124:127], v[164:167], v[196:199], v[124:127]
	v_mfma_f32_16x16x32_bf16 v[116:119], v[172:175], v[196:199], v[116:119]
	v_mfma_f32_16x16x32_bf16 v[108:111], v[164:167], v[204:207], v[108:111]
	v_mfma_f32_16x16x32_bf16 v[100:103], v[172:175], v[204:207], v[100:103]
	v_mfma_f32_16x16x32_bf16 v[92:95], v[164:167], v[212:215], v[92:95]
	v_mfma_f32_16x16x32_bf16 v[84:87], v[172:175], v[212:215], v[84:87]
	v_mfma_f32_16x16x32_bf16 v[76:79], v[164:167], v[220:223], v[76:79]
	v_mfma_f32_16x16x32_bf16 v[68:71], v[172:175], v[220:223], v[68:71]
	v_mfma_f32_16x16x32_bf16 v[124:127], v[168:171], v[200:203], v[124:127]
	v_mfma_f32_16x16x32_bf16 v[116:119], v[176:179], v[200:203], v[116:119]
	v_mfma_f32_16x16x32_bf16 v[108:111], v[168:171], v[208:211], v[108:111]
	v_mfma_f32_16x16x32_bf16 v[100:103], v[176:179], v[208:211], v[100:103]
	v_mfma_f32_16x16x32_bf16 v[92:95], v[168:171], v[216:219], v[92:95]
	v_mfma_f32_16x16x32_bf16 v[84:87], v[176:179], v[216:219], v[84:87]
	v_mfma_f32_16x16x32_bf16 v[76:79], v[168:171], v[224:227], v[76:79]
	v_mfma_f32_16x16x32_bf16 v[68:71], v[176:179], v[224:227], v[68:71]
	s_setprio 0
	s_setprio 1
	v_mfma_f32_16x16x32_bf16 v[120:123], v[180:183], v[196:199], v[120:123]
	v_mfma_f32_16x16x32_bf16 v[112:115], v[188:191], v[196:199], v[112:115]
	v_mfma_f32_16x16x32_bf16 v[104:107], v[180:183], v[204:207], v[104:107]
	v_mfma_f32_16x16x32_bf16 v[96:99], v[188:191], v[204:207], v[96:99]
	v_mfma_f32_16x16x32_bf16 v[88:91], v[180:183], v[212:215], v[88:91]
	v_mfma_f32_16x16x32_bf16 v[80:83], v[188:191], v[212:215], v[80:83]
	v_mfma_f32_16x16x32_bf16 v[72:75], v[180:183], v[220:223], v[72:75]
	v_mfma_f32_16x16x32_bf16 v[64:67], v[188:191], v[220:223], v[64:67]
	v_mfma_f32_16x16x32_bf16 v[120:123], v[184:187], v[200:203], v[120:123]
	v_mfma_f32_16x16x32_bf16 v[112:115], v[192:195], v[200:203], v[112:115]
	v_mfma_f32_16x16x32_bf16 v[104:107], v[184:187], v[208:211], v[104:107]
	v_mfma_f32_16x16x32_bf16 v[96:99], v[192:195], v[208:211], v[96:99]
	v_mfma_f32_16x16x32_bf16 v[88:91], v[184:187], v[216:219], v[88:91]
	v_mfma_f32_16x16x32_bf16 v[80:83], v[192:195], v[216:219], v[80:83]
	v_mfma_f32_16x16x32_bf16 v[72:75], v[184:187], v[224:227], v[72:75]
	v_mfma_f32_16x16x32_bf16 v[64:67], v[192:195], v[224:227], v[64:67]
	s_setprio 0
	s_barrier
	s_mov_b32 m0, s17
	v_lshl_add_u64 v[228:229], s[52:53], 0, v[132:133]
	v_lshl_add_u64 v[230:231], s[52:53], 0, v[128:129]
	s_add_u32 s52, s52, s10
	ds_read_b128 v[196:199], v146 offset:16384
	ds_read_b128 v[200:203], v146 offset:17408
	ds_read_b128 v[204:207], v146 offset:18432
	ds_read_b128 v[208:211], v146 offset:19456
	ds_read_b128 v[212:215], v146 offset:20480
	ds_read_b128 v[216:219], v146 offset:21504
	ds_read_b128 v[220:223], v146 offset:22528
	ds_read_b128 v[224:227], v146 offset:23552
	global_load_lds_dwordx4 v[228:229], off
	s_mov_b32 m0, s18
	s_addc_u32 s53, s53, s11
	global_load_lds_dwordx4 v[230:231], off
	v_lshl_add_u64 v[232:233], s[52:53], 0, v[132:133]
	s_mov_b32 m0, s19
	v_lshl_add_u64 v[234:235], s[52:53], 0, v[128:129]
	global_load_lds_dwordx4 v[232:233], off
	s_mov_b32 m0, s20
	v_lshl_add_u64 v[236:237], s[94:95], 0, v[134:135]
	global_load_lds_dwordx4 v[234:235], off
	s_mov_b32 m0, s14
	v_lshl_add_u64 v[238:239], s[94:95], 0, v[130:131]
	global_load_lds_dwordx4 v[236:237], off
	s_mov_b32 m0, s21
	s_nop 0
	global_load_lds_dwordx4 v[238:239], off
	s_waitcnt vmcnt(8)
	s_waitcnt lgkmcnt(0)
	s_barrier
	s_setprio 1
	s_waitcnt lgkmcnt(0)
	v_mfma_f32_16x16x32_bf16 v[60:63], v[164:167], v[196:199], v[60:63]
	v_mfma_f32_16x16x32_bf16 v[52:55], v[172:175], v[196:199], v[52:55]
	v_mfma_f32_16x16x32_bf16 v[44:47], v[164:167], v[204:207], v[44:47]
	v_mfma_f32_16x16x32_bf16 v[36:39], v[172:175], v[204:207], v[36:39]
	v_mfma_f32_16x16x32_bf16 v[28:31], v[164:167], v[212:215], v[28:31]
	v_mfma_f32_16x16x32_bf16 v[20:23], v[172:175], v[212:215], v[20:23]
	v_mfma_f32_16x16x32_bf16 v[12:15], v[164:167], v[220:223], v[12:15]
	v_mfma_f32_16x16x32_bf16 v[4:7], v[172:175], v[220:223], v[4:7]
	v_mfma_f32_16x16x32_bf16 v[60:63], v[168:171], v[200:203], v[60:63]
	v_mfma_f32_16x16x32_bf16 v[52:55], v[176:179], v[200:203], v[52:55]
	v_mfma_f32_16x16x32_bf16 v[44:47], v[168:171], v[208:211], v[44:47]
	v_mfma_f32_16x16x32_bf16 v[36:39], v[176:179], v[208:211], v[36:39]
	v_mfma_f32_16x16x32_bf16 v[28:31], v[168:171], v[216:219], v[28:31]
	v_mfma_f32_16x16x32_bf16 v[20:23], v[176:179], v[216:219], v[20:23]
	v_mfma_f32_16x16x32_bf16 v[12:15], v[168:171], v[224:227], v[12:15]
	v_mfma_f32_16x16x32_bf16 v[4:7], v[176:179], v[224:227], v[4:7]
	s_setprio 0
	s_setprio 1
	v_mfma_f32_16x16x32_bf16 v[56:59], v[180:183], v[196:199], v[56:59]
	v_mfma_f32_16x16x32_bf16 v[48:51], v[188:191], v[196:199], v[48:51]
	v_mfma_f32_16x16x32_bf16 v[40:43], v[180:183], v[204:207], v[40:43]
	v_mfma_f32_16x16x32_bf16 v[32:35], v[188:191], v[204:207], v[32:35]
	v_mfma_f32_16x16x32_bf16 v[24:27], v[180:183], v[212:215], v[24:27]
	v_mfma_f32_16x16x32_bf16 v[16:19], v[188:191], v[212:215], v[16:19]
	v_mfma_f32_16x16x32_bf16 v[8:11], v[180:183], v[220:223], v[8:11]
	v_mfma_f32_16x16x32_bf16 v[0:3], v[188:191], v[220:223], v[0:3]
	v_mfma_f32_16x16x32_bf16 v[56:59], v[184:187], v[200:203], v[56:59]
	v_mfma_f32_16x16x32_bf16 v[48:51], v[192:195], v[200:203], v[48:51]
	v_mfma_f32_16x16x32_bf16 v[40:43], v[184:187], v[208:211], v[40:43]
	v_mfma_f32_16x16x32_bf16 v[32:35], v[192:195], v[208:211], v[32:35]
	v_mfma_f32_16x16x32_bf16 v[24:27], v[184:187], v[216:219], v[24:27]
	v_mfma_f32_16x16x32_bf16 v[16:19], v[192:195], v[216:219], v[16:19]
	v_mfma_f32_16x16x32_bf16 v[8:11], v[184:187], v[224:227], v[8:11]
	v_mfma_f32_16x16x32_bf16 v[0:3], v[192:195], v[224:227], v[0:3]
	s_setprio 0
	s_barrier
	ds_read_b128 v[164:167], v155
	ds_read_b128 v[168:171], v156
	ds_read_b128 v[172:175], v157
	ds_read_b128 v[176:179], v158
	ds_read_b128 v[180:183], v159
	ds_read_b128 v[184:187], v160
	ds_read_b128 v[188:191], v161
	ds_read_b128 v[192:195], v163
	s_add_u32 s52, s94, s8
	s_addc_u32 s53, s95, s9
	s_mov_b32 m0, s22
	v_lshl_add_u64 v[240:241], s[52:53], 0, v[134:135]
	ds_read_b128 v[196:199], v146 offset:32768
	ds_read_b128 v[200:203], v146 offset:33792
	ds_read_b128 v[204:207], v146 offset:34816
	ds_read_b128 v[208:211], v146 offset:35840
	ds_read_b128 v[212:215], v146 offset:36864
	ds_read_b128 v[216:219], v146 offset:37888
	ds_read_b128 v[220:223], v146 offset:38912
	ds_read_b128 v[224:227], v146 offset:39936
	global_load_lds_dwordx4 v[240:241], off
	v_lshl_add_u64 v[240:241], s[52:53], 0, v[130:131]
	s_mov_b32 m0, s23
	s_nop 0
	global_load_lds_dwordx4 v[240:241], off
	s_waitcnt vmcnt(8)
	s_waitcnt lgkmcnt(0)
	s_barrier
	s_setprio 1
	s_waitcnt lgkmcnt(0)
	v_mfma_f32_16x16x32_bf16 v[124:127], v[164:167], v[196:199], v[124:127]
	v_mfma_f32_16x16x32_bf16 v[116:119], v[172:175], v[196:199], v[116:119]
	v_mfma_f32_16x16x32_bf16 v[108:111], v[164:167], v[204:207], v[108:111]
	v_mfma_f32_16x16x32_bf16 v[100:103], v[172:175], v[204:207], v[100:103]
	v_mfma_f32_16x16x32_bf16 v[92:95], v[164:167], v[212:215], v[92:95]
	v_mfma_f32_16x16x32_bf16 v[84:87], v[172:175], v[212:215], v[84:87]
	v_mfma_f32_16x16x32_bf16 v[76:79], v[164:167], v[220:223], v[76:79]
	v_mfma_f32_16x16x32_bf16 v[68:71], v[172:175], v[220:223], v[68:71]
	v_mfma_f32_16x16x32_bf16 v[124:127], v[168:171], v[200:203], v[124:127]
	v_mfma_f32_16x16x32_bf16 v[116:119], v[176:179], v[200:203], v[116:119]
	v_mfma_f32_16x16x32_bf16 v[108:111], v[168:171], v[208:211], v[108:111]
	v_mfma_f32_16x16x32_bf16 v[100:103], v[176:179], v[208:211], v[100:103]
	v_mfma_f32_16x16x32_bf16 v[92:95], v[168:171], v[216:219], v[92:95]
	v_mfma_f32_16x16x32_bf16 v[84:87], v[176:179], v[216:219], v[84:87]
	v_mfma_f32_16x16x32_bf16 v[76:79], v[168:171], v[224:227], v[76:79]
	v_mfma_f32_16x16x32_bf16 v[68:71], v[176:179], v[224:227], v[68:71]
	s_setprio 0
	s_setprio 1
	v_mfma_f32_16x16x32_bf16 v[120:123], v[180:183], v[196:199], v[120:123]
	v_mfma_f32_16x16x32_bf16 v[112:115], v[188:191], v[196:199], v[112:115]
	v_mfma_f32_16x16x32_bf16 v[104:107], v[180:183], v[204:207], v[104:107]
	v_mfma_f32_16x16x32_bf16 v[96:99], v[188:191], v[204:207], v[96:99]
	v_mfma_f32_16x16x32_bf16 v[88:91], v[180:183], v[212:215], v[88:91]
	v_mfma_f32_16x16x32_bf16 v[80:83], v[188:191], v[212:215], v[80:83]
	v_mfma_f32_16x16x32_bf16 v[72:75], v[180:183], v[220:223], v[72:75]
	v_mfma_f32_16x16x32_bf16 v[64:67], v[188:191], v[220:223], v[64:67]
	v_mfma_f32_16x16x32_bf16 v[120:123], v[184:187], v[200:203], v[120:123]
	v_mfma_f32_16x16x32_bf16 v[112:115], v[192:195], v[200:203], v[112:115]
	v_mfma_f32_16x16x32_bf16 v[104:107], v[184:187], v[208:211], v[104:107]
	v_mfma_f32_16x16x32_bf16 v[96:99], v[192:195], v[208:211], v[96:99]
	v_mfma_f32_16x16x32_bf16 v[88:91], v[184:187], v[216:219], v[88:91]
	v_mfma_f32_16x16x32_bf16 v[80:83], v[192:195], v[216:219], v[80:83]
	v_mfma_f32_16x16x32_bf16 v[72:75], v[184:187], v[224:227], v[72:75]
	v_mfma_f32_16x16x32_bf16 v[64:67], v[192:195], v[224:227], v[64:67]
	s_setprio 0
	s_barrier
	s_mov_b32 m0, s24
	v_lshl_add_u64 v[228:229], v[228:229], 0, s[76:77]
	ds_read_b128 v[196:199], v146 offset:49152
	ds_read_b128 v[200:203], v146 offset:50176
	ds_read_b128 v[204:207], v146 offset:51200
	ds_read_b128 v[208:211], v146 offset:52224
	ds_read_b128 v[212:215], v146 offset:53248
	ds_read_b128 v[216:219], v146 offset:54272
	ds_read_b128 v[220:223], v146 offset:55296
	ds_read_b128 v[224:227], v146 offset:56320
	global_load_lds_dwordx4 v[228:229], off
	v_lshl_add_u64 v[228:229], v[230:231], 0, s[76:77]
	s_mov_b32 m0, s25
	s_nop 0
	global_load_lds_dwordx4 v[228:229], off
	v_lshl_add_u64 v[228:229], v[232:233], 0, s[76:77]
	s_mov_b32 m0, s28
	s_nop 0
	global_load_lds_dwordx4 v[228:229], off
	v_lshl_add_u64 v[228:229], v[234:235], 0, s[76:77]
	s_mov_b32 m0, s29
	s_nop 0
	global_load_lds_dwordx4 v[228:229], off
	v_lshl_add_u64 v[228:229], v[236:237], 0, s[76:77]
	s_mov_b32 m0, s26
	s_nop 0
	global_load_lds_dwordx4 v[228:229], off
	v_lshl_add_u64 v[228:229], v[238:239], 0, s[76:77]
	s_mov_b32 m0, s27
	s_nop 0
	global_load_lds_dwordx4 v[228:229], off
	s_waitcnt vmcnt(8)
	s_waitcnt lgkmcnt(0)
	s_barrier
	s_setprio 1
	s_waitcnt lgkmcnt(0)
	v_mfma_f32_16x16x32_bf16 v[60:63], v[164:167], v[196:199], v[60:63]
	v_mfma_f32_16x16x32_bf16 v[52:55], v[172:175], v[196:199], v[52:55]
	v_mfma_f32_16x16x32_bf16 v[44:47], v[164:167], v[204:207], v[44:47]
	v_mfma_f32_16x16x32_bf16 v[36:39], v[172:175], v[204:207], v[36:39]
	v_mfma_f32_16x16x32_bf16 v[28:31], v[164:167], v[212:215], v[28:31]
	v_mfma_f32_16x16x32_bf16 v[20:23], v[172:175], v[212:215], v[20:23]
	v_mfma_f32_16x16x32_bf16 v[12:15], v[164:167], v[220:223], v[12:15]
	v_mfma_f32_16x16x32_bf16 v[4:7], v[172:175], v[220:223], v[4:7]
	v_mfma_f32_16x16x32_bf16 v[60:63], v[168:171], v[200:203], v[60:63]
	v_mfma_f32_16x16x32_bf16 v[52:55], v[176:179], v[200:203], v[52:55]
	v_mfma_f32_16x16x32_bf16 v[44:47], v[168:171], v[208:211], v[44:47]
	v_mfma_f32_16x16x32_bf16 v[36:39], v[176:179], v[208:211], v[36:39]
	v_mfma_f32_16x16x32_bf16 v[28:31], v[168:171], v[216:219], v[28:31]
	v_mfma_f32_16x16x32_bf16 v[20:23], v[176:179], v[216:219], v[20:23]
	v_mfma_f32_16x16x32_bf16 v[12:15], v[168:171], v[224:227], v[12:15]
	v_mfma_f32_16x16x32_bf16 v[4:7], v[176:179], v[224:227], v[4:7]
	s_setprio 0
	s_setprio 1
	v_mfma_f32_16x16x32_bf16 v[56:59], v[180:183], v[196:199], v[56:59]
	v_mfma_f32_16x16x32_bf16 v[48:51], v[188:191], v[196:199], v[48:51]
	v_mfma_f32_16x16x32_bf16 v[40:43], v[180:183], v[204:207], v[40:43]
	v_mfma_f32_16x16x32_bf16 v[32:35], v[188:191], v[204:207], v[32:35]
	v_mfma_f32_16x16x32_bf16 v[24:27], v[180:183], v[212:215], v[24:27]
	v_mfma_f32_16x16x32_bf16 v[16:19], v[188:191], v[212:215], v[16:19]
	v_mfma_f32_16x16x32_bf16 v[8:11], v[180:183], v[220:223], v[8:11]
	v_mfma_f32_16x16x32_bf16 v[0:3], v[188:191], v[220:223], v[0:3]
	v_mfma_f32_16x16x32_bf16 v[56:59], v[184:187], v[200:203], v[56:59]
	v_mfma_f32_16x16x32_bf16 v[48:51], v[192:195], v[200:203], v[48:51]
	v_mfma_f32_16x16x32_bf16 v[40:43], v[184:187], v[208:211], v[40:43]
	v_mfma_f32_16x16x32_bf16 v[32:35], v[192:195], v[208:211], v[32:35]
	v_mfma_f32_16x16x32_bf16 v[24:27], v[184:187], v[216:219], v[24:27]
	v_mfma_f32_16x16x32_bf16 v[16:19], v[192:195], v[216:219], v[16:19]
	v_mfma_f32_16x16x32_bf16 v[8:11], v[184:187], v[224:227], v[8:11]
	v_mfma_f32_16x16x32_bf16 v[0:3], v[192:195], v[224:227], v[0:3]
	s_setprio 0
	s_barrier
	s_add_u32 s92, s92, 0x100
	s_addc_u32 s93, s93, 0
	s_add_u32 s91, s91, 0x100
	s_addc_u32 vcc_lo, vcc_lo, 0
	s_cmp_ge_i32 vcc_hi, s30
	s_mov_b32 s94, vcc_hi
	s_cbranch_scc0 .LBB0_435

.LBB0_837:
	ds_read_b128 v[168:171], v149
	ds_read_b128 v[172:175], v150
	ds_read_b128 v[176:179], v151
	ds_read_b128 v[180:183], v152
	ds_read_b128 v[184:187], v153
	ds_read_b128 v[188:191], v154
	ds_read_b128 v[192:195], v155
	ds_read_b128 v[196:199], v156
	s_add_i32 s96, s76, 2
	s_add_u32 s52, s74, 0x80
	s_addc_u32 s53, s75, 0
	s_cmp_eq_u32 s79, s76
	s_cselect_b32 s76, s0, s52
	s_cselect_b32 s77, s1, s53
	s_cselect_b32 s53, s71, s9
	s_cselect_b32 s52, s70, s3
	s_mov_b32 m0, s90
	v_lshl_add_u64 v[144:145], s[74:75], 0, v[136:137]
	ds_read_b128 v[200:203], v148
	ds_read_b128 v[204:207], v148 offset:1024
	ds_read_b128 v[208:211], v148 offset:2048
	ds_read_b128 v[212:215], v148 offset:3072
	ds_read_b128 v[216:219], v148 offset:4096
	ds_read_b128 v[220:223], v148 offset:5120
	ds_read_b128 v[224:227], v148 offset:6144
	ds_read_b128 v[228:231], v148 offset:7168
	global_load_lds_dwordx4 v[144:145], off
	v_lshl_add_u64 v[144:145], s[74:75], 0, v[138:139]
	s_mov_b32 m0, s91
	s_nop 0
	global_load_lds_dwordx4 v[144:145], off
	s_waitcnt vmcnt(8)
	s_waitcnt lgkmcnt(0)
	s_barrier
	s_setprio 1
	s_waitcnt lgkmcnt(0)
	v_mfma_f32_16x16x32_bf16 v[124:127], v[168:171], v[200:203], v[124:127]
	v_mfma_f32_16x16x32_bf16 v[120:123], v[176:179], v[200:203], v[120:123]
	v_mfma_f32_16x16x32_bf16 v[108:111], v[168:171], v[208:211], v[108:111]
	v_mfma_f32_16x16x32_bf16 v[104:107], v[176:179], v[208:211], v[104:107]
	v_mfma_f32_16x16x32_bf16 v[92:95], v[168:171], v[216:219], v[92:95]
	v_mfma_f32_16x16x32_bf16 v[88:91], v[176:179], v[216:219], v[88:91]
	v_mfma_f32_16x16x32_bf16 v[76:79], v[168:171], v[224:227], v[76:79]
	v_mfma_f32_16x16x32_bf16 v[72:75], v[176:179], v[224:227], v[72:75]
	v_mfma_f32_16x16x32_bf16 v[124:127], v[172:175], v[204:207], v[124:127]
	v_mfma_f32_16x16x32_bf16 v[120:123], v[180:183], v[204:207], v[120:123]
	v_mfma_f32_16x16x32_bf16 v[108:111], v[172:175], v[212:215], v[108:111]
	v_mfma_f32_16x16x32_bf16 v[104:107], v[180:183], v[212:215], v[104:107]
	v_mfma_f32_16x16x32_bf16 v[92:95], v[172:175], v[220:223], v[92:95]
	v_mfma_f32_16x16x32_bf16 v[88:91], v[180:183], v[220:223], v[88:91]
	v_mfma_f32_16x16x32_bf16 v[76:79], v[172:175], v[228:231], v[76:79]
	v_mfma_f32_16x16x32_bf16 v[72:75], v[180:183], v[228:231], v[72:75]
	s_setprio 0
	s_setprio 1
	v_mfma_f32_16x16x32_bf16 v[116:119], v[184:187], v[200:203], v[116:119]
	v_mfma_f32_16x16x32_bf16 v[112:115], v[192:195], v[200:203], v[112:115]
	v_mfma_f32_16x16x32_bf16 v[100:103], v[184:187], v[208:211], v[100:103]
	v_mfma_f32_16x16x32_bf16 v[96:99], v[192:195], v[208:211], v[96:99]
	v_mfma_f32_16x16x32_bf16 v[84:87], v[184:187], v[216:219], v[84:87]
	v_mfma_f32_16x16x32_bf16 v[80:83], v[192:195], v[216:219], v[80:83]
	v_mfma_f32_16x16x32_bf16 v[68:71], v[184:187], v[224:227], v[68:71]
	v_mfma_f32_16x16x32_bf16 v[64:67], v[192:195], v[224:227], v[64:67]
	v_mfma_f32_16x16x32_bf16 v[116:119], v[188:191], v[204:207], v[116:119]
	v_mfma_f32_16x16x32_bf16 v[112:115], v[196:199], v[204:207], v[112:115]
	v_mfma_f32_16x16x32_bf16 v[100:103], v[188:191], v[212:215], v[100:103]
	v_mfma_f32_16x16x32_bf16 v[96:99], v[196:199], v[212:215], v[96:99]
	v_mfma_f32_16x16x32_bf16 v[84:87], v[188:191], v[220:223], v[84:87]
	v_mfma_f32_16x16x32_bf16 v[80:83], v[196:199], v[220:223], v[80:83]
	v_mfma_f32_16x16x32_bf16 v[68:71], v[188:191], v[228:231], v[68:71]
	v_mfma_f32_16x16x32_bf16 v[64:67], v[196:199], v[228:231], v[64:67]
	s_setprio 0
	s_barrier
	s_mov_b32 m0, s19
	v_lshl_add_u64 v[144:145], s[52:53], 0, v[130:131]
	v_lshl_add_u64 v[232:233], s[52:53], 0, v[134:135]
	s_add_u32 s52, s52, s12
	ds_read_b128 v[200:203], v148 offset:16384
	ds_read_b128 v[204:207], v148 offset:17408
	ds_read_b128 v[208:211], v148 offset:18432
	ds_read_b128 v[212:215], v148 offset:19456
	ds_read_b128 v[216:219], v148 offset:20480
	ds_read_b128 v[220:223], v148 offset:21504
	ds_read_b128 v[224:227], v148 offset:22528
	ds_read_b128 v[228:231], v148 offset:23552
	global_load_lds_dwordx4 v[144:145], off
	s_mov_b32 m0, s20
	s_addc_u32 s53, s53, s13
	global_load_lds_dwordx4 v[232:233], off
	v_lshl_add_u64 v[234:235], s[52:53], 0, v[130:131]
	s_mov_b32 m0, s21
	v_lshl_add_u64 v[236:237], s[52:53], 0, v[134:135]
	global_load_lds_dwordx4 v[234:235], off
	s_mov_b32 m0, s28
	v_lshl_add_u64 v[238:239], s[76:77], 0, v[128:129]
	global_load_lds_dwordx4 v[236:237], off
	s_mov_b32 m0, s18
	v_lshl_add_u64 v[240:241], s[76:77], 0, v[132:133]
	global_load_lds_dwordx4 v[238:239], off
	s_mov_b32 m0, s29
	s_nop 0
	global_load_lds_dwordx4 v[240:241], off
	s_waitcnt vmcnt(8)
	s_waitcnt lgkmcnt(0)
	s_barrier
	s_setprio 1
	s_waitcnt lgkmcnt(0)
	v_mfma_f32_16x16x32_bf16 v[60:63], v[168:171], v[200:203], v[60:63]
	v_mfma_f32_16x16x32_bf16 v[56:59], v[176:179], v[200:203], v[56:59]
	v_mfma_f32_16x16x32_bf16 v[44:47], v[168:171], v[208:211], v[44:47]
	v_mfma_f32_16x16x32_bf16 v[40:43], v[176:179], v[208:211], v[40:43]
	v_mfma_f32_16x16x32_bf16 v[28:31], v[168:171], v[216:219], v[28:31]
	v_mfma_f32_16x16x32_bf16 v[24:27], v[176:179], v[216:219], v[24:27]
	v_mfma_f32_16x16x32_bf16 v[12:15], v[168:171], v[224:227], v[12:15]
	v_mfma_f32_16x16x32_bf16 v[8:11], v[176:179], v[224:227], v[8:11]
	v_mfma_f32_16x16x32_bf16 v[60:63], v[172:175], v[204:207], v[60:63]
	v_mfma_f32_16x16x32_bf16 v[56:59], v[180:183], v[204:207], v[56:59]
	v_mfma_f32_16x16x32_bf16 v[44:47], v[172:175], v[212:215], v[44:47]
	v_mfma_f32_16x16x32_bf16 v[40:43], v[180:183], v[212:215], v[40:43]
	v_mfma_f32_16x16x32_bf16 v[28:31], v[172:175], v[220:223], v[28:31]
	v_mfma_f32_16x16x32_bf16 v[24:27], v[180:183], v[220:223], v[24:27]
	v_mfma_f32_16x16x32_bf16 v[12:15], v[172:175], v[228:231], v[12:15]
	v_mfma_f32_16x16x32_bf16 v[8:11], v[180:183], v[228:231], v[8:11]
	s_setprio 0
	s_setprio 1
	v_mfma_f32_16x16x32_bf16 v[52:55], v[184:187], v[200:203], v[52:55]
	v_mfma_f32_16x16x32_bf16 v[48:51], v[192:195], v[200:203], v[48:51]
	v_mfma_f32_16x16x32_bf16 v[36:39], v[184:187], v[208:211], v[36:39]
	v_mfma_f32_16x16x32_bf16 v[32:35], v[192:195], v[208:211], v[32:35]
	v_mfma_f32_16x16x32_bf16 v[20:23], v[184:187], v[216:219], v[20:23]
	v_mfma_f32_16x16x32_bf16 v[16:19], v[192:195], v[216:219], v[16:19]
	v_mfma_f32_16x16x32_bf16 v[4:7], v[184:187], v[224:227], v[4:7]
	v_mfma_f32_16x16x32_bf16 v[0:3], v[192:195], v[224:227], v[0:3]
	v_mfma_f32_16x16x32_bf16 v[52:55], v[188:191], v[204:207], v[52:55]
	v_mfma_f32_16x16x32_bf16 v[48:51], v[196:199], v[204:207], v[48:51]
	v_mfma_f32_16x16x32_bf16 v[36:39], v[188:191], v[212:215], v[36:39]
	v_mfma_f32_16x16x32_bf16 v[32:35], v[196:199], v[212:215], v[32:35]
	v_mfma_f32_16x16x32_bf16 v[20:23], v[188:191], v[220:223], v[20:23]
	v_mfma_f32_16x16x32_bf16 v[16:19], v[196:199], v[220:223], v[16:19]
	v_mfma_f32_16x16x32_bf16 v[4:7], v[188:191], v[228:231], v[4:7]
	v_mfma_f32_16x16x32_bf16 v[0:3], v[196:199], v[228:231], v[0:3]
	s_setprio 0
	s_barrier
	ds_read_b128 v[168:171], v157
	ds_read_b128 v[172:175], v158
	ds_read_b128 v[176:179], v159
	ds_read_b128 v[180:183], v160
	ds_read_b128 v[184:187], v161
	ds_read_b128 v[188:191], v163
	ds_read_b128 v[192:195], v164
	ds_read_b128 v[196:199], v165
	s_add_u32 s52, s76, s10
	s_addc_u32 s53, s77, s11
	s_mov_b32 m0, s30
	v_lshl_add_u64 v[242:243], s[52:53], 0, v[128:129]
	ds_read_b128 v[200:203], v148 offset:32768
	ds_read_b128 v[204:207], v148 offset:33792
	ds_read_b128 v[208:211], v148 offset:34816
	ds_read_b128 v[212:215], v148 offset:35840
	ds_read_b128 v[216:219], v148 offset:36864
	ds_read_b128 v[220:223], v148 offset:37888
	ds_read_b128 v[224:227], v148 offset:38912
	ds_read_b128 v[228:231], v148 offset:39936
	global_load_lds_dwordx4 v[242:243], off
	v_lshl_add_u64 v[242:243], s[52:53], 0, v[132:133]
	s_mov_b32 m0, s31
	s_nop 0
	global_load_lds_dwordx4 v[242:243], off
	s_waitcnt vmcnt(8)
	s_waitcnt lgkmcnt(0)
	s_barrier
	s_setprio 1
	s_waitcnt lgkmcnt(0)
	v_mfma_f32_16x16x32_bf16 v[124:127], v[168:171], v[200:203], v[124:127]
	v_mfma_f32_16x16x32_bf16 v[120:123], v[176:179], v[200:203], v[120:123]
	v_mfma_f32_16x16x32_bf16 v[108:111], v[168:171], v[208:211], v[108:111]
	v_mfma_f32_16x16x32_bf16 v[104:107], v[176:179], v[208:211], v[104:107]
	v_mfma_f32_16x16x32_bf16 v[92:95], v[168:171], v[216:219], v[92:95]
	v_mfma_f32_16x16x32_bf16 v[88:91], v[176:179], v[216:219], v[88:91]
	v_mfma_f32_16x16x32_bf16 v[76:79], v[168:171], v[224:227], v[76:79]
	v_mfma_f32_16x16x32_bf16 v[72:75], v[176:179], v[224:227], v[72:75]
	v_mfma_f32_16x16x32_bf16 v[124:127], v[172:175], v[204:207], v[124:127]
	v_mfma_f32_16x16x32_bf16 v[120:123], v[180:183], v[204:207], v[120:123]
	v_mfma_f32_16x16x32_bf16 v[108:111], v[172:175], v[212:215], v[108:111]
	v_mfma_f32_16x16x32_bf16 v[104:107], v[180:183], v[212:215], v[104:107]
	v_mfma_f32_16x16x32_bf16 v[92:95], v[172:175], v[220:223], v[92:95]
	v_mfma_f32_16x16x32_bf16 v[88:91], v[180:183], v[220:223], v[88:91]
	v_mfma_f32_16x16x32_bf16 v[76:79], v[172:175], v[228:231], v[76:79]
	v_mfma_f32_16x16x32_bf16 v[72:75], v[180:183], v[228:231], v[72:75]
	s_setprio 0
	s_setprio 1
	v_mfma_f32_16x16x32_bf16 v[116:119], v[184:187], v[200:203], v[116:119]
	v_mfma_f32_16x16x32_bf16 v[112:115], v[192:195], v[200:203], v[112:115]
	v_mfma_f32_16x16x32_bf16 v[100:103], v[184:187], v[208:211], v[100:103]
	v_mfma_f32_16x16x32_bf16 v[96:99], v[192:195], v[208:211], v[96:99]
	v_mfma_f32_16x16x32_bf16 v[84:87], v[184:187], v[216:219], v[84:87]
	v_mfma_f32_16x16x32_bf16 v[80:83], v[192:195], v[216:219], v[80:83]
	v_mfma_f32_16x16x32_bf16 v[68:71], v[184:187], v[224:227], v[68:71]
	v_mfma_f32_16x16x32_bf16 v[64:67], v[192:195], v[224:227], v[64:67]
	v_mfma_f32_16x16x32_bf16 v[116:119], v[188:191], v[204:207], v[116:119]
	v_mfma_f32_16x16x32_bf16 v[112:115], v[196:199], v[204:207], v[112:115]
	v_mfma_f32_16x16x32_bf16 v[100:103], v[188:191], v[212:215], v[100:103]
	v_mfma_f32_16x16x32_bf16 v[96:99], v[196:199], v[212:215], v[96:99]
	v_mfma_f32_16x16x32_bf16 v[84:87], v[188:191], v[220:223], v[84:87]
	v_mfma_f32_16x16x32_bf16 v[80:83], v[196:199], v[220:223], v[80:83]
	v_mfma_f32_16x16x32_bf16 v[68:71], v[188:191], v[228:231], v[68:71]
	v_mfma_f32_16x16x32_bf16 v[64:67], v[196:199], v[228:231], v[64:67]
	s_setprio 0
	s_barrier
	s_mov_b32 m0, s33
	v_lshl_add_u64 v[144:145], v[144:145], 0, s[26:27]
	ds_read_b128 v[200:203], v148 offset:49152
	ds_read_b128 v[204:207], v148 offset:50176
	ds_read_b128 v[208:211], v148 offset:51200
	ds_read_b128 v[212:215], v148 offset:52224
	ds_read_b128 v[216:219], v148 offset:53248
	ds_read_b128 v[220:223], v148 offset:54272
	ds_read_b128 v[224:227], v148 offset:55296
	ds_read_b128 v[228:231], v148 offset:56320
	global_load_lds_dwordx4 v[144:145], off
	v_lshl_add_u64 v[144:145], v[232:233], 0, s[26:27]
	s_mov_b32 m0, s34
	s_nop 0
	global_load_lds_dwordx4 v[144:145], off
	v_lshl_add_u64 v[144:145], v[234:235], 0, s[26:27]
	s_mov_b32 m0, s69
	s_nop 0
	global_load_lds_dwordx4 v[144:145], off
	v_lshl_add_u64 v[144:145], v[236:237], 0, s[26:27]
	s_mov_b32 m0, s72
	s_nop 0
	global_load_lds_dwordx4 v[144:145], off
	v_lshl_add_u64 v[144:145], v[238:239], 0, s[26:27]
	s_mov_b32 m0, s35
	s_nop 0
	global_load_lds_dwordx4 v[144:145], off
	v_lshl_add_u64 v[144:145], v[240:241], 0, s[26:27]
	s_mov_b32 m0, s68
	s_nop 0
	global_load_lds_dwordx4 v[144:145], off
	s_waitcnt vmcnt(8)
	s_waitcnt lgkmcnt(0)
	s_barrier
	s_setprio 1
	s_waitcnt lgkmcnt(0)
	v_mfma_f32_16x16x32_bf16 v[60:63], v[168:171], v[200:203], v[60:63]
	v_mfma_f32_16x16x32_bf16 v[56:59], v[176:179], v[200:203], v[56:59]
	v_mfma_f32_16x16x32_bf16 v[44:47], v[168:171], v[208:211], v[44:47]
	v_mfma_f32_16x16x32_bf16 v[40:43], v[176:179], v[208:211], v[40:43]
	v_mfma_f32_16x16x32_bf16 v[28:31], v[168:171], v[216:219], v[28:31]
	v_mfma_f32_16x16x32_bf16 v[24:27], v[176:179], v[216:219], v[24:27]
	v_mfma_f32_16x16x32_bf16 v[12:15], v[168:171], v[224:227], v[12:15]
	v_mfma_f32_16x16x32_bf16 v[8:11], v[176:179], v[224:227], v[8:11]
	v_mfma_f32_16x16x32_bf16 v[60:63], v[172:175], v[204:207], v[60:63]
	v_mfma_f32_16x16x32_bf16 v[56:59], v[180:183], v[204:207], v[56:59]
	v_mfma_f32_16x16x32_bf16 v[44:47], v[172:175], v[212:215], v[44:47]
	v_mfma_f32_16x16x32_bf16 v[40:43], v[180:183], v[212:215], v[40:43]
	v_mfma_f32_16x16x32_bf16 v[28:31], v[172:175], v[220:223], v[28:31]
	v_mfma_f32_16x16x32_bf16 v[24:27], v[180:183], v[220:223], v[24:27]
	v_mfma_f32_16x16x32_bf16 v[12:15], v[172:175], v[228:231], v[12:15]
	v_mfma_f32_16x16x32_bf16 v[8:11], v[180:183], v[228:231], v[8:11]
	s_setprio 0
	s_setprio 1
	v_mfma_f32_16x16x32_bf16 v[52:55], v[184:187], v[200:203], v[52:55]
	v_mfma_f32_16x16x32_bf16 v[48:51], v[192:195], v[200:203], v[48:51]
	v_mfma_f32_16x16x32_bf16 v[36:39], v[184:187], v[208:211], v[36:39]
	v_mfma_f32_16x16x32_bf16 v[32:35], v[192:195], v[208:211], v[32:35]
	v_mfma_f32_16x16x32_bf16 v[20:23], v[184:187], v[216:219], v[20:23]
	v_mfma_f32_16x16x32_bf16 v[16:19], v[192:195], v[216:219], v[16:19]
	v_mfma_f32_16x16x32_bf16 v[4:7], v[184:187], v[224:227], v[4:7]
	v_mfma_f32_16x16x32_bf16 v[0:3], v[192:195], v[224:227], v[0:3]
	v_mfma_f32_16x16x32_bf16 v[52:55], v[188:191], v[204:207], v[52:55]
	v_mfma_f32_16x16x32_bf16 v[48:51], v[196:199], v[204:207], v[48:51]
	v_mfma_f32_16x16x32_bf16 v[36:39], v[188:191], v[212:215], v[36:39]
	v_mfma_f32_16x16x32_bf16 v[32:35], v[196:199], v[212:215], v[32:35]
	v_mfma_f32_16x16x32_bf16 v[20:23], v[188:191], v[220:223], v[20:23]
	v_mfma_f32_16x16x32_bf16 v[16:19], v[196:199], v[220:223], v[16:19]
	v_mfma_f32_16x16x32_bf16 v[4:7], v[188:191], v[228:231], v[4:7]
	v_mfma_f32_16x16x32_bf16 v[0:3], v[196:199], v[228:231], v[0:3]
	s_setprio 0
	s_barrier
	s_add_u32 s74, s74, 0x100
	s_addc_u32 s75, s75, 0
	s_add_u32 s3, s3, 0x100
	s_addc_u32 s9, s9, 0
	s_cmp_ge_i32 s96, s73
	s_mov_b32 s76, s96
	s_cbranch_scc0 .LBB0_837

.LBB0_865:
	ds_read_b128 v[164:167], v143
	ds_read_b128 v[168:171], v144
	ds_read_b128 v[172:175], v145
	ds_read_b128 v[176:179], v146
	ds_read_b128 v[180:183], v147
	ds_read_b128 v[184:187], v148
	ds_read_b128 v[188:191], v149
	ds_read_b128 v[192:195], v150
	s_add_i32 s72, s26, 2
	s_add_u32 s27, s24, 0x80
	s_addc_u32 s52, s25, 0
	s_cmp_lg_u32 s69, s26
	s_cselect_b32 s53, s52, 0
	s_cselect_b32 s52, s27, 0
	s_add_u32 s26, s14, s52
	s_addc_u32 s27, s15, s53
	s_add_u32 s52, s12, s52
	s_addc_u32 s53, s13, s53
	s_mov_b32 m0, s70
	v_lshl_add_u64 v[160:161], v[138:139], 0, s[24:25]
	ds_read_b128 v[196:199], v131
	ds_read_b128 v[200:203], v131 offset:1024
	ds_read_b128 v[204:207], v131 offset:2048
	ds_read_b128 v[208:211], v131 offset:3072
	ds_read_b128 v[212:215], v131 offset:4096
	ds_read_b128 v[216:219], v131 offset:5120
	ds_read_b128 v[220:223], v131 offset:6144
	ds_read_b128 v[224:227], v131 offset:7168
	global_load_lds_dwordx4 v[160:161], off
	v_lshl_add_u64 v[160:161], v[140:141], 0, s[24:25]
	s_mov_b32 m0, s71
	s_nop 0
	global_load_lds_dwordx4 v[160:161], off
	s_waitcnt vmcnt(8)
	s_waitcnt lgkmcnt(0)
	s_barrier
	s_setprio 1
	s_waitcnt lgkmcnt(0)
	v_mfma_f32_16x16x32_bf16 v[124:127], v[164:167], v[196:199], v[124:127]
	v_mfma_f32_16x16x32_bf16 v[120:123], v[172:175], v[196:199], v[120:123]
	v_mfma_f32_16x16x32_bf16 v[108:111], v[164:167], v[204:207], v[108:111]
	v_mfma_f32_16x16x32_bf16 v[104:107], v[172:175], v[204:207], v[104:107]
	v_mfma_f32_16x16x32_bf16 v[92:95], v[164:167], v[212:215], v[92:95]
	v_mfma_f32_16x16x32_bf16 v[88:91], v[172:175], v[212:215], v[88:91]
	v_mfma_f32_16x16x32_bf16 v[76:79], v[164:167], v[220:223], v[76:79]
	v_mfma_f32_16x16x32_bf16 v[72:75], v[172:175], v[220:223], v[72:75]
	v_mfma_f32_16x16x32_bf16 v[124:127], v[168:171], v[200:203], v[124:127]
	v_mfma_f32_16x16x32_bf16 v[120:123], v[176:179], v[200:203], v[120:123]
	v_mfma_f32_16x16x32_bf16 v[108:111], v[168:171], v[208:211], v[108:111]
	v_mfma_f32_16x16x32_bf16 v[104:107], v[176:179], v[208:211], v[104:107]
	v_mfma_f32_16x16x32_bf16 v[92:95], v[168:171], v[216:219], v[92:95]
	v_mfma_f32_16x16x32_bf16 v[88:91], v[176:179], v[216:219], v[88:91]
	v_mfma_f32_16x16x32_bf16 v[76:79], v[168:171], v[224:227], v[76:79]
	v_mfma_f32_16x16x32_bf16 v[72:75], v[176:179], v[224:227], v[72:75]
	s_setprio 0
	s_setprio 1
	v_mfma_f32_16x16x32_bf16 v[116:119], v[180:183], v[196:199], v[116:119]
	v_mfma_f32_16x16x32_bf16 v[112:115], v[188:191], v[196:199], v[112:115]
	v_mfma_f32_16x16x32_bf16 v[100:103], v[180:183], v[204:207], v[100:103]
	v_mfma_f32_16x16x32_bf16 v[96:99], v[188:191], v[204:207], v[96:99]
	v_mfma_f32_16x16x32_bf16 v[84:87], v[180:183], v[212:215], v[84:87]
	v_mfma_f32_16x16x32_bf16 v[80:83], v[188:191], v[212:215], v[80:83]
	v_mfma_f32_16x16x32_bf16 v[68:71], v[180:183], v[220:223], v[68:71]
	v_mfma_f32_16x16x32_bf16 v[64:67], v[188:191], v[220:223], v[64:67]
	v_mfma_f32_16x16x32_bf16 v[116:119], v[184:187], v[200:203], v[116:119]
	v_mfma_f32_16x16x32_bf16 v[112:115], v[192:195], v[200:203], v[112:115]
	v_mfma_f32_16x16x32_bf16 v[100:103], v[184:187], v[208:211], v[100:103]
	v_mfma_f32_16x16x32_bf16 v[96:99], v[192:195], v[208:211], v[96:99]
	v_mfma_f32_16x16x32_bf16 v[84:87], v[184:187], v[216:219], v[84:87]
	v_mfma_f32_16x16x32_bf16 v[80:83], v[192:195], v[216:219], v[80:83]
	v_mfma_f32_16x16x32_bf16 v[68:71], v[184:187], v[224:227], v[68:71]
	v_mfma_f32_16x16x32_bf16 v[64:67], v[192:195], v[224:227], v[64:67]
	s_setprio 0
	s_barrier
	s_mov_b32 m0, s20
	v_lshl_add_u64 v[160:161], s[52:53], 0, v[128:129]
	v_lshl_add_u64 v[228:229], s[52:53], 0, v[132:133]
	s_add_u32 s52, s52, s10
	ds_read_b128 v[196:199], v131 offset:16384
	ds_read_b128 v[200:203], v131 offset:17408
	ds_read_b128 v[204:207], v131 offset:18432
	ds_read_b128 v[208:211], v131 offset:19456
	ds_read_b128 v[212:215], v131 offset:20480
	ds_read_b128 v[216:219], v131 offset:21504
	ds_read_b128 v[220:223], v131 offset:22528
	ds_read_b128 v[224:227], v131 offset:23552
	global_load_lds_dwordx4 v[160:161], off
	s_mov_b32 m0, s21
	s_addc_u32 s53, s53, s11
	global_load_lds_dwordx4 v[228:229], off
	v_lshl_add_u64 v[230:231], s[52:53], 0, v[128:129]
	s_mov_b32 m0, s28
	v_lshl_add_u64 v[232:233], s[52:53], 0, v[132:133]
	global_load_lds_dwordx4 v[230:231], off
	s_mov_b32 m0, s29
	v_lshl_add_u64 v[234:235], s[26:27], 0, v[136:137]
	global_load_lds_dwordx4 v[232:233], off
	s_mov_b32 m0, s7
	v_lshl_add_u64 v[236:237], s[26:27], 0, v[134:135]
	global_load_lds_dwordx4 v[234:235], off
	s_mov_b32 m0, s30
	s_nop 0
	global_load_lds_dwordx4 v[236:237], off
	s_waitcnt vmcnt(8)
	s_waitcnt lgkmcnt(0)
	s_barrier
	s_setprio 1
	s_waitcnt lgkmcnt(0)
	v_mfma_f32_16x16x32_bf16 v[60:63], v[164:167], v[196:199], v[60:63]
	v_mfma_f32_16x16x32_bf16 v[56:59], v[172:175], v[196:199], v[56:59]
	v_mfma_f32_16x16x32_bf16 v[44:47], v[164:167], v[204:207], v[44:47]
	v_mfma_f32_16x16x32_bf16 v[40:43], v[172:175], v[204:207], v[40:43]
	v_mfma_f32_16x16x32_bf16 v[28:31], v[164:167], v[212:215], v[28:31]
	v_mfma_f32_16x16x32_bf16 v[24:27], v[172:175], v[212:215], v[24:27]
	v_mfma_f32_16x16x32_bf16 v[12:15], v[164:167], v[220:223], v[12:15]
	v_mfma_f32_16x16x32_bf16 v[8:11], v[172:175], v[220:223], v[8:11]
	v_mfma_f32_16x16x32_bf16 v[60:63], v[168:171], v[200:203], v[60:63]
	v_mfma_f32_16x16x32_bf16 v[56:59], v[176:179], v[200:203], v[56:59]
	v_mfma_f32_16x16x32_bf16 v[44:47], v[168:171], v[208:211], v[44:47]
	v_mfma_f32_16x16x32_bf16 v[40:43], v[176:179], v[208:211], v[40:43]
	v_mfma_f32_16x16x32_bf16 v[28:31], v[168:171], v[216:219], v[28:31]
	v_mfma_f32_16x16x32_bf16 v[24:27], v[176:179], v[216:219], v[24:27]
	v_mfma_f32_16x16x32_bf16 v[12:15], v[168:171], v[224:227], v[12:15]
	v_mfma_f32_16x16x32_bf16 v[8:11], v[176:179], v[224:227], v[8:11]
	s_setprio 0
	s_setprio 1
	v_mfma_f32_16x16x32_bf16 v[52:55], v[180:183], v[196:199], v[52:55]
	v_mfma_f32_16x16x32_bf16 v[48:51], v[188:191], v[196:199], v[48:51]
	v_mfma_f32_16x16x32_bf16 v[36:39], v[180:183], v[204:207], v[36:39]
	v_mfma_f32_16x16x32_bf16 v[32:35], v[188:191], v[204:207], v[32:35]
	v_mfma_f32_16x16x32_bf16 v[20:23], v[180:183], v[212:215], v[20:23]
	v_mfma_f32_16x16x32_bf16 v[16:19], v[188:191], v[212:215], v[16:19]
	v_mfma_f32_16x16x32_bf16 v[4:7], v[180:183], v[220:223], v[4:7]
	v_mfma_f32_16x16x32_bf16 v[0:3], v[188:191], v[220:223], v[0:3]
	v_mfma_f32_16x16x32_bf16 v[52:55], v[184:187], v[200:203], v[52:55]
	v_mfma_f32_16x16x32_bf16 v[48:51], v[192:195], v[200:203], v[48:51]
	v_mfma_f32_16x16x32_bf16 v[36:39], v[184:187], v[208:211], v[36:39]
	v_mfma_f32_16x16x32_bf16 v[32:35], v[192:195], v[208:211], v[32:35]
	v_mfma_f32_16x16x32_bf16 v[20:23], v[184:187], v[216:219], v[20:23]
	v_mfma_f32_16x16x32_bf16 v[16:19], v[192:195], v[216:219], v[16:19]
	v_mfma_f32_16x16x32_bf16 v[4:7], v[184:187], v[224:227], v[4:7]
	v_mfma_f32_16x16x32_bf16 v[0:3], v[192:195], v[224:227], v[0:3]
	s_setprio 0
	s_barrier
	ds_read_b128 v[164:167], v151
	ds_read_b128 v[168:171], v152
	ds_read_b128 v[172:175], v153
	ds_read_b128 v[176:179], v154
	ds_read_b128 v[180:183], v155
	ds_read_b128 v[184:187], v156
	ds_read_b128 v[188:191], v157
	ds_read_b128 v[192:195], v158
	s_add_u32 s26, s26, s8
	s_addc_u32 s27, s27, s9
	s_mov_b32 m0, s31
	v_lshl_add_u64 v[238:239], s[26:27], 0, v[136:137]
	ds_read_b128 v[196:199], v131 offset:32768
	ds_read_b128 v[200:203], v131 offset:33792
	ds_read_b128 v[204:207], v131 offset:34816
	ds_read_b128 v[208:211], v131 offset:35840
	ds_read_b128 v[212:215], v131 offset:36864
	ds_read_b128 v[216:219], v131 offset:37888
	ds_read_b128 v[220:223], v131 offset:38912
	ds_read_b128 v[224:227], v131 offset:39936
	global_load_lds_dwordx4 v[238:239], off
	v_lshl_add_u64 v[238:239], s[26:27], 0, v[134:135]
	s_mov_b32 m0, s33
	s_nop 0
	global_load_lds_dwordx4 v[238:239], off
	s_waitcnt vmcnt(8)
	s_waitcnt lgkmcnt(0)
	s_barrier
	s_setprio 1
	s_waitcnt lgkmcnt(0)
	v_mfma_f32_16x16x32_bf16 v[124:127], v[164:167], v[196:199], v[124:127]
	v_mfma_f32_16x16x32_bf16 v[120:123], v[172:175], v[196:199], v[120:123]
	v_mfma_f32_16x16x32_bf16 v[108:111], v[164:167], v[204:207], v[108:111]
	v_mfma_f32_16x16x32_bf16 v[104:107], v[172:175], v[204:207], v[104:107]
	v_mfma_f32_16x16x32_bf16 v[92:95], v[164:167], v[212:215], v[92:95]
	v_mfma_f32_16x16x32_bf16 v[88:91], v[172:175], v[212:215], v[88:91]
	v_mfma_f32_16x16x32_bf16 v[76:79], v[164:167], v[220:223], v[76:79]
	v_mfma_f32_16x16x32_bf16 v[72:75], v[172:175], v[220:223], v[72:75]
	v_mfma_f32_16x16x32_bf16 v[124:127], v[168:171], v[200:203], v[124:127]
	v_mfma_f32_16x16x32_bf16 v[120:123], v[176:179], v[200:203], v[120:123]
	v_mfma_f32_16x16x32_bf16 v[108:111], v[168:171], v[208:211], v[108:111]
	v_mfma_f32_16x16x32_bf16 v[104:107], v[176:179], v[208:211], v[104:107]
	v_mfma_f32_16x16x32_bf16 v[92:95], v[168:171], v[216:219], v[92:95]
	v_mfma_f32_16x16x32_bf16 v[88:91], v[176:179], v[216:219], v[88:91]
	v_mfma_f32_16x16x32_bf16 v[76:79], v[168:171], v[224:227], v[76:79]
	v_mfma_f32_16x16x32_bf16 v[72:75], v[176:179], v[224:227], v[72:75]
	s_setprio 0
	s_setprio 1
	v_mfma_f32_16x16x32_bf16 v[116:119], v[180:183], v[196:199], v[116:119]
	v_mfma_f32_16x16x32_bf16 v[112:115], v[188:191], v[196:199], v[112:115]
	v_mfma_f32_16x16x32_bf16 v[100:103], v[180:183], v[204:207], v[100:103]
	v_mfma_f32_16x16x32_bf16 v[96:99], v[188:191], v[204:207], v[96:99]
	v_mfma_f32_16x16x32_bf16 v[84:87], v[180:183], v[212:215], v[84:87]
	v_mfma_f32_16x16x32_bf16 v[80:83], v[188:191], v[212:215], v[80:83]
	v_mfma_f32_16x16x32_bf16 v[68:71], v[180:183], v[220:223], v[68:71]
	v_mfma_f32_16x16x32_bf16 v[64:67], v[188:191], v[220:223], v[64:67]
	v_mfma_f32_16x16x32_bf16 v[116:119], v[184:187], v[200:203], v[116:119]
	v_mfma_f32_16x16x32_bf16 v[112:115], v[192:195], v[200:203], v[112:115]
	v_mfma_f32_16x16x32_bf16 v[100:103], v[184:187], v[208:211], v[100:103]
	v_mfma_f32_16x16x32_bf16 v[96:99], v[192:195], v[208:211], v[96:99]
	v_mfma_f32_16x16x32_bf16 v[84:87], v[184:187], v[216:219], v[84:87]
	v_mfma_f32_16x16x32_bf16 v[80:83], v[192:195], v[216:219], v[80:83]
	v_mfma_f32_16x16x32_bf16 v[68:71], v[184:187], v[224:227], v[68:71]
	v_mfma_f32_16x16x32_bf16 v[64:67], v[192:195], v[224:227], v[64:67]
	s_setprio 0
	s_barrier
	s_mov_b32 m0, s34
	v_lshl_add_u64 v[160:161], v[160:161], 0, s[16:17]
	ds_read_b128 v[196:199], v131 offset:49152
	ds_read_b128 v[200:203], v131 offset:50176
	ds_read_b128 v[204:207], v131 offset:51200
	ds_read_b128 v[208:211], v131 offset:52224
	ds_read_b128 v[212:215], v131 offset:53248
	ds_read_b128 v[216:219], v131 offset:54272
	ds_read_b128 v[220:223], v131 offset:55296
	ds_read_b128 v[224:227], v131 offset:56320
	global_load_lds_dwordx4 v[160:161], off
	v_lshl_add_u64 v[160:161], v[228:229], 0, s[16:17]
	s_mov_b32 m0, s35
	s_nop 0
	global_load_lds_dwordx4 v[160:161], off
	v_lshl_add_u64 v[160:161], v[230:231], 0, s[16:17]
	s_mov_b32 m0, s46
	s_nop 0
	global_load_lds_dwordx4 v[160:161], off
	v_lshl_add_u64 v[160:161], v[232:233], 0, s[16:17]
	s_mov_b32 m0, s47
	s_nop 0
	global_load_lds_dwordx4 v[160:161], off
	v_lshl_add_u64 v[160:161], v[234:235], 0, s[16:17]
	s_mov_b32 m0, s36
	s_nop 0
	global_load_lds_dwordx4 v[160:161], off
	v_lshl_add_u64 v[160:161], v[236:237], 0, s[16:17]
	s_mov_b32 m0, s37
	s_nop 0
	global_load_lds_dwordx4 v[160:161], off
	s_waitcnt vmcnt(8)
	s_waitcnt lgkmcnt(0)
	s_barrier
	s_setprio 1
	s_waitcnt lgkmcnt(0)
	v_mfma_f32_16x16x32_bf16 v[60:63], v[164:167], v[196:199], v[60:63]
	v_mfma_f32_16x16x32_bf16 v[56:59], v[172:175], v[196:199], v[56:59]
	v_mfma_f32_16x16x32_bf16 v[44:47], v[164:167], v[204:207], v[44:47]
	v_mfma_f32_16x16x32_bf16 v[40:43], v[172:175], v[204:207], v[40:43]
	v_mfma_f32_16x16x32_bf16 v[28:31], v[164:167], v[212:215], v[28:31]
	v_mfma_f32_16x16x32_bf16 v[24:27], v[172:175], v[212:215], v[24:27]
	v_mfma_f32_16x16x32_bf16 v[12:15], v[164:167], v[220:223], v[12:15]
	v_mfma_f32_16x16x32_bf16 v[8:11], v[172:175], v[220:223], v[8:11]
	v_mfma_f32_16x16x32_bf16 v[60:63], v[168:171], v[200:203], v[60:63]
	v_mfma_f32_16x16x32_bf16 v[56:59], v[176:179], v[200:203], v[56:59]
	v_mfma_f32_16x16x32_bf16 v[44:47], v[168:171], v[208:211], v[44:47]
	v_mfma_f32_16x16x32_bf16 v[40:43], v[176:179], v[208:211], v[40:43]
	v_mfma_f32_16x16x32_bf16 v[28:31], v[168:171], v[216:219], v[28:31]
	v_mfma_f32_16x16x32_bf16 v[24:27], v[176:179], v[216:219], v[24:27]
	v_mfma_f32_16x16x32_bf16 v[12:15], v[168:171], v[224:227], v[12:15]
	v_mfma_f32_16x16x32_bf16 v[8:11], v[176:179], v[224:227], v[8:11]
	s_setprio 0
	s_setprio 1
	v_mfma_f32_16x16x32_bf16 v[52:55], v[180:183], v[196:199], v[52:55]
	v_mfma_f32_16x16x32_bf16 v[48:51], v[188:191], v[196:199], v[48:51]
	v_mfma_f32_16x16x32_bf16 v[36:39], v[180:183], v[204:207], v[36:39]
	v_mfma_f32_16x16x32_bf16 v[32:35], v[188:191], v[204:207], v[32:35]
	v_mfma_f32_16x16x32_bf16 v[20:23], v[180:183], v[212:215], v[20:23]
	v_mfma_f32_16x16x32_bf16 v[16:19], v[188:191], v[212:215], v[16:19]
	v_mfma_f32_16x16x32_bf16 v[4:7], v[180:183], v[220:223], v[4:7]
	v_mfma_f32_16x16x32_bf16 v[0:3], v[188:191], v[220:223], v[0:3]
	v_mfma_f32_16x16x32_bf16 v[52:55], v[184:187], v[200:203], v[52:55]
	v_mfma_f32_16x16x32_bf16 v[48:51], v[192:195], v[200:203], v[48:51]
	v_mfma_f32_16x16x32_bf16 v[36:39], v[184:187], v[208:211], v[36:39]
	v_mfma_f32_16x16x32_bf16 v[32:35], v[192:195], v[208:211], v[32:35]
	v_mfma_f32_16x16x32_bf16 v[20:23], v[184:187], v[216:219], v[20:23]
	v_mfma_f32_16x16x32_bf16 v[16:19], v[192:195], v[216:219], v[16:19]
	v_mfma_f32_16x16x32_bf16 v[4:7], v[184:187], v[224:227], v[4:7]
	v_mfma_f32_16x16x32_bf16 v[0:3], v[192:195], v[224:227], v[0:3]
	s_setprio 0
	s_barrier
	s_add_u32 s24, s24, 0x100
	s_addc_u32 s25, s25, 0
	s_cmp_ge_i32 s72, s68
	s_mov_b32 s26, s72
	s_cbranch_scc0 .LBB0_865
	v_mov_b32_e32 v129, v127

.LBB0_875:
	ds_read_b128 v[164:167], v143
	ds_read_b128 v[168:171], v144
	ds_read_b128 v[172:175], v145
	ds_read_b128 v[176:179], v146
	ds_read_b128 v[180:183], v147
	ds_read_b128 v[184:187], v148
	ds_read_b128 v[188:191], v149
	ds_read_b128 v[192:195], v150
	s_add_i32 s70, s26, 2
	s_add_u32 s27, s24, 0xfffff580
	s_addc_u32 s52, s25, -1
	s_cmp_lg_u32 s49, s26
	s_cselect_b32 s53, s52, 0
	s_cselect_b32 s52, s27, 0
	s_add_u32 s26, s14, s52
	s_addc_u32 s27, s15, s53
	s_add_u32 s52, s12, s52
	s_addc_u32 s53, s13, s53
	s_mov_b32 m0, s68
	v_lshl_add_u64 v[160:161], v[140:141], 0, s[24:25]
	ds_read_b128 v[196:199], v131
	ds_read_b128 v[200:203], v131 offset:1024
	ds_read_b128 v[204:207], v131 offset:2048
	ds_read_b128 v[208:211], v131 offset:3072
	ds_read_b128 v[212:215], v131 offset:4096
	ds_read_b128 v[216:219], v131 offset:5120
	ds_read_b128 v[220:223], v131 offset:6144
	ds_read_b128 v[224:227], v131 offset:7168
	global_load_lds_dwordx4 v[160:161], off
	v_lshl_add_u64 v[160:161], v[138:139], 0, s[24:25]
	s_mov_b32 m0, s69
	s_nop 0
	global_load_lds_dwordx4 v[160:161], off
	s_waitcnt vmcnt(8)
	s_waitcnt lgkmcnt(0)
	s_barrier
	s_setprio 1
	s_waitcnt lgkmcnt(0)
	v_mfma_f32_16x16x32_bf16 v[124:127], v[164:167], v[196:199], v[124:127]
	v_mfma_f32_16x16x32_bf16 v[120:123], v[172:175], v[196:199], v[120:123]
	v_mfma_f32_16x16x32_bf16 v[108:111], v[164:167], v[204:207], v[108:111]
	v_mfma_f32_16x16x32_bf16 v[104:107], v[172:175], v[204:207], v[104:107]
	v_mfma_f32_16x16x32_bf16 v[92:95], v[164:167], v[212:215], v[92:95]
	v_mfma_f32_16x16x32_bf16 v[88:91], v[172:175], v[212:215], v[88:91]
	v_mfma_f32_16x16x32_bf16 v[76:79], v[164:167], v[220:223], v[76:79]
	v_mfma_f32_16x16x32_bf16 v[72:75], v[172:175], v[220:223], v[72:75]
	v_mfma_f32_16x16x32_bf16 v[124:127], v[168:171], v[200:203], v[124:127]
	v_mfma_f32_16x16x32_bf16 v[120:123], v[176:179], v[200:203], v[120:123]
	v_mfma_f32_16x16x32_bf16 v[108:111], v[168:171], v[208:211], v[108:111]
	v_mfma_f32_16x16x32_bf16 v[104:107], v[176:179], v[208:211], v[104:107]
	v_mfma_f32_16x16x32_bf16 v[92:95], v[168:171], v[216:219], v[92:95]
	v_mfma_f32_16x16x32_bf16 v[88:91], v[176:179], v[216:219], v[88:91]
	v_mfma_f32_16x16x32_bf16 v[76:79], v[168:171], v[224:227], v[76:79]
	v_mfma_f32_16x16x32_bf16 v[72:75], v[176:179], v[224:227], v[72:75]
	s_setprio 0
	s_setprio 1
	v_mfma_f32_16x16x32_bf16 v[116:119], v[180:183], v[196:199], v[116:119]
	v_mfma_f32_16x16x32_bf16 v[112:115], v[188:191], v[196:199], v[112:115]
	v_mfma_f32_16x16x32_bf16 v[100:103], v[180:183], v[204:207], v[100:103]
	v_mfma_f32_16x16x32_bf16 v[96:99], v[188:191], v[204:207], v[96:99]
	v_mfma_f32_16x16x32_bf16 v[84:87], v[180:183], v[212:215], v[84:87]
	v_mfma_f32_16x16x32_bf16 v[80:83], v[188:191], v[212:215], v[80:83]
	v_mfma_f32_16x16x32_bf16 v[68:71], v[180:183], v[220:223], v[68:71]
	v_mfma_f32_16x16x32_bf16 v[64:67], v[188:191], v[220:223], v[64:67]
	v_mfma_f32_16x16x32_bf16 v[116:119], v[184:187], v[200:203], v[116:119]
	v_mfma_f32_16x16x32_bf16 v[112:115], v[192:195], v[200:203], v[112:115]
	v_mfma_f32_16x16x32_bf16 v[100:103], v[184:187], v[208:211], v[100:103]
	v_mfma_f32_16x16x32_bf16 v[96:99], v[192:195], v[208:211], v[96:99]
	v_mfma_f32_16x16x32_bf16 v[84:87], v[184:187], v[216:219], v[84:87]
	v_mfma_f32_16x16x32_bf16 v[80:83], v[192:195], v[216:219], v[80:83]
	v_mfma_f32_16x16x32_bf16 v[68:71], v[184:187], v[224:227], v[68:71]
	v_mfma_f32_16x16x32_bf16 v[64:67], v[192:195], v[224:227], v[64:67]
	s_setprio 0
	s_barrier
	v_lshl_add_u64 v[160:161], s[52:53], 0, v[128:129]
	s_mov_b32 m0, s21
	v_lshl_add_u64 v[228:229], v[160:161], 0, s[0:1]
	ds_read_b128 v[196:199], v131 offset:16384
	ds_read_b128 v[200:203], v131 offset:17408
	ds_read_b128 v[204:207], v131 offset:18432
	ds_read_b128 v[208:211], v131 offset:19456
	ds_read_b128 v[212:215], v131 offset:20480
	ds_read_b128 v[216:219], v131 offset:21504
	ds_read_b128 v[220:223], v131 offset:22528
	ds_read_b128 v[224:227], v131 offset:23552
	global_load_lds_dwordx4 v[228:229], off
	v_lshl_add_u64 v[228:229], s[52:53], 0, v[132:133]
	s_add_u32 s52, s52, s10
	v_lshl_add_u64 v[230:231], v[228:229], 0, s[0:1]
	s_mov_b32 m0, s28
	s_addc_u32 s53, s53, s11
	global_load_lds_dwordx4 v[230:231], off
	v_lshl_add_u64 v[230:231], s[52:53], 0, v[128:129]
	v_lshl_add_u64 v[232:233], v[230:231], 0, s[0:1]
	s_mov_b32 m0, s29
	s_nop 0
	global_load_lds_dwordx4 v[232:233], off
	v_lshl_add_u64 v[232:233], s[52:53], 0, v[132:133]
	v_lshl_add_u64 v[234:235], v[232:233], 0, s[0:1]
	s_mov_b32 m0, s30
	s_nop 0
	global_load_lds_dwordx4 v[234:235], off
	v_lshl_add_u64 v[234:235], s[26:27], 0, v[136:137]
	v_lshl_add_u64 v[236:237], v[234:235], 0, s[0:1]
	s_mov_b32 m0, s7
	s_nop 0
	global_load_lds_dwordx4 v[236:237], off
	v_lshl_add_u64 v[236:237], s[26:27], 0, v[134:135]
	v_lshl_add_u64 v[238:239], v[236:237], 0, s[0:1]
	s_mov_b32 m0, s31
	s_nop 0
	global_load_lds_dwordx4 v[238:239], off
	s_waitcnt vmcnt(8)
	s_waitcnt lgkmcnt(0)
	s_barrier
	s_setprio 1
	s_waitcnt lgkmcnt(0)
	v_mfma_f32_16x16x32_bf16 v[60:63], v[164:167], v[196:199], v[60:63]
	v_mfma_f32_16x16x32_bf16 v[56:59], v[172:175], v[196:199], v[56:59]
	v_mfma_f32_16x16x32_bf16 v[44:47], v[164:167], v[204:207], v[44:47]
	v_mfma_f32_16x16x32_bf16 v[40:43], v[172:175], v[204:207], v[40:43]
	v_mfma_f32_16x16x32_bf16 v[28:31], v[164:167], v[212:215], v[28:31]
	v_mfma_f32_16x16x32_bf16 v[24:27], v[172:175], v[212:215], v[24:27]
	v_mfma_f32_16x16x32_bf16 v[12:15], v[164:167], v[220:223], v[12:15]
	v_mfma_f32_16x16x32_bf16 v[8:11], v[172:175], v[220:223], v[8:11]
	v_mfma_f32_16x16x32_bf16 v[60:63], v[168:171], v[200:203], v[60:63]
	v_mfma_f32_16x16x32_bf16 v[56:59], v[176:179], v[200:203], v[56:59]
	v_mfma_f32_16x16x32_bf16 v[44:47], v[168:171], v[208:211], v[44:47]
	v_mfma_f32_16x16x32_bf16 v[40:43], v[176:179], v[208:211], v[40:43]
	v_mfma_f32_16x16x32_bf16 v[28:31], v[168:171], v[216:219], v[28:31]
	v_mfma_f32_16x16x32_bf16 v[24:27], v[176:179], v[216:219], v[24:27]
	v_mfma_f32_16x16x32_bf16 v[12:15], v[168:171], v[224:227], v[12:15]
	v_mfma_f32_16x16x32_bf16 v[8:11], v[176:179], v[224:227], v[8:11]
	s_setprio 0
	s_setprio 1
	v_mfma_f32_16x16x32_bf16 v[52:55], v[180:183], v[196:199], v[52:55]
	v_mfma_f32_16x16x32_bf16 v[48:51], v[188:191], v[196:199], v[48:51]
	v_mfma_f32_16x16x32_bf16 v[36:39], v[180:183], v[204:207], v[36:39]
	v_mfma_f32_16x16x32_bf16 v[32:35], v[188:191], v[204:207], v[32:35]
	v_mfma_f32_16x16x32_bf16 v[20:23], v[180:183], v[212:215], v[20:23]
	v_mfma_f32_16x16x32_bf16 v[16:19], v[188:191], v[212:215], v[16:19]
	v_mfma_f32_16x16x32_bf16 v[4:7], v[180:183], v[220:223], v[4:7]
	v_mfma_f32_16x16x32_bf16 v[0:3], v[188:191], v[220:223], v[0:3]
	v_mfma_f32_16x16x32_bf16 v[52:55], v[184:187], v[200:203], v[52:55]
	v_mfma_f32_16x16x32_bf16 v[48:51], v[192:195], v[200:203], v[48:51]
	v_mfma_f32_16x16x32_bf16 v[36:39], v[184:187], v[208:211], v[36:39]
	v_mfma_f32_16x16x32_bf16 v[32:35], v[192:195], v[208:211], v[32:35]
	v_mfma_f32_16x16x32_bf16 v[20:23], v[184:187], v[216:219], v[20:23]
	v_mfma_f32_16x16x32_bf16 v[16:19], v[192:195], v[216:219], v[16:19]
	v_mfma_f32_16x16x32_bf16 v[4:7], v[184:187], v[224:227], v[4:7]
	v_mfma_f32_16x16x32_bf16 v[0:3], v[192:195], v[224:227], v[0:3]
	s_setprio 0
	s_barrier
	ds_read_b128 v[164:167], v151
	ds_read_b128 v[168:171], v152
	ds_read_b128 v[172:175], v153
	ds_read_b128 v[176:179], v154
	ds_read_b128 v[180:183], v155
	ds_read_b128 v[184:187], v156
	ds_read_b128 v[188:191], v157
	ds_read_b128 v[192:195], v158
	s_add_u32 s26, s26, s8
	s_addc_u32 s27, s27, s9
	v_lshl_add_u64 v[238:239], s[26:27], 0, v[136:137]
	s_mov_b32 m0, s33
	v_lshl_add_u64 v[238:239], v[238:239], 0, s[0:1]
	ds_read_b128 v[196:199], v131 offset:32768
	ds_read_b128 v[200:203], v131 offset:33792
	ds_read_b128 v[204:207], v131 offset:34816
	ds_read_b128 v[208:211], v131 offset:35840
	ds_read_b128 v[212:215], v131 offset:36864
	ds_read_b128 v[216:219], v131 offset:37888
	ds_read_b128 v[220:223], v131 offset:38912
	ds_read_b128 v[224:227], v131 offset:39936
	global_load_lds_dwordx4 v[238:239], off
	v_lshl_add_u64 v[238:239], s[26:27], 0, v[134:135]
	v_lshl_add_u64 v[238:239], v[238:239], 0, s[0:1]
	s_mov_b32 m0, s34
	s_nop 0
	global_load_lds_dwordx4 v[238:239], off
	s_waitcnt vmcnt(8)
	s_waitcnt lgkmcnt(0)
	s_barrier
	s_setprio 1
	s_waitcnt lgkmcnt(0)
	v_mfma_f32_16x16x32_bf16 v[124:127], v[164:167], v[196:199], v[124:127]
	v_mfma_f32_16x16x32_bf16 v[120:123], v[172:175], v[196:199], v[120:123]
	v_mfma_f32_16x16x32_bf16 v[108:111], v[164:167], v[204:207], v[108:111]
	v_mfma_f32_16x16x32_bf16 v[104:107], v[172:175], v[204:207], v[104:107]
	v_mfma_f32_16x16x32_bf16 v[92:95], v[164:167], v[212:215], v[92:95]
	v_mfma_f32_16x16x32_bf16 v[88:91], v[172:175], v[212:215], v[88:91]
	v_mfma_f32_16x16x32_bf16 v[76:79], v[164:167], v[220:223], v[76:79]
	v_mfma_f32_16x16x32_bf16 v[72:75], v[172:175], v[220:223], v[72:75]
	v_mfma_f32_16x16x32_bf16 v[124:127], v[168:171], v[200:203], v[124:127]
	v_mfma_f32_16x16x32_bf16 v[120:123], v[176:179], v[200:203], v[120:123]
	v_mfma_f32_16x16x32_bf16 v[108:111], v[168:171], v[208:211], v[108:111]
	v_mfma_f32_16x16x32_bf16 v[104:107], v[176:179], v[208:211], v[104:107]
	v_mfma_f32_16x16x32_bf16 v[92:95], v[168:171], v[216:219], v[92:95]
	v_mfma_f32_16x16x32_bf16 v[88:91], v[176:179], v[216:219], v[88:91]
	v_mfma_f32_16x16x32_bf16 v[76:79], v[168:171], v[224:227], v[76:79]
	v_mfma_f32_16x16x32_bf16 v[72:75], v[176:179], v[224:227], v[72:75]
	s_setprio 0
	s_setprio 1
	v_mfma_f32_16x16x32_bf16 v[116:119], v[180:183], v[196:199], v[116:119]
	v_mfma_f32_16x16x32_bf16 v[112:115], v[188:191], v[196:199], v[112:115]
	v_mfma_f32_16x16x32_bf16 v[100:103], v[180:183], v[204:207], v[100:103]
	v_mfma_f32_16x16x32_bf16 v[96:99], v[188:191], v[204:207], v[96:99]
	v_mfma_f32_16x16x32_bf16 v[84:87], v[180:183], v[212:215], v[84:87]
	v_mfma_f32_16x16x32_bf16 v[80:83], v[188:191], v[212:215], v[80:83]
	v_mfma_f32_16x16x32_bf16 v[68:71], v[180:183], v[220:223], v[68:71]
	v_mfma_f32_16x16x32_bf16 v[64:67], v[188:191], v[220:223], v[64:67]
	v_mfma_f32_16x16x32_bf16 v[116:119], v[184:187], v[200:203], v[116:119]
	v_mfma_f32_16x16x32_bf16 v[112:115], v[192:195], v[200:203], v[112:115]
	v_mfma_f32_16x16x32_bf16 v[100:103], v[184:187], v[208:211], v[100:103]
	v_mfma_f32_16x16x32_bf16 v[96:99], v[192:195], v[208:211], v[96:99]
	v_mfma_f32_16x16x32_bf16 v[84:87], v[184:187], v[216:219], v[84:87]
	v_mfma_f32_16x16x32_bf16 v[80:83], v[192:195], v[216:219], v[80:83]
	v_mfma_f32_16x16x32_bf16 v[68:71], v[184:187], v[224:227], v[68:71]
	v_mfma_f32_16x16x32_bf16 v[64:67], v[192:195], v[224:227], v[64:67]
	s_setprio 0
	s_barrier
	s_mov_b32 m0, s35
	v_lshl_add_u64 v[160:161], v[160:161], 0, s[16:17]
	ds_read_b128 v[196:199], v131 offset:49152
	ds_read_b128 v[200:203], v131 offset:50176
	ds_read_b128 v[204:207], v131 offset:51200
	ds_read_b128 v[208:211], v131 offset:52224
	ds_read_b128 v[212:215], v131 offset:53248
	ds_read_b128 v[216:219], v131 offset:54272
	ds_read_b128 v[220:223], v131 offset:55296
	ds_read_b128 v[224:227], v131 offset:56320
	global_load_lds_dwordx4 v[160:161], off
	v_lshl_add_u64 v[160:161], v[228:229], 0, s[16:17]
	s_mov_b32 m0, s36
	s_nop 0
	global_load_lds_dwordx4 v[160:161], off
	v_lshl_add_u64 v[160:161], v[230:231], 0, s[16:17]
	s_mov_b32 m0, s47
	s_nop 0
	global_load_lds_dwordx4 v[160:161], off
	v_lshl_add_u64 v[160:161], v[232:233], 0, s[16:17]
	s_mov_b32 m0, s48
	s_nop 0
	global_load_lds_dwordx4 v[160:161], off
	v_lshl_add_u64 v[160:161], v[234:235], 0, s[16:17]
	s_mov_b32 m0, s37
	s_nop 0
	global_load_lds_dwordx4 v[160:161], off
	v_lshl_add_u64 v[160:161], v[236:237], 0, s[16:17]
	s_mov_b32 m0, s46
	s_nop 0
	global_load_lds_dwordx4 v[160:161], off
	s_waitcnt vmcnt(8)
	s_waitcnt lgkmcnt(0)
	s_barrier
	s_setprio 1
	s_waitcnt lgkmcnt(0)
	v_mfma_f32_16x16x32_bf16 v[60:63], v[164:167], v[196:199], v[60:63]
	v_mfma_f32_16x16x32_bf16 v[56:59], v[172:175], v[196:199], v[56:59]
	v_mfma_f32_16x16x32_bf16 v[44:47], v[164:167], v[204:207], v[44:47]
	v_mfma_f32_16x16x32_bf16 v[40:43], v[172:175], v[204:207], v[40:43]
	v_mfma_f32_16x16x32_bf16 v[28:31], v[164:167], v[212:215], v[28:31]
	v_mfma_f32_16x16x32_bf16 v[24:27], v[172:175], v[212:215], v[24:27]
	v_mfma_f32_16x16x32_bf16 v[12:15], v[164:167], v[220:223], v[12:15]
	v_mfma_f32_16x16x32_bf16 v[8:11], v[172:175], v[220:223], v[8:11]
	v_mfma_f32_16x16x32_bf16 v[60:63], v[168:171], v[200:203], v[60:63]
	v_mfma_f32_16x16x32_bf16 v[56:59], v[176:179], v[200:203], v[56:59]
	v_mfma_f32_16x16x32_bf16 v[44:47], v[168:171], v[208:211], v[44:47]
	v_mfma_f32_16x16x32_bf16 v[40:43], v[176:179], v[208:211], v[40:43]
	v_mfma_f32_16x16x32_bf16 v[28:31], v[168:171], v[216:219], v[28:31]
	v_mfma_f32_16x16x32_bf16 v[24:27], v[176:179], v[216:219], v[24:27]
	v_mfma_f32_16x16x32_bf16 v[12:15], v[168:171], v[224:227], v[12:15]
	v_mfma_f32_16x16x32_bf16 v[8:11], v[176:179], v[224:227], v[8:11]
	s_setprio 0
	s_setprio 1
	v_mfma_f32_16x16x32_bf16 v[52:55], v[180:183], v[196:199], v[52:55]
	v_mfma_f32_16x16x32_bf16 v[48:51], v[188:191], v[196:199], v[48:51]
	v_mfma_f32_16x16x32_bf16 v[36:39], v[180:183], v[204:207], v[36:39]
	v_mfma_f32_16x16x32_bf16 v[32:35], v[188:191], v[204:207], v[32:35]
	v_mfma_f32_16x16x32_bf16 v[20:23], v[180:183], v[212:215], v[20:23]
	v_mfma_f32_16x16x32_bf16 v[16:19], v[188:191], v[212:215], v[16:19]
	v_mfma_f32_16x16x32_bf16 v[4:7], v[180:183], v[220:223], v[4:7]
	v_mfma_f32_16x16x32_bf16 v[0:3], v[188:191], v[220:223], v[0:3]
	v_mfma_f32_16x16x32_bf16 v[52:55], v[184:187], v[200:203], v[52:55]
	v_mfma_f32_16x16x32_bf16 v[48:51], v[192:195], v[200:203], v[48:51]
	v_mfma_f32_16x16x32_bf16 v[36:39], v[184:187], v[208:211], v[36:39]
	v_mfma_f32_16x16x32_bf16 v[32:35], v[192:195], v[208:211], v[32:35]
	v_mfma_f32_16x16x32_bf16 v[20:23], v[184:187], v[216:219], v[20:23]
	v_mfma_f32_16x16x32_bf16 v[16:19], v[192:195], v[216:219], v[16:19]
	v_mfma_f32_16x16x32_bf16 v[4:7], v[184:187], v[224:227], v[4:7]
	v_mfma_f32_16x16x32_bf16 v[0:3], v[192:195], v[224:227], v[0:3]
	s_setprio 0
	s_barrier
	s_add_u32 s24, s24, 0x100
	s_addc_u32 s25, s25, 0
	s_cmp_ge_i32 s70, s19
	s_mov_b32 s26, s70
	s_cbranch_scc0 .LBB0_875
	v_mov_b32_e32 v129, v127

.LBB0_1095:
	s_waitcnt lgkmcnt(0)
	ds_read_b128 v[128:131], v161
	ds_read_b128 v[132:135], v164
	ds_read_b128 v[150:153], v165
	ds_read_b128 v[154:157], v166
	ds_read_b128 v[182:185], v167
	ds_read_b128 v[186:189], v168
	ds_read_b128 v[190:193], v169
	ds_read_b128 v[194:197], v170
	s_add_i32 s77, s70, 2
	s_add_u32 s8, s6, 0x80
	s_addc_u32 s9, s7, 0
	s_cmp_eq_u32 s35, s70
	s_cselect_b32 s9, s79, s9
	s_cselect_b32 s8, s78, s8
	s_cselect_b32 s53, s83, s11
	s_cselect_b32 s52, s82, s10
	s_mov_b32 m0, s18
	v_lshl_add_u64 v[230:231], s[6:7], 0, v[144:145]
	ds_read_b128 v[198:201], v160
	ds_read_b128 v[202:205], v160 offset:1024
	ds_read_b128 v[206:209], v160 offset:2048
	ds_read_b128 v[210:213], v160 offset:3072
	ds_read_b128 v[214:217], v160 offset:4096
	ds_read_b128 v[218:221], v160 offset:5120
	ds_read_b128 v[222:225], v160 offset:6144
	ds_read_b128 v[226:229], v160 offset:7168
	global_load_lds_dwordx4 v[230:231], off
	v_lshl_add_u64 v[230:231], s[6:7], 0, v[146:147]
	s_mov_b32 m0, s19
	s_nop 0
	global_load_lds_dwordx4 v[230:231], off
	s_waitcnt vmcnt(8)
	s_waitcnt lgkmcnt(0)
	s_barrier
	s_setprio 1
	s_waitcnt lgkmcnt(0)
	v_mfma_f32_16x16x32_bf16 v[112:115], v[128:131], v[198:201], v[112:115]
	v_mfma_f32_16x16x32_bf16 v[124:127], v[150:153], v[198:201], v[124:127]
	v_mfma_f32_16x16x32_bf16 v[120:123], v[128:131], v[206:209], v[120:123]
	v_mfma_f32_16x16x32_bf16 v[116:119], v[150:153], v[206:209], v[116:119]
	v_mfma_f32_16x16x32_bf16 v[108:111], v[128:131], v[214:217], v[108:111]
	v_mfma_f32_16x16x32_bf16 v[104:107], v[150:153], v[214:217], v[104:107]
	v_mfma_f32_16x16x32_bf16 v[92:95], v[128:131], v[222:225], v[92:95]
	v_mfma_f32_16x16x32_bf16 v[88:91], v[150:153], v[222:225], v[88:91]
	v_mfma_f32_16x16x32_bf16 v[112:115], v[132:135], v[202:205], v[112:115]
	v_mfma_f32_16x16x32_bf16 v[124:127], v[154:157], v[202:205], v[124:127]
	v_mfma_f32_16x16x32_bf16 v[120:123], v[132:135], v[210:213], v[120:123]
	v_mfma_f32_16x16x32_bf16 v[116:119], v[154:157], v[210:213], v[116:119]
	v_mfma_f32_16x16x32_bf16 v[108:111], v[132:135], v[218:221], v[108:111]
	v_mfma_f32_16x16x32_bf16 v[104:107], v[154:157], v[218:221], v[104:107]
	v_mfma_f32_16x16x32_bf16 v[92:95], v[132:135], v[226:229], v[92:95]
	v_mfma_f32_16x16x32_bf16 v[88:91], v[154:157], v[226:229], v[88:91]
	s_setprio 0
	s_setprio 1
	v_mfma_f32_16x16x32_bf16 v[100:103], v[182:185], v[198:201], v[100:103]
	v_mfma_f32_16x16x32_bf16 v[96:99], v[190:193], v[198:201], v[96:99]
	v_mfma_f32_16x16x32_bf16 v[84:87], v[182:185], v[206:209], v[84:87]
	v_mfma_f32_16x16x32_bf16 v[80:83], v[190:193], v[206:209], v[80:83]
	v_mfma_f32_16x16x32_bf16 v[76:79], v[182:185], v[214:217], v[76:79]
	v_mfma_f32_16x16x32_bf16 v[72:75], v[190:193], v[214:217], v[72:75]
	v_mfma_f32_16x16x32_bf16 v[60:63], v[182:185], v[222:225], v[60:63]
	v_mfma_f32_16x16x32_bf16 v[56:59], v[190:193], v[222:225], v[56:59]
	v_mfma_f32_16x16x32_bf16 v[100:103], v[186:189], v[202:205], v[100:103]
	v_mfma_f32_16x16x32_bf16 v[96:99], v[194:197], v[202:205], v[96:99]
	v_mfma_f32_16x16x32_bf16 v[84:87], v[186:189], v[210:213], v[84:87]
	v_mfma_f32_16x16x32_bf16 v[80:83], v[194:197], v[210:213], v[80:83]
	v_mfma_f32_16x16x32_bf16 v[76:79], v[186:189], v[218:221], v[76:79]
	v_mfma_f32_16x16x32_bf16 v[72:75], v[194:197], v[218:221], v[72:75]
	v_mfma_f32_16x16x32_bf16 v[60:63], v[186:189], v[226:229], v[60:63]
	v_mfma_f32_16x16x32_bf16 v[56:59], v[194:197], v[226:229], v[56:59]
	s_setprio 0
	s_barrier
	s_mov_b32 m0, s88
	v_lshl_add_u64 v[230:231], s[52:53], 0, v[138:139]
	v_lshl_add_u64 v[232:233], s[52:53], 0, v[142:143]
	s_add_u32 s52, s52, s12
	ds_read_b128 v[198:201], v160 offset:16384
	ds_read_b128 v[202:205], v160 offset:17408
	ds_read_b128 v[206:209], v160 offset:18432
	ds_read_b128 v[210:213], v160 offset:19456
	ds_read_b128 v[214:217], v160 offset:20480
	ds_read_b128 v[218:221], v160 offset:21504
	ds_read_b128 v[222:225], v160 offset:22528
	ds_read_b128 v[226:229], v160 offset:23552
	global_load_lds_dwordx4 v[230:231], off
	s_mov_b32 m0, s89
	s_addc_u32 s53, s53, s13
	global_load_lds_dwordx4 v[232:233], off
	v_lshl_add_u64 v[234:235], s[52:53], 0, v[138:139]
	s_mov_b32 m0, s91
	v_lshl_add_u64 v[236:237], s[52:53], 0, v[142:143]
	global_load_lds_dwordx4 v[234:235], off
	s_mov_b32 m0, s92
	v_lshl_add_u64 v[238:239], s[8:9], 0, v[136:137]
	global_load_lds_dwordx4 v[236:237], off
	s_mov_b32 m0, s3
	v_lshl_add_u64 v[240:241], s[8:9], 0, v[140:141]
	global_load_lds_dwordx4 v[238:239], off
	s_mov_b32 m0, s93
	s_nop 0
	global_load_lds_dwordx4 v[240:241], off
	s_waitcnt vmcnt(8)
	s_waitcnt lgkmcnt(0)
	s_barrier
	s_setprio 1
	s_waitcnt lgkmcnt(0)
	v_mfma_f32_16x16x32_bf16 v[68:71], v[128:131], v[198:201], v[68:71]
	v_mfma_f32_16x16x32_bf16 v[64:67], v[150:153], v[198:201], v[64:67]
	v_mfma_f32_16x16x32_bf16 v[52:55], v[128:131], v[206:209], v[52:55]
	v_mfma_f32_16x16x32_bf16 v[48:51], v[150:153], v[206:209], v[48:51]
	v_mfma_f32_16x16x32_bf16 v[44:47], v[128:131], v[214:217], v[44:47]
	v_mfma_f32_16x16x32_bf16 v[32:35], v[150:153], v[214:217], v[32:35]
	v_mfma_f32_16x16x32_bf16 v[24:27], v[128:131], v[222:225], v[24:27]
	v_mfma_f32_16x16x32_bf16 v[16:19], v[150:153], v[222:225], v[16:19]
	v_mfma_f32_16x16x32_bf16 v[68:71], v[132:135], v[202:205], v[68:71]
	v_mfma_f32_16x16x32_bf16 v[64:67], v[154:157], v[202:205], v[64:67]
	v_mfma_f32_16x16x32_bf16 v[52:55], v[132:135], v[210:213], v[52:55]
	v_mfma_f32_16x16x32_bf16 v[48:51], v[154:157], v[210:213], v[48:51]
	v_mfma_f32_16x16x32_bf16 v[44:47], v[132:135], v[218:221], v[44:47]
	v_mfma_f32_16x16x32_bf16 v[32:35], v[154:157], v[218:221], v[32:35]
	v_mfma_f32_16x16x32_bf16 v[24:27], v[132:135], v[226:229], v[24:27]
	v_mfma_f32_16x16x32_bf16 v[16:19], v[154:157], v[226:229], v[16:19]
	s_setprio 0
	s_setprio 1
	v_mfma_f32_16x16x32_bf16 v[40:43], v[182:185], v[198:201], v[40:43]
	v_mfma_f32_16x16x32_bf16 v[36:39], v[190:193], v[198:201], v[36:39]
	v_mfma_f32_16x16x32_bf16 v[28:31], v[182:185], v[206:209], v[28:31]
	v_mfma_f32_16x16x32_bf16 v[20:23], v[190:193], v[206:209], v[20:23]
	v_mfma_f32_16x16x32_bf16 v[12:15], v[182:185], v[214:217], v[12:15]
	v_mfma_f32_16x16x32_bf16 v[8:11], v[190:193], v[214:217], v[8:11]
	v_mfma_f32_16x16x32_bf16 v[4:7], v[182:185], v[222:225], v[4:7]
	v_mfma_f32_16x16x32_bf16 v[0:3], v[190:193], v[222:225], v[0:3]
	v_mfma_f32_16x16x32_bf16 v[40:43], v[186:189], v[202:205], v[40:43]
	v_mfma_f32_16x16x32_bf16 v[36:39], v[194:197], v[202:205], v[36:39]
	v_mfma_f32_16x16x32_bf16 v[28:31], v[186:189], v[210:213], v[28:31]
	v_mfma_f32_16x16x32_bf16 v[20:23], v[194:197], v[210:213], v[20:23]
	v_mfma_f32_16x16x32_bf16 v[12:15], v[186:189], v[218:221], v[12:15]
	v_mfma_f32_16x16x32_bf16 v[8:11], v[194:197], v[218:221], v[8:11]
	v_mfma_f32_16x16x32_bf16 v[4:7], v[186:189], v[226:229], v[4:7]
	v_mfma_f32_16x16x32_bf16 v[0:3], v[194:197], v[226:229], v[0:3]
	s_setprio 0
	s_barrier
	ds_read_b128 v[128:131], v171
	ds_read_b128 v[132:135], v172
	ds_read_b128 v[150:153], v173
	ds_read_b128 v[154:157], v174
	ds_read_b128 v[182:185], v175
	ds_read_b128 v[186:189], v176
	ds_read_b128 v[190:193], v177
	ds_read_b128 v[194:197], v178
	s_add_u32 s8, s8, s0
	s_addc_u32 s9, s9, s1
	s_mov_b32 m0, s94
	v_lshl_add_u64 v[242:243], s[8:9], 0, v[136:137]
	ds_read_b128 v[198:201], v160 offset:32768
	ds_read_b128 v[202:205], v160 offset:33792
	ds_read_b128 v[206:209], v160 offset:34816
	ds_read_b128 v[210:213], v160 offset:35840
	ds_read_b128 v[214:217], v160 offset:36864
	ds_read_b128 v[218:221], v160 offset:37888
	ds_read_b128 v[222:225], v160 offset:38912
	ds_read_b128 v[226:229], v160 offset:39936
	global_load_lds_dwordx4 v[242:243], off
	v_lshl_add_u64 v[242:243], s[8:9], 0, v[140:141]
	s_mov_b32 m0, s95
	s_nop 0
	global_load_lds_dwordx4 v[242:243], off
	s_waitcnt vmcnt(8)
	s_waitcnt lgkmcnt(0)
	s_barrier
	s_setprio 1
	s_waitcnt lgkmcnt(0)
	v_mfma_f32_16x16x32_bf16 v[112:115], v[128:131], v[198:201], v[112:115]
	v_mfma_f32_16x16x32_bf16 v[124:127], v[150:153], v[198:201], v[124:127]
	v_mfma_f32_16x16x32_bf16 v[120:123], v[128:131], v[206:209], v[120:123]
	v_mfma_f32_16x16x32_bf16 v[116:119], v[150:153], v[206:209], v[116:119]
	v_mfma_f32_16x16x32_bf16 v[108:111], v[128:131], v[214:217], v[108:111]
	v_mfma_f32_16x16x32_bf16 v[104:107], v[150:153], v[214:217], v[104:107]
	v_mfma_f32_16x16x32_bf16 v[92:95], v[128:131], v[222:225], v[92:95]
	v_mfma_f32_16x16x32_bf16 v[88:91], v[150:153], v[222:225], v[88:91]
	v_mfma_f32_16x16x32_bf16 v[112:115], v[132:135], v[202:205], v[112:115]
	v_mfma_f32_16x16x32_bf16 v[124:127], v[154:157], v[202:205], v[124:127]
	v_mfma_f32_16x16x32_bf16 v[120:123], v[132:135], v[210:213], v[120:123]
	v_mfma_f32_16x16x32_bf16 v[116:119], v[154:157], v[210:213], v[116:119]
	v_mfma_f32_16x16x32_bf16 v[108:111], v[132:135], v[218:221], v[108:111]
	v_mfma_f32_16x16x32_bf16 v[104:107], v[154:157], v[218:221], v[104:107]
	v_mfma_f32_16x16x32_bf16 v[92:95], v[132:135], v[226:229], v[92:95]
	v_mfma_f32_16x16x32_bf16 v[88:91], v[154:157], v[226:229], v[88:91]
	s_setprio 0
	s_setprio 1
	v_mfma_f32_16x16x32_bf16 v[100:103], v[182:185], v[198:201], v[100:103]
	v_mfma_f32_16x16x32_bf16 v[96:99], v[190:193], v[198:201], v[96:99]
	v_mfma_f32_16x16x32_bf16 v[84:87], v[182:185], v[206:209], v[84:87]
	v_mfma_f32_16x16x32_bf16 v[80:83], v[190:193], v[206:209], v[80:83]
	v_mfma_f32_16x16x32_bf16 v[76:79], v[182:185], v[214:217], v[76:79]
	v_mfma_f32_16x16x32_bf16 v[72:75], v[190:193], v[214:217], v[72:75]
	v_mfma_f32_16x16x32_bf16 v[60:63], v[182:185], v[222:225], v[60:63]
	v_mfma_f32_16x16x32_bf16 v[56:59], v[190:193], v[222:225], v[56:59]
	v_mfma_f32_16x16x32_bf16 v[100:103], v[186:189], v[202:205], v[100:103]
	v_mfma_f32_16x16x32_bf16 v[96:99], v[194:197], v[202:205], v[96:99]
	v_mfma_f32_16x16x32_bf16 v[84:87], v[186:189], v[210:213], v[84:87]
	v_mfma_f32_16x16x32_bf16 v[80:83], v[194:197], v[210:213], v[80:83]
	v_mfma_f32_16x16x32_bf16 v[76:79], v[186:189], v[218:221], v[76:79]
	v_mfma_f32_16x16x32_bf16 v[72:75], v[194:197], v[218:221], v[72:75]
	v_mfma_f32_16x16x32_bf16 v[60:63], v[186:189], v[226:229], v[60:63]
	v_mfma_f32_16x16x32_bf16 v[56:59], v[194:197], v[226:229], v[56:59]
	s_setprio 0
	s_barrier
	s_mov_b32 m0, s97
	v_lshl_add_u64 v[230:231], v[230:231], 0, s[46:47]
	ds_read_b128 v[198:201], v160 offset:49152
	ds_read_b128 v[202:205], v160 offset:50176
	ds_read_b128 v[206:209], v160 offset:51200
	ds_read_b128 v[210:213], v160 offset:52224
	ds_read_b128 v[214:217], v160 offset:53248
	ds_read_b128 v[218:221], v160 offset:54272
	ds_read_b128 v[222:225], v160 offset:55296
	ds_read_b128 v[226:229], v160 offset:56320
	global_load_lds_dwordx4 v[230:231], off
	v_lshl_add_u64 v[230:231], v[232:233], 0, s[46:47]
	s_mov_b32 m0, s96
	s_nop 0
	global_load_lds_dwordx4 v[230:231], off
	v_lshl_add_u64 v[230:231], v[234:235], 0, s[46:47]
	s_mov_b32 m0, s90
	s_nop 0
	global_load_lds_dwordx4 v[230:231], off
	v_lshl_add_u64 v[230:231], v[236:237], 0, s[46:47]
	s_mov_b32 m0, s28
	s_nop 0
	global_load_lds_dwordx4 v[230:231], off
	v_lshl_add_u64 v[230:231], v[238:239], 0, s[46:47]
	s_mov_b32 m0, s20
	s_nop 0
	global_load_lds_dwordx4 v[230:231], off
	v_lshl_add_u64 v[230:231], v[240:241], 0, s[46:47]
	s_mov_b32 m0, s21
	s_nop 0
	global_load_lds_dwordx4 v[230:231], off
	s_waitcnt vmcnt(8)
	s_waitcnt lgkmcnt(0)
	s_barrier
	s_setprio 1
	s_waitcnt lgkmcnt(0)
	v_mfma_f32_16x16x32_bf16 v[68:71], v[128:131], v[198:201], v[68:71]
	v_mfma_f32_16x16x32_bf16 v[64:67], v[150:153], v[198:201], v[64:67]
	v_mfma_f32_16x16x32_bf16 v[52:55], v[128:131], v[206:209], v[52:55]
	v_mfma_f32_16x16x32_bf16 v[48:51], v[150:153], v[206:209], v[48:51]
	v_mfma_f32_16x16x32_bf16 v[44:47], v[128:131], v[214:217], v[44:47]
	v_mfma_f32_16x16x32_bf16 v[32:35], v[150:153], v[214:217], v[32:35]
	v_mfma_f32_16x16x32_bf16 v[24:27], v[128:131], v[222:225], v[24:27]
	v_mfma_f32_16x16x32_bf16 v[16:19], v[150:153], v[222:225], v[16:19]
	v_mfma_f32_16x16x32_bf16 v[68:71], v[132:135], v[202:205], v[68:71]
	v_mfma_f32_16x16x32_bf16 v[64:67], v[154:157], v[202:205], v[64:67]
	v_mfma_f32_16x16x32_bf16 v[52:55], v[132:135], v[210:213], v[52:55]
	v_mfma_f32_16x16x32_bf16 v[48:51], v[154:157], v[210:213], v[48:51]
	v_mfma_f32_16x16x32_bf16 v[44:47], v[132:135], v[218:221], v[44:47]
	v_mfma_f32_16x16x32_bf16 v[32:35], v[154:157], v[218:221], v[32:35]
	v_mfma_f32_16x16x32_bf16 v[24:27], v[132:135], v[226:229], v[24:27]
	v_mfma_f32_16x16x32_bf16 v[16:19], v[154:157], v[226:229], v[16:19]
	s_setprio 0
	s_setprio 1
	v_mfma_f32_16x16x32_bf16 v[40:43], v[182:185], v[198:201], v[40:43]
	v_mfma_f32_16x16x32_bf16 v[36:39], v[190:193], v[198:201], v[36:39]
	v_mfma_f32_16x16x32_bf16 v[28:31], v[182:185], v[206:209], v[28:31]
	v_mfma_f32_16x16x32_bf16 v[20:23], v[190:193], v[206:209], v[20:23]
	v_mfma_f32_16x16x32_bf16 v[12:15], v[182:185], v[214:217], v[12:15]
	v_mfma_f32_16x16x32_bf16 v[8:11], v[190:193], v[214:217], v[8:11]
	v_mfma_f32_16x16x32_bf16 v[4:7], v[182:185], v[222:225], v[4:7]
	v_mfma_f32_16x16x32_bf16 v[0:3], v[190:193], v[222:225], v[0:3]
	v_mfma_f32_16x16x32_bf16 v[40:43], v[186:189], v[202:205], v[40:43]
	v_mfma_f32_16x16x32_bf16 v[36:39], v[194:197], v[202:205], v[36:39]
	v_mfma_f32_16x16x32_bf16 v[28:31], v[186:189], v[210:213], v[28:31]
	v_mfma_f32_16x16x32_bf16 v[20:23], v[194:197], v[210:213], v[20:23]
	v_mfma_f32_16x16x32_bf16 v[12:15], v[186:189], v[218:221], v[12:15]
	v_mfma_f32_16x16x32_bf16 v[8:11], v[194:197], v[218:221], v[8:11]
	v_mfma_f32_16x16x32_bf16 v[4:7], v[186:189], v[226:229], v[4:7]
	v_mfma_f32_16x16x32_bf16 v[0:3], v[194:197], v[226:229], v[0:3]
	s_setprio 0
	s_barrier
	s_add_u32 s6, s6, 0x100
	s_addc_u32 s7, s7, 0
	s_add_u32 s10, s10, 0x100
	s_addc_u32 s11, s11, 0
	s_cmp_ge_i32 s77, s29
	s_mov_b32 s70, s77
	s_cbranch_scc0 .LBB0_1095
	s_and_b64 vcc, exec, s[68:69]
	s_cbranch_vccz .LBB0_1098

.LBB0_1221:
	ds_read_b128 v[144:147], v155
	ds_read_b128 v[148:151], v156
	ds_read_b128 v[176:179], v157
	ds_read_b128 v[180:183], v158
	ds_read_b128 v[184:187], v159
	ds_read_b128 v[188:191], v160
	ds_read_b128 v[192:195], v161
	ds_read_b128 v[196:199], v164
	s_add_i32 s14, s8, 2
	s_add_u32 s15, s0, 0x80
	s_addc_u32 s9, s1, 0
	s_cmp_eq_u32 s89, s8
	s_cselect_b32 s8, s70, s15
	s_cselect_b32 s9, s71, s9
	s_cselect_b32 s53, s73, s11
	s_cselect_b32 s52, s72, s10
	s_mov_b32 m0, s94
	v_lshl_add_u64 v[232:233], s[0:1], 0, v[136:137]
	ds_read_b128 v[200:203], v154
	ds_read_b128 v[204:207], v154 offset:1024
	ds_read_b128 v[208:211], v154 offset:2048
	ds_read_b128 v[212:215], v154 offset:3072
	ds_read_b128 v[216:219], v154 offset:4096
	ds_read_b128 v[220:223], v154 offset:5120
	ds_read_b128 v[224:227], v154 offset:6144
	ds_read_b128 v[228:231], v154 offset:7168
	global_load_lds_dwordx4 v[232:233], off
	v_lshl_add_u64 v[232:233], s[0:1], 0, v[138:139]
	s_mov_b32 m0, s95
	s_nop 0
	global_load_lds_dwordx4 v[232:233], off
	s_waitcnt vmcnt(8)
	s_waitcnt lgkmcnt(0)
	s_barrier
	s_setprio 1
	s_waitcnt lgkmcnt(0)
	v_mfma_f32_16x16x32_bf16 v[124:127], v[144:147], v[200:203], v[124:127]
	v_mfma_f32_16x16x32_bf16 v[120:123], v[176:179], v[200:203], v[120:123]
	v_mfma_f32_16x16x32_bf16 v[108:111], v[144:147], v[208:211], v[108:111]
	v_mfma_f32_16x16x32_bf16 v[104:107], v[176:179], v[208:211], v[104:107]
	v_mfma_f32_16x16x32_bf16 v[92:95], v[144:147], v[216:219], v[92:95]
	v_mfma_f32_16x16x32_bf16 v[88:91], v[176:179], v[216:219], v[88:91]
	v_mfma_f32_16x16x32_bf16 v[76:79], v[144:147], v[224:227], v[76:79]
	v_mfma_f32_16x16x32_bf16 v[72:75], v[176:179], v[224:227], v[72:75]
	v_mfma_f32_16x16x32_bf16 v[124:127], v[148:151], v[204:207], v[124:127]
	v_mfma_f32_16x16x32_bf16 v[120:123], v[180:183], v[204:207], v[120:123]
	v_mfma_f32_16x16x32_bf16 v[108:111], v[148:151], v[212:215], v[108:111]
	v_mfma_f32_16x16x32_bf16 v[104:107], v[180:183], v[212:215], v[104:107]
	v_mfma_f32_16x16x32_bf16 v[92:95], v[148:151], v[220:223], v[92:95]
	v_mfma_f32_16x16x32_bf16 v[88:91], v[180:183], v[220:223], v[88:91]
	v_mfma_f32_16x16x32_bf16 v[76:79], v[148:151], v[228:231], v[76:79]
	v_mfma_f32_16x16x32_bf16 v[72:75], v[180:183], v[228:231], v[72:75]
	s_setprio 0
	s_setprio 1
	v_mfma_f32_16x16x32_bf16 v[116:119], v[184:187], v[200:203], v[116:119]
	v_mfma_f32_16x16x32_bf16 v[112:115], v[192:195], v[200:203], v[112:115]
	v_mfma_f32_16x16x32_bf16 v[100:103], v[184:187], v[208:211], v[100:103]
	v_mfma_f32_16x16x32_bf16 v[96:99], v[192:195], v[208:211], v[96:99]
	v_mfma_f32_16x16x32_bf16 v[84:87], v[184:187], v[216:219], v[84:87]
	v_mfma_f32_16x16x32_bf16 v[80:83], v[192:195], v[216:219], v[80:83]
	v_mfma_f32_16x16x32_bf16 v[68:71], v[184:187], v[224:227], v[68:71]
	v_mfma_f32_16x16x32_bf16 v[64:67], v[192:195], v[224:227], v[64:67]
	v_mfma_f32_16x16x32_bf16 v[116:119], v[188:191], v[204:207], v[116:119]
	v_mfma_f32_16x16x32_bf16 v[112:115], v[196:199], v[204:207], v[112:115]
	v_mfma_f32_16x16x32_bf16 v[100:103], v[188:191], v[212:215], v[100:103]
	v_mfma_f32_16x16x32_bf16 v[96:99], v[196:199], v[212:215], v[96:99]
	v_mfma_f32_16x16x32_bf16 v[84:87], v[188:191], v[220:223], v[84:87]
	v_mfma_f32_16x16x32_bf16 v[80:83], v[196:199], v[220:223], v[80:83]
	v_mfma_f32_16x16x32_bf16 v[68:71], v[188:191], v[228:231], v[68:71]
	v_mfma_f32_16x16x32_bf16 v[64:67], v[196:199], v[228:231], v[64:67]
	s_setprio 0
	s_barrier
	s_mov_b32 m0, s20
	v_lshl_add_u64 v[232:233], s[52:53], 0, v[130:131]
	v_lshl_add_u64 v[234:235], s[52:53], 0, v[134:135]
	s_add_u32 s52, s52, s36
	ds_read_b128 v[200:203], v154 offset:16384
	ds_read_b128 v[204:207], v154 offset:17408
	ds_read_b128 v[208:211], v154 offset:18432
	ds_read_b128 v[212:215], v154 offset:19456
	ds_read_b128 v[216:219], v154 offset:20480
	ds_read_b128 v[220:223], v154 offset:21504
	ds_read_b128 v[224:227], v154 offset:22528
	ds_read_b128 v[228:231], v154 offset:23552
	global_load_lds_dwordx4 v[232:233], off
	s_mov_b32 m0, s21
	s_addc_u32 s53, s53, s37
	global_load_lds_dwordx4 v[234:235], off
	v_lshl_add_u64 v[236:237], s[52:53], 0, v[130:131]
	s_mov_b32 m0, s28
	v_lshl_add_u64 v[238:239], s[52:53], 0, v[134:135]
	global_load_lds_dwordx4 v[236:237], off
	s_mov_b32 m0, s29
	v_lshl_add_u64 v[240:241], s[8:9], 0, v[128:129]
	global_load_lds_dwordx4 v[238:239], off
	s_mov_b32 m0, s3
	v_lshl_add_u64 v[242:243], s[8:9], 0, v[132:133]
	global_load_lds_dwordx4 v[240:241], off
	s_mov_b32 m0, s30
	s_nop 0
	global_load_lds_dwordx4 v[242:243], off
	s_waitcnt vmcnt(8)
	s_waitcnt lgkmcnt(0)
	s_barrier
	s_setprio 1
	s_waitcnt lgkmcnt(0)
	v_mfma_f32_16x16x32_bf16 v[60:63], v[144:147], v[200:203], v[60:63]
	v_mfma_f32_16x16x32_bf16 v[56:59], v[176:179], v[200:203], v[56:59]
	v_mfma_f32_16x16x32_bf16 v[44:47], v[144:147], v[208:211], v[44:47]
	v_mfma_f32_16x16x32_bf16 v[40:43], v[176:179], v[208:211], v[40:43]
	v_mfma_f32_16x16x32_bf16 v[28:31], v[144:147], v[216:219], v[28:31]
	v_mfma_f32_16x16x32_bf16 v[24:27], v[176:179], v[216:219], v[24:27]
	v_mfma_f32_16x16x32_bf16 v[12:15], v[144:147], v[224:227], v[12:15]
	v_mfma_f32_16x16x32_bf16 v[8:11], v[176:179], v[224:227], v[8:11]
	v_mfma_f32_16x16x32_bf16 v[60:63], v[148:151], v[204:207], v[60:63]
	v_mfma_f32_16x16x32_bf16 v[56:59], v[180:183], v[204:207], v[56:59]
	v_mfma_f32_16x16x32_bf16 v[44:47], v[148:151], v[212:215], v[44:47]
	v_mfma_f32_16x16x32_bf16 v[40:43], v[180:183], v[212:215], v[40:43]
	v_mfma_f32_16x16x32_bf16 v[28:31], v[148:151], v[220:223], v[28:31]
	v_mfma_f32_16x16x32_bf16 v[24:27], v[180:183], v[220:223], v[24:27]
	v_mfma_f32_16x16x32_bf16 v[12:15], v[148:151], v[228:231], v[12:15]
	v_mfma_f32_16x16x32_bf16 v[8:11], v[180:183], v[228:231], v[8:11]
	s_setprio 0
	s_setprio 1
	v_mfma_f32_16x16x32_bf16 v[52:55], v[184:187], v[200:203], v[52:55]
	v_mfma_f32_16x16x32_bf16 v[48:51], v[192:195], v[200:203], v[48:51]
	v_mfma_f32_16x16x32_bf16 v[36:39], v[184:187], v[208:211], v[36:39]
	v_mfma_f32_16x16x32_bf16 v[32:35], v[192:195], v[208:211], v[32:35]
	v_mfma_f32_16x16x32_bf16 v[20:23], v[184:187], v[216:219], v[20:23]
	v_mfma_f32_16x16x32_bf16 v[16:19], v[192:195], v[216:219], v[16:19]
	v_mfma_f32_16x16x32_bf16 v[4:7], v[184:187], v[224:227], v[4:7]
	v_mfma_f32_16x16x32_bf16 v[0:3], v[192:195], v[224:227], v[0:3]
	v_mfma_f32_16x16x32_bf16 v[52:55], v[188:191], v[204:207], v[52:55]
	v_mfma_f32_16x16x32_bf16 v[48:51], v[196:199], v[204:207], v[48:51]
	v_mfma_f32_16x16x32_bf16 v[36:39], v[188:191], v[212:215], v[36:39]
	v_mfma_f32_16x16x32_bf16 v[32:35], v[196:199], v[212:215], v[32:35]
	v_mfma_f32_16x16x32_bf16 v[20:23], v[188:191], v[220:223], v[20:23]
	v_mfma_f32_16x16x32_bf16 v[16:19], v[196:199], v[220:223], v[16:19]
	v_mfma_f32_16x16x32_bf16 v[4:7], v[188:191], v[228:231], v[4:7]
	v_mfma_f32_16x16x32_bf16 v[0:3], v[196:199], v[228:231], v[0:3]
	s_setprio 0
	s_barrier
	ds_read_b128 v[144:147], v165
	ds_read_b128 v[148:151], v166
	ds_read_b128 v[176:179], v167
	ds_read_b128 v[180:183], v168
	ds_read_b128 v[184:187], v169
	ds_read_b128 v[188:191], v170
	ds_read_b128 v[192:195], v171
	ds_read_b128 v[196:199], v172
	s_add_u32 s8, s8, s26
	s_addc_u32 s9, s9, s27
	s_mov_b32 m0, s31
	v_lshl_add_u64 v[244:245], s[8:9], 0, v[128:129]
	ds_read_b128 v[200:203], v154 offset:32768
	ds_read_b128 v[204:207], v154 offset:33792
	ds_read_b128 v[208:211], v154 offset:34816
	ds_read_b128 v[212:215], v154 offset:35840
	ds_read_b128 v[216:219], v154 offset:36864
	ds_read_b128 v[220:223], v154 offset:37888
	ds_read_b128 v[224:227], v154 offset:38912
	ds_read_b128 v[228:231], v154 offset:39936
	global_load_lds_dwordx4 v[244:245], off
	v_lshl_add_u64 v[244:245], s[8:9], 0, v[132:133]
	s_mov_b32 m0, s33
	s_nop 0
	global_load_lds_dwordx4 v[244:245], off
	s_waitcnt vmcnt(8)
	s_waitcnt lgkmcnt(0)
	s_barrier
	s_setprio 1
	s_waitcnt lgkmcnt(0)
	v_mfma_f32_16x16x32_bf16 v[124:127], v[144:147], v[200:203], v[124:127]
	v_mfma_f32_16x16x32_bf16 v[120:123], v[176:179], v[200:203], v[120:123]
	v_mfma_f32_16x16x32_bf16 v[108:111], v[144:147], v[208:211], v[108:111]
	v_mfma_f32_16x16x32_bf16 v[104:107], v[176:179], v[208:211], v[104:107]
	v_mfma_f32_16x16x32_bf16 v[92:95], v[144:147], v[216:219], v[92:95]
	v_mfma_f32_16x16x32_bf16 v[88:91], v[176:179], v[216:219], v[88:91]
	v_mfma_f32_16x16x32_bf16 v[76:79], v[144:147], v[224:227], v[76:79]
	v_mfma_f32_16x16x32_bf16 v[72:75], v[176:179], v[224:227], v[72:75]
	v_mfma_f32_16x16x32_bf16 v[124:127], v[148:151], v[204:207], v[124:127]
	v_mfma_f32_16x16x32_bf16 v[120:123], v[180:183], v[204:207], v[120:123]
	v_mfma_f32_16x16x32_bf16 v[108:111], v[148:151], v[212:215], v[108:111]
	v_mfma_f32_16x16x32_bf16 v[104:107], v[180:183], v[212:215], v[104:107]
	v_mfma_f32_16x16x32_bf16 v[92:95], v[148:151], v[220:223], v[92:95]
	v_mfma_f32_16x16x32_bf16 v[88:91], v[180:183], v[220:223], v[88:91]
	v_mfma_f32_16x16x32_bf16 v[76:79], v[148:151], v[228:231], v[76:79]
	v_mfma_f32_16x16x32_bf16 v[72:75], v[180:183], v[228:231], v[72:75]
	s_setprio 0
	s_setprio 1
	v_mfma_f32_16x16x32_bf16 v[116:119], v[184:187], v[200:203], v[116:119]
	v_mfma_f32_16x16x32_bf16 v[112:115], v[192:195], v[200:203], v[112:115]
	v_mfma_f32_16x16x32_bf16 v[100:103], v[184:187], v[208:211], v[100:103]
	v_mfma_f32_16x16x32_bf16 v[96:99], v[192:195], v[208:211], v[96:99]
	v_mfma_f32_16x16x32_bf16 v[84:87], v[184:187], v[216:219], v[84:87]
	v_mfma_f32_16x16x32_bf16 v[80:83], v[192:195], v[216:219], v[80:83]
	v_mfma_f32_16x16x32_bf16 v[68:71], v[184:187], v[224:227], v[68:71]
	v_mfma_f32_16x16x32_bf16 v[64:67], v[192:195], v[224:227], v[64:67]
	v_mfma_f32_16x16x32_bf16 v[116:119], v[188:191], v[204:207], v[116:119]
	v_mfma_f32_16x16x32_bf16 v[112:115], v[196:199], v[204:207], v[112:115]
	v_mfma_f32_16x16x32_bf16 v[100:103], v[188:191], v[212:215], v[100:103]
	v_mfma_f32_16x16x32_bf16 v[96:99], v[196:199], v[212:215], v[96:99]
	v_mfma_f32_16x16x32_bf16 v[84:87], v[188:191], v[220:223], v[84:87]
	v_mfma_f32_16x16x32_bf16 v[80:83], v[196:199], v[220:223], v[80:83]
	v_mfma_f32_16x16x32_bf16 v[68:71], v[188:191], v[228:231], v[68:71]
	v_mfma_f32_16x16x32_bf16 v[64:67], v[196:199], v[228:231], v[64:67]
	s_setprio 0
	s_barrier
	s_mov_b32 m0, s34
	v_lshl_add_u64 v[232:233], v[232:233], 0, s[66:67]
	ds_read_b128 v[200:203], v154 offset:49152
	ds_read_b128 v[204:207], v154 offset:50176
	ds_read_b128 v[208:211], v154 offset:51200
	ds_read_b128 v[212:215], v154 offset:52224
	ds_read_b128 v[216:219], v154 offset:53248
	ds_read_b128 v[220:223], v154 offset:54272
	ds_read_b128 v[224:227], v154 offset:55296
	ds_read_b128 v[228:231], v154 offset:56320
	global_load_lds_dwordx4 v[232:233], off
	v_lshl_add_u64 v[232:233], v[234:235], 0, s[66:67]
	s_mov_b32 m0, s35
	s_nop 0
	global_load_lds_dwordx4 v[232:233], off
	v_lshl_add_u64 v[232:233], v[236:237], 0, s[66:67]
	s_mov_b32 m0, s82
	s_nop 0
	global_load_lds_dwordx4 v[232:233], off
	v_lshl_add_u64 v[232:233], v[238:239], 0, s[66:67]
	s_mov_b32 m0, s83
	s_nop 0
	global_load_lds_dwordx4 v[232:233], off
	v_lshl_add_u64 v[232:233], v[240:241], 0, s[66:67]
	s_mov_b32 m0, s80
	s_nop 0
	global_load_lds_dwordx4 v[232:233], off
	v_lshl_add_u64 v[232:233], v[242:243], 0, s[66:67]
	s_mov_b32 m0, s81
	s_nop 0
	global_load_lds_dwordx4 v[232:233], off
	s_waitcnt vmcnt(8)
	s_waitcnt lgkmcnt(0)
	s_barrier
	s_setprio 1
	s_waitcnt lgkmcnt(0)
	v_mfma_f32_16x16x32_bf16 v[60:63], v[144:147], v[200:203], v[60:63]
	v_mfma_f32_16x16x32_bf16 v[56:59], v[176:179], v[200:203], v[56:59]
	v_mfma_f32_16x16x32_bf16 v[44:47], v[144:147], v[208:211], v[44:47]
	v_mfma_f32_16x16x32_bf16 v[40:43], v[176:179], v[208:211], v[40:43]
	v_mfma_f32_16x16x32_bf16 v[28:31], v[144:147], v[216:219], v[28:31]
	v_mfma_f32_16x16x32_bf16 v[24:27], v[176:179], v[216:219], v[24:27]
	v_mfma_f32_16x16x32_bf16 v[12:15], v[144:147], v[224:227], v[12:15]
	v_mfma_f32_16x16x32_bf16 v[8:11], v[176:179], v[224:227], v[8:11]
	v_mfma_f32_16x16x32_bf16 v[60:63], v[148:151], v[204:207], v[60:63]
	v_mfma_f32_16x16x32_bf16 v[56:59], v[180:183], v[204:207], v[56:59]
	v_mfma_f32_16x16x32_bf16 v[44:47], v[148:151], v[212:215], v[44:47]
	v_mfma_f32_16x16x32_bf16 v[40:43], v[180:183], v[212:215], v[40:43]
	v_mfma_f32_16x16x32_bf16 v[28:31], v[148:151], v[220:223], v[28:31]
	v_mfma_f32_16x16x32_bf16 v[24:27], v[180:183], v[220:223], v[24:27]
	v_mfma_f32_16x16x32_bf16 v[12:15], v[148:151], v[228:231], v[12:15]
	v_mfma_f32_16x16x32_bf16 v[8:11], v[180:183], v[228:231], v[8:11]
	s_setprio 0
	s_setprio 1
	v_mfma_f32_16x16x32_bf16 v[52:55], v[184:187], v[200:203], v[52:55]
	v_mfma_f32_16x16x32_bf16 v[48:51], v[192:195], v[200:203], v[48:51]
	v_mfma_f32_16x16x32_bf16 v[36:39], v[184:187], v[208:211], v[36:39]
	v_mfma_f32_16x16x32_bf16 v[32:35], v[192:195], v[208:211], v[32:35]
	v_mfma_f32_16x16x32_bf16 v[20:23], v[184:187], v[216:219], v[20:23]
	v_mfma_f32_16x16x32_bf16 v[16:19], v[192:195], v[216:219], v[16:19]
	v_mfma_f32_16x16x32_bf16 v[4:7], v[184:187], v[224:227], v[4:7]
	v_mfma_f32_16x16x32_bf16 v[0:3], v[192:195], v[224:227], v[0:3]
	v_mfma_f32_16x16x32_bf16 v[52:55], v[188:191], v[204:207], v[52:55]
	v_mfma_f32_16x16x32_bf16 v[48:51], v[196:199], v[204:207], v[48:51]
	v_mfma_f32_16x16x32_bf16 v[36:39], v[188:191], v[212:215], v[36:39]
	v_mfma_f32_16x16x32_bf16 v[32:35], v[196:199], v[212:215], v[32:35]
	v_mfma_f32_16x16x32_bf16 v[20:23], v[188:191], v[220:223], v[20:23]
	v_mfma_f32_16x16x32_bf16 v[16:19], v[196:199], v[220:223], v[16:19]
	v_mfma_f32_16x16x32_bf16 v[4:7], v[188:191], v[228:231], v[4:7]
	v_mfma_f32_16x16x32_bf16 v[0:3], v[196:199], v[228:231], v[0:3]
	s_setprio 0
	s_barrier
	s_add_u32 s0, s0, 0x100
	s_addc_u32 s1, s1, 0
	s_add_u32 s10, s10, 0x100
	s_addc_u32 s11, s11, 0
	s_cmp_ge_i32 s14, s84
	s_mov_b32 s8, s14
	s_cbranch_scc0 .LBB0_1221

.LBB0_1289:
	ds_read_b128 v[140:143], v147
	ds_read_b128 v[166:169], v148
	ds_read_b128 v[170:173], v149
	ds_read_b128 v[174:177], v150
	ds_read_b128 v[178:181], v151
	ds_read_b128 v[182:185], v152
	ds_read_b128 v[186:189], v153
	ds_read_b128 v[190:193], v154
	s_add_i32 s92, s66, 2
	s_add_u32 s54, s52, 0x80
	s_addc_u32 s55, s53, 0
	s_cmp_eq_u32 s77, s66
	s_cselect_b32 s66, s48, s54
	s_cselect_b32 s67, s49, s55
	s_cselect_b32 s55, s51, s91
	s_cselect_b32 s54, s50, s90
	s_mov_b32 m0, s80
	v_lshl_add_u64 v[226:227], s[52:53], 0, v[136:137]
	ds_read_b128 v[194:197], v146
	ds_read_b128 v[198:201], v146 offset:1024
	ds_read_b128 v[202:205], v146 offset:2048
	ds_read_b128 v[206:209], v146 offset:3072
	ds_read_b128 v[210:213], v146 offset:4096
	ds_read_b128 v[214:217], v146 offset:5120
	ds_read_b128 v[218:221], v146 offset:6144
	ds_read_b128 v[222:225], v146 offset:7168
	global_load_lds_dwordx4 v[226:227], off
	v_lshl_add_u64 v[226:227], s[52:53], 0, v[138:139]
	s_mov_b32 m0, s81
	s_nop 0
	global_load_lds_dwordx4 v[226:227], off
	s_waitcnt vmcnt(8)
	s_waitcnt lgkmcnt(0)
	s_barrier
	s_setprio 1
	s_waitcnt lgkmcnt(0)
	v_mfma_f32_16x16x32_bf16 v[124:127], v[140:143], v[194:197], v[124:127]
	v_mfma_f32_16x16x32_bf16 v[120:123], v[170:173], v[194:197], v[120:123]
	v_mfma_f32_16x16x32_bf16 v[108:111], v[140:143], v[202:205], v[108:111]
	v_mfma_f32_16x16x32_bf16 v[104:107], v[170:173], v[202:205], v[104:107]
	v_mfma_f32_16x16x32_bf16 v[92:95], v[140:143], v[210:213], v[92:95]
	v_mfma_f32_16x16x32_bf16 v[88:91], v[170:173], v[210:213], v[88:91]
	v_mfma_f32_16x16x32_bf16 v[76:79], v[140:143], v[218:221], v[76:79]
	v_mfma_f32_16x16x32_bf16 v[72:75], v[170:173], v[218:221], v[72:75]
	v_mfma_f32_16x16x32_bf16 v[124:127], v[166:169], v[198:201], v[124:127]
	v_mfma_f32_16x16x32_bf16 v[120:123], v[174:177], v[198:201], v[120:123]
	v_mfma_f32_16x16x32_bf16 v[108:111], v[166:169], v[206:209], v[108:111]
	v_mfma_f32_16x16x32_bf16 v[104:107], v[174:177], v[206:209], v[104:107]
	v_mfma_f32_16x16x32_bf16 v[92:95], v[166:169], v[214:217], v[92:95]
	v_mfma_f32_16x16x32_bf16 v[88:91], v[174:177], v[214:217], v[88:91]
	v_mfma_f32_16x16x32_bf16 v[76:79], v[166:169], v[222:225], v[76:79]
	v_mfma_f32_16x16x32_bf16 v[72:75], v[174:177], v[222:225], v[72:75]
	s_setprio 0
	s_setprio 1
	v_mfma_f32_16x16x32_bf16 v[116:119], v[178:181], v[194:197], v[116:119]
	v_mfma_f32_16x16x32_bf16 v[112:115], v[186:189], v[194:197], v[112:115]
	v_mfma_f32_16x16x32_bf16 v[100:103], v[178:181], v[202:205], v[100:103]
	v_mfma_f32_16x16x32_bf16 v[96:99], v[186:189], v[202:205], v[96:99]
	v_mfma_f32_16x16x32_bf16 v[84:87], v[178:181], v[210:213], v[84:87]
	v_mfma_f32_16x16x32_bf16 v[80:83], v[186:189], v[210:213], v[80:83]
	v_mfma_f32_16x16x32_bf16 v[68:71], v[178:181], v[218:221], v[68:71]
	v_mfma_f32_16x16x32_bf16 v[64:67], v[186:189], v[218:221], v[64:67]
	v_mfma_f32_16x16x32_bf16 v[116:119], v[182:185], v[198:201], v[116:119]
	v_mfma_f32_16x16x32_bf16 v[112:115], v[190:193], v[198:201], v[112:115]
	v_mfma_f32_16x16x32_bf16 v[100:103], v[182:185], v[206:209], v[100:103]
	v_mfma_f32_16x16x32_bf16 v[96:99], v[190:193], v[206:209], v[96:99]
	v_mfma_f32_16x16x32_bf16 v[84:87], v[182:185], v[214:217], v[84:87]
	v_mfma_f32_16x16x32_bf16 v[80:83], v[190:193], v[214:217], v[80:83]
	v_mfma_f32_16x16x32_bf16 v[68:71], v[182:185], v[222:225], v[68:71]
	v_mfma_f32_16x16x32_bf16 v[64:67], v[190:193], v[222:225], v[64:67]
	s_setprio 0
	s_barrier
	s_mov_b32 m0, s28
	v_lshl_add_u64 v[226:227], s[54:55], 0, v[130:131]
	v_lshl_add_u64 v[228:229], s[54:55], 0, v[134:135]
	s_add_u32 s54, s54, s10
	ds_read_b128 v[194:197], v146 offset:16384
	ds_read_b128 v[198:201], v146 offset:17408
	ds_read_b128 v[202:205], v146 offset:18432
	ds_read_b128 v[206:209], v146 offset:19456
	ds_read_b128 v[210:213], v146 offset:20480
	ds_read_b128 v[214:217], v146 offset:21504
	ds_read_b128 v[218:221], v146 offset:22528
	ds_read_b128 v[222:225], v146 offset:23552
	global_load_lds_dwordx4 v[226:227], off
	s_mov_b32 m0, s29
	s_addc_u32 s55, s55, s11
	global_load_lds_dwordx4 v[228:229], off
	v_lshl_add_u64 v[230:231], s[54:55], 0, v[130:131]
	s_mov_b32 m0, s30
	v_lshl_add_u64 v[232:233], s[54:55], 0, v[134:135]
	global_load_lds_dwordx4 v[230:231], off
	s_mov_b32 m0, s31
	v_lshl_add_u64 v[234:235], s[66:67], 0, v[128:129]
	global_load_lds_dwordx4 v[232:233], off
	s_mov_b32 m0, s21
	v_lshl_add_u64 v[236:237], s[66:67], 0, v[132:133]
	global_load_lds_dwordx4 v[234:235], off
	s_mov_b32 m0, s33
	s_nop 0
	global_load_lds_dwordx4 v[236:237], off
	s_waitcnt vmcnt(8)
	s_waitcnt lgkmcnt(0)
	s_barrier
	s_setprio 1
	s_waitcnt lgkmcnt(0)
	v_mfma_f32_16x16x32_bf16 v[60:63], v[140:143], v[194:197], v[60:63]
	v_mfma_f32_16x16x32_bf16 v[56:59], v[170:173], v[194:197], v[56:59]
	v_mfma_f32_16x16x32_bf16 v[44:47], v[140:143], v[202:205], v[44:47]
	v_mfma_f32_16x16x32_bf16 v[40:43], v[170:173], v[202:205], v[40:43]
	v_mfma_f32_16x16x32_bf16 v[28:31], v[140:143], v[210:213], v[28:31]
	v_mfma_f32_16x16x32_bf16 v[24:27], v[170:173], v[210:213], v[24:27]
	v_mfma_f32_16x16x32_bf16 v[12:15], v[140:143], v[218:221], v[12:15]
	v_mfma_f32_16x16x32_bf16 v[8:11], v[170:173], v[218:221], v[8:11]
	v_mfma_f32_16x16x32_bf16 v[60:63], v[166:169], v[198:201], v[60:63]
	v_mfma_f32_16x16x32_bf16 v[56:59], v[174:177], v[198:201], v[56:59]
	v_mfma_f32_16x16x32_bf16 v[44:47], v[166:169], v[206:209], v[44:47]
	v_mfma_f32_16x16x32_bf16 v[40:43], v[174:177], v[206:209], v[40:43]
	v_mfma_f32_16x16x32_bf16 v[28:31], v[166:169], v[214:217], v[28:31]
	v_mfma_f32_16x16x32_bf16 v[24:27], v[174:177], v[214:217], v[24:27]
	v_mfma_f32_16x16x32_bf16 v[12:15], v[166:169], v[222:225], v[12:15]
	v_mfma_f32_16x16x32_bf16 v[8:11], v[174:177], v[222:225], v[8:11]
	s_setprio 0
	s_setprio 1
	v_mfma_f32_16x16x32_bf16 v[52:55], v[178:181], v[194:197], v[52:55]
	v_mfma_f32_16x16x32_bf16 v[48:51], v[186:189], v[194:197], v[48:51]
	v_mfma_f32_16x16x32_bf16 v[36:39], v[178:181], v[202:205], v[36:39]
	v_mfma_f32_16x16x32_bf16 v[32:35], v[186:189], v[202:205], v[32:35]
	v_mfma_f32_16x16x32_bf16 v[20:23], v[178:181], v[210:213], v[20:23]
	v_mfma_f32_16x16x32_bf16 v[16:19], v[186:189], v[210:213], v[16:19]
	v_mfma_f32_16x16x32_bf16 v[4:7], v[178:181], v[218:221], v[4:7]
	v_mfma_f32_16x16x32_bf16 v[0:3], v[186:189], v[218:221], v[0:3]
	v_mfma_f32_16x16x32_bf16 v[52:55], v[182:185], v[198:201], v[52:55]
	v_mfma_f32_16x16x32_bf16 v[48:51], v[190:193], v[198:201], v[48:51]
	v_mfma_f32_16x16x32_bf16 v[36:39], v[182:185], v[206:209], v[36:39]
	v_mfma_f32_16x16x32_bf16 v[32:35], v[190:193], v[206:209], v[32:35]
	v_mfma_f32_16x16x32_bf16 v[20:23], v[182:185], v[214:217], v[20:23]
	v_mfma_f32_16x16x32_bf16 v[16:19], v[190:193], v[214:217], v[16:19]
	v_mfma_f32_16x16x32_bf16 v[4:7], v[182:185], v[222:225], v[4:7]
	v_mfma_f32_16x16x32_bf16 v[0:3], v[190:193], v[222:225], v[0:3]
	s_setprio 0
	s_barrier
	ds_read_b128 v[140:143], v155
	ds_read_b128 v[166:169], v156
	ds_read_b128 v[170:173], v157
	ds_read_b128 v[174:177], v158
	ds_read_b128 v[178:181], v159
	ds_read_b128 v[182:185], v160
	ds_read_b128 v[186:189], v161
	ds_read_b128 v[190:193], v164
	s_add_u32 s54, s66, s0
	s_addc_u32 s55, s67, s1
	s_mov_b32 m0, s34
	v_lshl_add_u64 v[238:239], s[54:55], 0, v[128:129]
	ds_read_b128 v[194:197], v146 offset:32768
	ds_read_b128 v[198:201], v146 offset:33792
	ds_read_b128 v[202:205], v146 offset:34816
	ds_read_b128 v[206:209], v146 offset:35840
	ds_read_b128 v[210:213], v146 offset:36864
	ds_read_b128 v[214:217], v146 offset:37888
	ds_read_b128 v[218:221], v146 offset:38912
	ds_read_b128 v[222:225], v146 offset:39936
	global_load_lds_dwordx4 v[238:239], off
	v_lshl_add_u64 v[238:239], s[54:55], 0, v[132:133]
	s_mov_b32 m0, s35
	s_nop 0
	global_load_lds_dwordx4 v[238:239], off
	s_waitcnt vmcnt(8)
	s_waitcnt lgkmcnt(0)
	s_barrier
	s_setprio 1
	s_waitcnt lgkmcnt(0)
	v_mfma_f32_16x16x32_bf16 v[124:127], v[140:143], v[194:197], v[124:127]
	v_mfma_f32_16x16x32_bf16 v[120:123], v[170:173], v[194:197], v[120:123]
	v_mfma_f32_16x16x32_bf16 v[108:111], v[140:143], v[202:205], v[108:111]
	v_mfma_f32_16x16x32_bf16 v[104:107], v[170:173], v[202:205], v[104:107]
	v_mfma_f32_16x16x32_bf16 v[92:95], v[140:143], v[210:213], v[92:95]
	v_mfma_f32_16x16x32_bf16 v[88:91], v[170:173], v[210:213], v[88:91]
	v_mfma_f32_16x16x32_bf16 v[76:79], v[140:143], v[218:221], v[76:79]
	v_mfma_f32_16x16x32_bf16 v[72:75], v[170:173], v[218:221], v[72:75]
	v_mfma_f32_16x16x32_bf16 v[124:127], v[166:169], v[198:201], v[124:127]
	v_mfma_f32_16x16x32_bf16 v[120:123], v[174:177], v[198:201], v[120:123]
	v_mfma_f32_16x16x32_bf16 v[108:111], v[166:169], v[206:209], v[108:111]
	v_mfma_f32_16x16x32_bf16 v[104:107], v[174:177], v[206:209], v[104:107]
	v_mfma_f32_16x16x32_bf16 v[92:95], v[166:169], v[214:217], v[92:95]
	v_mfma_f32_16x16x32_bf16 v[88:91], v[174:177], v[214:217], v[88:91]
	v_mfma_f32_16x16x32_bf16 v[76:79], v[166:169], v[222:225], v[76:79]
	v_mfma_f32_16x16x32_bf16 v[72:75], v[174:177], v[222:225], v[72:75]
	s_setprio 0
	s_setprio 1
	v_mfma_f32_16x16x32_bf16 v[116:119], v[178:181], v[194:197], v[116:119]
	v_mfma_f32_16x16x32_bf16 v[112:115], v[186:189], v[194:197], v[112:115]
	v_mfma_f32_16x16x32_bf16 v[100:103], v[178:181], v[202:205], v[100:103]
	v_mfma_f32_16x16x32_bf16 v[96:99], v[186:189], v[202:205], v[96:99]
	v_mfma_f32_16x16x32_bf16 v[84:87], v[178:181], v[210:213], v[84:87]
	v_mfma_f32_16x16x32_bf16 v[80:83], v[186:189], v[210:213], v[80:83]
	v_mfma_f32_16x16x32_bf16 v[68:71], v[178:181], v[218:221], v[68:71]
	v_mfma_f32_16x16x32_bf16 v[64:67], v[186:189], v[218:221], v[64:67]
	v_mfma_f32_16x16x32_bf16 v[116:119], v[182:185], v[198:201], v[116:119]
	v_mfma_f32_16x16x32_bf16 v[112:115], v[190:193], v[198:201], v[112:115]
	v_mfma_f32_16x16x32_bf16 v[100:103], v[182:185], v[206:209], v[100:103]
	v_mfma_f32_16x16x32_bf16 v[96:99], v[190:193], v[206:209], v[96:99]
	v_mfma_f32_16x16x32_bf16 v[84:87], v[182:185], v[214:217], v[84:87]
	v_mfma_f32_16x16x32_bf16 v[80:83], v[190:193], v[214:217], v[80:83]
	v_mfma_f32_16x16x32_bf16 v[68:71], v[182:185], v[222:225], v[68:71]
	v_mfma_f32_16x16x32_bf16 v[64:67], v[190:193], v[222:225], v[64:67]
	s_setprio 0
	s_barrier
	s_mov_b32 m0, s68
	v_lshl_add_u64 v[226:227], v[226:227], 0, s[26:27]
	ds_read_b128 v[194:197], v146 offset:49152
	ds_read_b128 v[198:201], v146 offset:50176
	ds_read_b128 v[202:205], v146 offset:51200
	ds_read_b128 v[206:209], v146 offset:52224
	ds_read_b128 v[210:213], v146 offset:53248
	ds_read_b128 v[214:217], v146 offset:54272
	ds_read_b128 v[218:221], v146 offset:55296
	ds_read_b128 v[222:225], v146 offset:56320
	global_load_lds_dwordx4 v[226:227], off
	v_lshl_add_u64 v[226:227], v[228:229], 0, s[26:27]
	s_mov_b32 m0, s69
	s_nop 0
	global_load_lds_dwordx4 v[226:227], off
	v_lshl_add_u64 v[226:227], v[230:231], 0, s[26:27]
	s_mov_b32 m0, s72
	s_nop 0
	global_load_lds_dwordx4 v[226:227], off
	v_lshl_add_u64 v[226:227], v[232:233], 0, s[26:27]
	s_mov_b32 m0, s73
	s_nop 0
	global_load_lds_dwordx4 v[226:227], off
	v_lshl_add_u64 v[226:227], v[234:235], 0, s[26:27]
	s_mov_b32 m0, s70
	s_nop 0
	global_load_lds_dwordx4 v[226:227], off
	v_lshl_add_u64 v[226:227], v[236:237], 0, s[26:27]
	s_mov_b32 m0, s71
	s_nop 0
	global_load_lds_dwordx4 v[226:227], off
	s_waitcnt vmcnt(8)
	s_waitcnt lgkmcnt(0)
	s_barrier
	s_setprio 1
	s_waitcnt lgkmcnt(0)
	v_mfma_f32_16x16x32_bf16 v[60:63], v[140:143], v[194:197], v[60:63]
	v_mfma_f32_16x16x32_bf16 v[56:59], v[170:173], v[194:197], v[56:59]
	v_mfma_f32_16x16x32_bf16 v[44:47], v[140:143], v[202:205], v[44:47]
	v_mfma_f32_16x16x32_bf16 v[40:43], v[170:173], v[202:205], v[40:43]
	v_mfma_f32_16x16x32_bf16 v[28:31], v[140:143], v[210:213], v[28:31]
	v_mfma_f32_16x16x32_bf16 v[24:27], v[170:173], v[210:213], v[24:27]
	v_mfma_f32_16x16x32_bf16 v[12:15], v[140:143], v[218:221], v[12:15]
	v_mfma_f32_16x16x32_bf16 v[8:11], v[170:173], v[218:221], v[8:11]
	v_mfma_f32_16x16x32_bf16 v[60:63], v[166:169], v[198:201], v[60:63]
	v_mfma_f32_16x16x32_bf16 v[56:59], v[174:177], v[198:201], v[56:59]
	v_mfma_f32_16x16x32_bf16 v[44:47], v[166:169], v[206:209], v[44:47]
	v_mfma_f32_16x16x32_bf16 v[40:43], v[174:177], v[206:209], v[40:43]
	v_mfma_f32_16x16x32_bf16 v[28:31], v[166:169], v[214:217], v[28:31]
	v_mfma_f32_16x16x32_bf16 v[24:27], v[174:177], v[214:217], v[24:27]
	v_mfma_f32_16x16x32_bf16 v[12:15], v[166:169], v[222:225], v[12:15]
	v_mfma_f32_16x16x32_bf16 v[8:11], v[174:177], v[222:225], v[8:11]
	s_setprio 0
	s_setprio 1
	v_mfma_f32_16x16x32_bf16 v[52:55], v[178:181], v[194:197], v[52:55]
	v_mfma_f32_16x16x32_bf16 v[48:51], v[186:189], v[194:197], v[48:51]
	v_mfma_f32_16x16x32_bf16 v[36:39], v[178:181], v[202:205], v[36:39]
	v_mfma_f32_16x16x32_bf16 v[32:35], v[186:189], v[202:205], v[32:35]
	v_mfma_f32_16x16x32_bf16 v[20:23], v[178:181], v[210:213], v[20:23]
	v_mfma_f32_16x16x32_bf16 v[16:19], v[186:189], v[210:213], v[16:19]
	v_mfma_f32_16x16x32_bf16 v[4:7], v[178:181], v[218:221], v[4:7]
	v_mfma_f32_16x16x32_bf16 v[0:3], v[186:189], v[218:221], v[0:3]
	v_mfma_f32_16x16x32_bf16 v[52:55], v[182:185], v[198:201], v[52:55]
	v_mfma_f32_16x16x32_bf16 v[48:51], v[190:193], v[198:201], v[48:51]
	v_mfma_f32_16x16x32_bf16 v[36:39], v[182:185], v[206:209], v[36:39]
	v_mfma_f32_16x16x32_bf16 v[32:35], v[190:193], v[206:209], v[32:35]
	v_mfma_f32_16x16x32_bf16 v[20:23], v[182:185], v[214:217], v[20:23]
	v_mfma_f32_16x16x32_bf16 v[16:19], v[190:193], v[214:217], v[16:19]
	v_mfma_f32_16x16x32_bf16 v[4:7], v[182:185], v[222:225], v[4:7]
	v_mfma_f32_16x16x32_bf16 v[0:3], v[190:193], v[222:225], v[0:3]
	s_setprio 0
	s_barrier
	s_add_u32 s52, s52, 0x100
	s_addc_u32 s53, s53, 0
	s_add_u32 s90, s90, 0x100
	s_addc_u32 s91, s91, 0
	s_cmp_ge_i32 s92, s74
	s_mov_b32 s66, s92
	s_cbranch_scc0 .LBB0_1289

.LBB0_1484:
	ds_read_b128 v[144:147], v151
	ds_read_b128 v[170:173], v152
	ds_read_b128 v[174:177], v153
	ds_read_b128 v[178:181], v154
	ds_read_b128 v[182:185], v155
	ds_read_b128 v[186:189], v156
	ds_read_b128 v[190:193], v157
	ds_read_b128 v[194:197], v158
	s_add_i32 s84, s50, 2
	s_add_u32 s56, s48, 0x80
	s_addc_u32 s51, s49, 0
	s_cmp_eq_u32 s71, s50
	s_cselect_b32 s50, s0, s56
	s_cselect_b32 s51, s1, s51
	s_cselect_b32 s57, s43, s83
	s_cselect_b32 s56, s42, s47
	s_mov_b32 m0, s76
	v_lshl_add_u64 v[230:231], s[48:49], 0, v[136:137]
	ds_read_b128 v[198:201], v150
	ds_read_b128 v[202:205], v150 offset:1024
	ds_read_b128 v[206:209], v150 offset:2048
	ds_read_b128 v[210:213], v150 offset:3072
	ds_read_b128 v[214:217], v150 offset:4096
	ds_read_b128 v[218:221], v150 offset:5120
	ds_read_b128 v[222:225], v150 offset:6144
	ds_read_b128 v[226:229], v150 offset:7168
	global_load_lds_dwordx4 v[230:231], off
	v_lshl_add_u64 v[230:231], s[48:49], 0, v[138:139]
	s_mov_b32 m0, s77
	s_nop 0
	global_load_lds_dwordx4 v[230:231], off
	s_waitcnt vmcnt(8)
	s_waitcnt lgkmcnt(0)
	s_barrier
	s_setprio 1
	s_waitcnt lgkmcnt(0)
	v_mfma_f32_16x16x32_bf16 v[124:127], v[144:147], v[198:201], v[124:127]
	v_mfma_f32_16x16x32_bf16 v[120:123], v[174:177], v[198:201], v[120:123]
	v_mfma_f32_16x16x32_bf16 v[108:111], v[144:147], v[206:209], v[108:111]
	v_mfma_f32_16x16x32_bf16 v[104:107], v[174:177], v[206:209], v[104:107]
	v_mfma_f32_16x16x32_bf16 v[92:95], v[144:147], v[214:217], v[92:95]
	v_mfma_f32_16x16x32_bf16 v[88:91], v[174:177], v[214:217], v[88:91]
	v_mfma_f32_16x16x32_bf16 v[76:79], v[144:147], v[222:225], v[76:79]
	v_mfma_f32_16x16x32_bf16 v[72:75], v[174:177], v[222:225], v[72:75]
	v_mfma_f32_16x16x32_bf16 v[124:127], v[170:173], v[202:205], v[124:127]
	v_mfma_f32_16x16x32_bf16 v[120:123], v[178:181], v[202:205], v[120:123]
	v_mfma_f32_16x16x32_bf16 v[108:111], v[170:173], v[210:213], v[108:111]
	v_mfma_f32_16x16x32_bf16 v[104:107], v[178:181], v[210:213], v[104:107]
	v_mfma_f32_16x16x32_bf16 v[92:95], v[170:173], v[218:221], v[92:95]
	v_mfma_f32_16x16x32_bf16 v[88:91], v[178:181], v[218:221], v[88:91]
	v_mfma_f32_16x16x32_bf16 v[76:79], v[170:173], v[226:229], v[76:79]
	v_mfma_f32_16x16x32_bf16 v[72:75], v[178:181], v[226:229], v[72:75]
	s_setprio 0
	s_setprio 1
	v_mfma_f32_16x16x32_bf16 v[116:119], v[182:185], v[198:201], v[116:119]
	v_mfma_f32_16x16x32_bf16 v[112:115], v[190:193], v[198:201], v[112:115]
	v_mfma_f32_16x16x32_bf16 v[100:103], v[182:185], v[206:209], v[100:103]
	v_mfma_f32_16x16x32_bf16 v[96:99], v[190:193], v[206:209], v[96:99]
	v_mfma_f32_16x16x32_bf16 v[84:87], v[182:185], v[214:217], v[84:87]
	v_mfma_f32_16x16x32_bf16 v[80:83], v[190:193], v[214:217], v[80:83]
	v_mfma_f32_16x16x32_bf16 v[68:71], v[182:185], v[222:225], v[68:71]
	v_mfma_f32_16x16x32_bf16 v[64:67], v[190:193], v[222:225], v[64:67]
	v_mfma_f32_16x16x32_bf16 v[116:119], v[186:189], v[202:205], v[116:119]
	v_mfma_f32_16x16x32_bf16 v[112:115], v[194:197], v[202:205], v[112:115]
	v_mfma_f32_16x16x32_bf16 v[100:103], v[186:189], v[210:213], v[100:103]
	v_mfma_f32_16x16x32_bf16 v[96:99], v[194:197], v[210:213], v[96:99]
	v_mfma_f32_16x16x32_bf16 v[84:87], v[186:189], v[218:221], v[84:87]
	v_mfma_f32_16x16x32_bf16 v[80:83], v[194:197], v[218:221], v[80:83]
	v_mfma_f32_16x16x32_bf16 v[68:71], v[186:189], v[226:229], v[68:71]
	v_mfma_f32_16x16x32_bf16 v[64:67], v[194:197], v[226:229], v[64:67]
	s_setprio 0
	s_barrier
	s_mov_b32 m0, s28
	v_lshl_add_u64 v[230:231], s[56:57], 0, v[130:131]
	v_lshl_add_u64 v[232:233], s[56:57], 0, v[134:135]
	s_add_u32 s56, s56, s12
	ds_read_b128 v[198:201], v150 offset:16384
	ds_read_b128 v[202:205], v150 offset:17408
	ds_read_b128 v[206:209], v150 offset:18432
	ds_read_b128 v[210:213], v150 offset:19456
	ds_read_b128 v[214:217], v150 offset:20480
	ds_read_b128 v[218:221], v150 offset:21504
	ds_read_b128 v[222:225], v150 offset:22528
	ds_read_b128 v[226:229], v150 offset:23552
	global_load_lds_dwordx4 v[230:231], off
	s_mov_b32 m0, s29
	s_addc_u32 s57, s57, s13
	global_load_lds_dwordx4 v[232:233], off
	v_lshl_add_u64 v[234:235], s[56:57], 0, v[130:131]
	s_mov_b32 m0, s30
	v_lshl_add_u64 v[236:237], s[56:57], 0, v[134:135]
	global_load_lds_dwordx4 v[234:235], off
	s_mov_b32 m0, s31
	v_lshl_add_u64 v[238:239], s[50:51], 0, v[128:129]
	global_load_lds_dwordx4 v[236:237], off
	s_mov_b32 m0, s21
	v_lshl_add_u64 v[240:241], s[50:51], 0, v[132:133]
	global_load_lds_dwordx4 v[238:239], off
	s_mov_b32 m0, s33
	s_nop 0
	global_load_lds_dwordx4 v[240:241], off
	s_waitcnt vmcnt(8)
	s_waitcnt lgkmcnt(0)
	s_barrier
	s_setprio 1
	s_waitcnt lgkmcnt(0)
	v_mfma_f32_16x16x32_bf16 v[60:63], v[144:147], v[198:201], v[60:63]
	v_mfma_f32_16x16x32_bf16 v[56:59], v[174:177], v[198:201], v[56:59]
	v_mfma_f32_16x16x32_bf16 v[44:47], v[144:147], v[206:209], v[44:47]
	v_mfma_f32_16x16x32_bf16 v[40:43], v[174:177], v[206:209], v[40:43]
	v_mfma_f32_16x16x32_bf16 v[28:31], v[144:147], v[214:217], v[28:31]
	v_mfma_f32_16x16x32_bf16 v[24:27], v[174:177], v[214:217], v[24:27]
	v_mfma_f32_16x16x32_bf16 v[12:15], v[144:147], v[222:225], v[12:15]
	v_mfma_f32_16x16x32_bf16 v[8:11], v[174:177], v[222:225], v[8:11]
	v_mfma_f32_16x16x32_bf16 v[60:63], v[170:173], v[202:205], v[60:63]
	v_mfma_f32_16x16x32_bf16 v[56:59], v[178:181], v[202:205], v[56:59]
	v_mfma_f32_16x16x32_bf16 v[44:47], v[170:173], v[210:213], v[44:47]
	v_mfma_f32_16x16x32_bf16 v[40:43], v[178:181], v[210:213], v[40:43]
	v_mfma_f32_16x16x32_bf16 v[28:31], v[170:173], v[218:221], v[28:31]
	v_mfma_f32_16x16x32_bf16 v[24:27], v[178:181], v[218:221], v[24:27]
	v_mfma_f32_16x16x32_bf16 v[12:15], v[170:173], v[226:229], v[12:15]
	v_mfma_f32_16x16x32_bf16 v[8:11], v[178:181], v[226:229], v[8:11]
	s_setprio 0
	s_setprio 1
	v_mfma_f32_16x16x32_bf16 v[52:55], v[182:185], v[198:201], v[52:55]
	v_mfma_f32_16x16x32_bf16 v[48:51], v[190:193], v[198:201], v[48:51]
	v_mfma_f32_16x16x32_bf16 v[36:39], v[182:185], v[206:209], v[36:39]
	v_mfma_f32_16x16x32_bf16 v[32:35], v[190:193], v[206:209], v[32:35]
	v_mfma_f32_16x16x32_bf16 v[20:23], v[182:185], v[214:217], v[20:23]
	v_mfma_f32_16x16x32_bf16 v[16:19], v[190:193], v[214:217], v[16:19]
	v_mfma_f32_16x16x32_bf16 v[4:7], v[182:185], v[222:225], v[4:7]
	v_mfma_f32_16x16x32_bf16 v[0:3], v[190:193], v[222:225], v[0:3]
	v_mfma_f32_16x16x32_bf16 v[52:55], v[186:189], v[202:205], v[52:55]
	v_mfma_f32_16x16x32_bf16 v[48:51], v[194:197], v[202:205], v[48:51]
	v_mfma_f32_16x16x32_bf16 v[36:39], v[186:189], v[210:213], v[36:39]
	v_mfma_f32_16x16x32_bf16 v[32:35], v[194:197], v[210:213], v[32:35]
	v_mfma_f32_16x16x32_bf16 v[20:23], v[186:189], v[218:221], v[20:23]
	v_mfma_f32_16x16x32_bf16 v[16:19], v[194:197], v[218:221], v[16:19]
	v_mfma_f32_16x16x32_bf16 v[4:7], v[186:189], v[226:229], v[4:7]
	v_mfma_f32_16x16x32_bf16 v[0:3], v[194:197], v[226:229], v[0:3]
	s_setprio 0
	s_barrier
	ds_read_b128 v[144:147], v159
	ds_read_b128 v[170:173], v160
	ds_read_b128 v[174:177], v161
	ds_read_b128 v[178:181], v164
	ds_read_b128 v[182:185], v165
	ds_read_b128 v[186:189], v166
	ds_read_b128 v[190:193], v167
	ds_read_b128 v[194:197], v168
	s_add_u32 s50, s50, s10
	s_addc_u32 s51, s51, s11
	s_mov_b32 m0, s34
	v_lshl_add_u64 v[242:243], s[50:51], 0, v[128:129]
	ds_read_b128 v[198:201], v150 offset:32768
	ds_read_b128 v[202:205], v150 offset:33792
	ds_read_b128 v[206:209], v150 offset:34816
	ds_read_b128 v[210:213], v150 offset:35840
	ds_read_b128 v[214:217], v150 offset:36864
	ds_read_b128 v[218:221], v150 offset:37888
	ds_read_b128 v[222:225], v150 offset:38912
	ds_read_b128 v[226:229], v150 offset:39936
	global_load_lds_dwordx4 v[242:243], off
	v_lshl_add_u64 v[242:243], s[50:51], 0, v[132:133]
	s_mov_b32 m0, s35
	s_nop 0
	global_load_lds_dwordx4 v[242:243], off
	s_waitcnt vmcnt(8)
	s_waitcnt lgkmcnt(0)
	s_barrier
	s_setprio 1
	s_waitcnt lgkmcnt(0)
	v_mfma_f32_16x16x32_bf16 v[124:127], v[144:147], v[198:201], v[124:127]
	v_mfma_f32_16x16x32_bf16 v[120:123], v[174:177], v[198:201], v[120:123]
	v_mfma_f32_16x16x32_bf16 v[108:111], v[144:147], v[206:209], v[108:111]
	v_mfma_f32_16x16x32_bf16 v[104:107], v[174:177], v[206:209], v[104:107]
	v_mfma_f32_16x16x32_bf16 v[92:95], v[144:147], v[214:217], v[92:95]
	v_mfma_f32_16x16x32_bf16 v[88:91], v[174:177], v[214:217], v[88:91]
	v_mfma_f32_16x16x32_bf16 v[76:79], v[144:147], v[222:225], v[76:79]
	v_mfma_f32_16x16x32_bf16 v[72:75], v[174:177], v[222:225], v[72:75]
	v_mfma_f32_16x16x32_bf16 v[124:127], v[170:173], v[202:205], v[124:127]
	v_mfma_f32_16x16x32_bf16 v[120:123], v[178:181], v[202:205], v[120:123]
	v_mfma_f32_16x16x32_bf16 v[108:111], v[170:173], v[210:213], v[108:111]
	v_mfma_f32_16x16x32_bf16 v[104:107], v[178:181], v[210:213], v[104:107]
	v_mfma_f32_16x16x32_bf16 v[92:95], v[170:173], v[218:221], v[92:95]
	v_mfma_f32_16x16x32_bf16 v[88:91], v[178:181], v[218:221], v[88:91]
	v_mfma_f32_16x16x32_bf16 v[76:79], v[170:173], v[226:229], v[76:79]
	v_mfma_f32_16x16x32_bf16 v[72:75], v[178:181], v[226:229], v[72:75]
	s_setprio 0
	s_setprio 1
	v_mfma_f32_16x16x32_bf16 v[116:119], v[182:185], v[198:201], v[116:119]
	v_mfma_f32_16x16x32_bf16 v[112:115], v[190:193], v[198:201], v[112:115]
	v_mfma_f32_16x16x32_bf16 v[100:103], v[182:185], v[206:209], v[100:103]
	v_mfma_f32_16x16x32_bf16 v[96:99], v[190:193], v[206:209], v[96:99]
	v_mfma_f32_16x16x32_bf16 v[84:87], v[182:185], v[214:217], v[84:87]
	v_mfma_f32_16x16x32_bf16 v[80:83], v[190:193], v[214:217], v[80:83]
	v_mfma_f32_16x16x32_bf16 v[68:71], v[182:185], v[222:225], v[68:71]
	v_mfma_f32_16x16x32_bf16 v[64:67], v[190:193], v[222:225], v[64:67]
	v_mfma_f32_16x16x32_bf16 v[116:119], v[186:189], v[202:205], v[116:119]
	v_mfma_f32_16x16x32_bf16 v[112:115], v[194:197], v[202:205], v[112:115]
	v_mfma_f32_16x16x32_bf16 v[100:103], v[186:189], v[210:213], v[100:103]
	v_mfma_f32_16x16x32_bf16 v[96:99], v[194:197], v[210:213], v[96:99]
	v_mfma_f32_16x16x32_bf16 v[84:87], v[186:189], v[218:221], v[84:87]
	v_mfma_f32_16x16x32_bf16 v[80:83], v[194:197], v[218:221], v[80:83]
	v_mfma_f32_16x16x32_bf16 v[68:71], v[186:189], v[226:229], v[68:71]
	v_mfma_f32_16x16x32_bf16 v[64:67], v[194:197], v[226:229], v[64:67]
	s_setprio 0
	s_barrier
	s_mov_b32 m0, s78
	v_lshl_add_u64 v[230:231], v[230:231], 0, s[26:27]
	ds_read_b128 v[198:201], v150 offset:49152
	ds_read_b128 v[202:205], v150 offset:50176
	ds_read_b128 v[206:209], v150 offset:51200
	ds_read_b128 v[210:213], v150 offset:52224
	ds_read_b128 v[214:217], v150 offset:53248
	ds_read_b128 v[218:221], v150 offset:54272
	ds_read_b128 v[222:225], v150 offset:55296
	ds_read_b128 v[226:229], v150 offset:56320
	global_load_lds_dwordx4 v[230:231], off
	v_lshl_add_u64 v[230:231], v[232:233], 0, s[26:27]
	s_mov_b32 m0, s79
	s_nop 0
	global_load_lds_dwordx4 v[230:231], off
	v_lshl_add_u64 v[230:231], v[234:235], 0, s[26:27]
	s_mov_b32 m0, s89
	s_nop 0
	global_load_lds_dwordx4 v[230:231], off
	v_lshl_add_u64 v[230:231], v[236:237], 0, s[26:27]
	s_mov_b32 m0, s90
	s_nop 0
	global_load_lds_dwordx4 v[230:231], off
	v_lshl_add_u64 v[230:231], v[238:239], 0, s[26:27]
	s_mov_b32 m0, s85
	s_nop 0
	global_load_lds_dwordx4 v[230:231], off
	v_lshl_add_u64 v[230:231], v[240:241], 0, s[26:27]
	s_mov_b32 m0, s88
	s_nop 0
	global_load_lds_dwordx4 v[230:231], off
	s_waitcnt vmcnt(8)
	s_waitcnt lgkmcnt(0)
	s_barrier
	s_setprio 1
	s_waitcnt lgkmcnt(0)
	v_mfma_f32_16x16x32_bf16 v[60:63], v[144:147], v[198:201], v[60:63]
	v_mfma_f32_16x16x32_bf16 v[56:59], v[174:177], v[198:201], v[56:59]
	v_mfma_f32_16x16x32_bf16 v[44:47], v[144:147], v[206:209], v[44:47]
	v_mfma_f32_16x16x32_bf16 v[40:43], v[174:177], v[206:209], v[40:43]
	v_mfma_f32_16x16x32_bf16 v[28:31], v[144:147], v[214:217], v[28:31]
	v_mfma_f32_16x16x32_bf16 v[24:27], v[174:177], v[214:217], v[24:27]
	v_mfma_f32_16x16x32_bf16 v[12:15], v[144:147], v[222:225], v[12:15]
	v_mfma_f32_16x16x32_bf16 v[8:11], v[174:177], v[222:225], v[8:11]
	v_mfma_f32_16x16x32_bf16 v[60:63], v[170:173], v[202:205], v[60:63]
	v_mfma_f32_16x16x32_bf16 v[56:59], v[178:181], v[202:205], v[56:59]
	v_mfma_f32_16x16x32_bf16 v[44:47], v[170:173], v[210:213], v[44:47]
	v_mfma_f32_16x16x32_bf16 v[40:43], v[178:181], v[210:213], v[40:43]
	v_mfma_f32_16x16x32_bf16 v[28:31], v[170:173], v[218:221], v[28:31]
	v_mfma_f32_16x16x32_bf16 v[24:27], v[178:181], v[218:221], v[24:27]
	v_mfma_f32_16x16x32_bf16 v[12:15], v[170:173], v[226:229], v[12:15]
	v_mfma_f32_16x16x32_bf16 v[8:11], v[178:181], v[226:229], v[8:11]
	s_setprio 0
	s_setprio 1
	v_mfma_f32_16x16x32_bf16 v[52:55], v[182:185], v[198:201], v[52:55]
	v_mfma_f32_16x16x32_bf16 v[48:51], v[190:193], v[198:201], v[48:51]
	v_mfma_f32_16x16x32_bf16 v[36:39], v[182:185], v[206:209], v[36:39]
	v_mfma_f32_16x16x32_bf16 v[32:35], v[190:193], v[206:209], v[32:35]
	v_mfma_f32_16x16x32_bf16 v[20:23], v[182:185], v[214:217], v[20:23]
	v_mfma_f32_16x16x32_bf16 v[16:19], v[190:193], v[214:217], v[16:19]
	v_mfma_f32_16x16x32_bf16 v[4:7], v[182:185], v[222:225], v[4:7]
	v_mfma_f32_16x16x32_bf16 v[0:3], v[190:193], v[222:225], v[0:3]
	v_mfma_f32_16x16x32_bf16 v[52:55], v[186:189], v[202:205], v[52:55]
	v_mfma_f32_16x16x32_bf16 v[48:51], v[194:197], v[202:205], v[48:51]
	v_mfma_f32_16x16x32_bf16 v[36:39], v[186:189], v[210:213], v[36:39]
	v_mfma_f32_16x16x32_bf16 v[32:35], v[194:197], v[210:213], v[32:35]
	v_mfma_f32_16x16x32_bf16 v[20:23], v[186:189], v[218:221], v[20:23]
	v_mfma_f32_16x16x32_bf16 v[16:19], v[194:197], v[218:221], v[16:19]
	v_mfma_f32_16x16x32_bf16 v[4:7], v[186:189], v[226:229], v[4:7]
	v_mfma_f32_16x16x32_bf16 v[0:3], v[194:197], v[226:229], v[0:3]
	s_setprio 0
	s_barrier
	s_add_u32 s48, s48, 0x100
	s_addc_u32 s49, s49, 0
	s_add_u32 s47, s47, 0x100
	s_addc_u32 s83, s83, 0
	s_cmp_ge_i32 s84, s68
	s_mov_b32 s50, s84
	s_cbranch_scc0 .LBB0_1484

.LBB0_1513:
	ds_read_b128 v[144:147], v151
	ds_read_b128 v[170:173], v152
	ds_read_b128 v[174:177], v153
	ds_read_b128 v[178:181], v154
	ds_read_b128 v[182:185], v155
	ds_read_b128 v[186:189], v156
	ds_read_b128 v[190:193], v157
	ds_read_b128 v[194:197], v158
	s_add_i32 s81, s50, 2
	s_add_u32 s58, s48, 0x80
	s_addc_u32 s51, s49, 0
	s_cmp_eq_u32 s68, s50
	s_cselect_b32 s50, s0, s58
	s_cselect_b32 s51, s1, s51
	s_cselect_b32 s59, s43, s80
	s_cselect_b32 s58, s42, s47
	s_mov_b32 m0, s73
	v_lshl_add_u64 v[230:231], s[48:49], 0, v[136:137]
	ds_read_b128 v[198:201], v150
	ds_read_b128 v[202:205], v150 offset:1024
	ds_read_b128 v[206:209], v150 offset:2048
	ds_read_b128 v[210:213], v150 offset:3072
	ds_read_b128 v[214:217], v150 offset:4096
	ds_read_b128 v[218:221], v150 offset:5120
	ds_read_b128 v[222:225], v150 offset:6144
	ds_read_b128 v[226:229], v150 offset:7168
	global_load_lds_dwordx4 v[230:231], off
	v_lshl_add_u64 v[230:231], s[48:49], 0, v[138:139]
	s_mov_b32 m0, s74
	s_nop 0
	global_load_lds_dwordx4 v[230:231], off
	s_waitcnt vmcnt(8)
	s_waitcnt lgkmcnt(0)
	s_barrier
	s_setprio 1
	s_waitcnt lgkmcnt(0)
	v_mfma_f32_16x16x32_bf16 v[124:127], v[144:147], v[198:201], v[124:127]
	v_mfma_f32_16x16x32_bf16 v[120:123], v[174:177], v[198:201], v[120:123]
	v_mfma_f32_16x16x32_bf16 v[108:111], v[144:147], v[206:209], v[108:111]
	v_mfma_f32_16x16x32_bf16 v[104:107], v[174:177], v[206:209], v[104:107]
	v_mfma_f32_16x16x32_bf16 v[92:95], v[144:147], v[214:217], v[92:95]
	v_mfma_f32_16x16x32_bf16 v[88:91], v[174:177], v[214:217], v[88:91]
	v_mfma_f32_16x16x32_bf16 v[76:79], v[144:147], v[222:225], v[76:79]
	v_mfma_f32_16x16x32_bf16 v[72:75], v[174:177], v[222:225], v[72:75]
	v_mfma_f32_16x16x32_bf16 v[124:127], v[170:173], v[202:205], v[124:127]
	v_mfma_f32_16x16x32_bf16 v[120:123], v[178:181], v[202:205], v[120:123]
	v_mfma_f32_16x16x32_bf16 v[108:111], v[170:173], v[210:213], v[108:111]
	v_mfma_f32_16x16x32_bf16 v[104:107], v[178:181], v[210:213], v[104:107]
	v_mfma_f32_16x16x32_bf16 v[92:95], v[170:173], v[218:221], v[92:95]
	v_mfma_f32_16x16x32_bf16 v[88:91], v[178:181], v[218:221], v[88:91]
	v_mfma_f32_16x16x32_bf16 v[76:79], v[170:173], v[226:229], v[76:79]
	v_mfma_f32_16x16x32_bf16 v[72:75], v[178:181], v[226:229], v[72:75]
	s_setprio 0
	s_setprio 1
	v_mfma_f32_16x16x32_bf16 v[116:119], v[182:185], v[198:201], v[116:119]
	v_mfma_f32_16x16x32_bf16 v[112:115], v[190:193], v[198:201], v[112:115]
	v_mfma_f32_16x16x32_bf16 v[100:103], v[182:185], v[206:209], v[100:103]
	v_mfma_f32_16x16x32_bf16 v[96:99], v[190:193], v[206:209], v[96:99]
	v_mfma_f32_16x16x32_bf16 v[84:87], v[182:185], v[214:217], v[84:87]
	v_mfma_f32_16x16x32_bf16 v[80:83], v[190:193], v[214:217], v[80:83]
	v_mfma_f32_16x16x32_bf16 v[68:71], v[182:185], v[222:225], v[68:71]
	v_mfma_f32_16x16x32_bf16 v[64:67], v[190:193], v[222:225], v[64:67]
	v_mfma_f32_16x16x32_bf16 v[116:119], v[186:189], v[202:205], v[116:119]
	v_mfma_f32_16x16x32_bf16 v[112:115], v[194:197], v[202:205], v[112:115]
	v_mfma_f32_16x16x32_bf16 v[100:103], v[186:189], v[210:213], v[100:103]
	v_mfma_f32_16x16x32_bf16 v[96:99], v[194:197], v[210:213], v[96:99]
	v_mfma_f32_16x16x32_bf16 v[84:87], v[186:189], v[218:221], v[84:87]
	v_mfma_f32_16x16x32_bf16 v[80:83], v[194:197], v[218:221], v[80:83]
	v_mfma_f32_16x16x32_bf16 v[68:71], v[186:189], v[226:229], v[68:71]
	v_mfma_f32_16x16x32_bf16 v[64:67], v[194:197], v[226:229], v[64:67]
	s_setprio 0
	s_barrier
	s_mov_b32 m0, s21
	v_lshl_add_u64 v[230:231], s[58:59], 0, v[130:131]
	v_lshl_add_u64 v[232:233], s[58:59], 0, v[134:135]
	s_add_u32 s58, s58, s12
	ds_read_b128 v[198:201], v150 offset:16384
	ds_read_b128 v[202:205], v150 offset:17408
	ds_read_b128 v[206:209], v150 offset:18432
	ds_read_b128 v[210:213], v150 offset:19456
	ds_read_b128 v[214:217], v150 offset:20480
	ds_read_b128 v[218:221], v150 offset:21504
	ds_read_b128 v[222:225], v150 offset:22528
	ds_read_b128 v[226:229], v150 offset:23552
	global_load_lds_dwordx4 v[230:231], off
	s_mov_b32 m0, s28
	s_addc_u32 s59, s59, s13
	global_load_lds_dwordx4 v[232:233], off
	v_lshl_add_u64 v[234:235], s[58:59], 0, v[130:131]
	s_mov_b32 m0, s29
	v_lshl_add_u64 v[236:237], s[58:59], 0, v[134:135]
	global_load_lds_dwordx4 v[234:235], off
	s_mov_b32 m0, s30
	v_lshl_add_u64 v[238:239], s[50:51], 0, v[128:129]
	global_load_lds_dwordx4 v[236:237], off
	s_mov_b32 m0, s20
	v_lshl_add_u64 v[240:241], s[50:51], 0, v[132:133]
	global_load_lds_dwordx4 v[238:239], off
	s_mov_b32 m0, s31
	s_nop 0
	global_load_lds_dwordx4 v[240:241], off
	s_waitcnt vmcnt(8)
	s_waitcnt lgkmcnt(0)
	s_barrier
	s_setprio 1
	s_waitcnt lgkmcnt(0)
	v_mfma_f32_16x16x32_bf16 v[60:63], v[144:147], v[198:201], v[60:63]
	v_mfma_f32_16x16x32_bf16 v[56:59], v[174:177], v[198:201], v[56:59]
	v_mfma_f32_16x16x32_bf16 v[44:47], v[144:147], v[206:209], v[44:47]
	v_mfma_f32_16x16x32_bf16 v[40:43], v[174:177], v[206:209], v[40:43]
	v_mfma_f32_16x16x32_bf16 v[28:31], v[144:147], v[214:217], v[28:31]
	v_mfma_f32_16x16x32_bf16 v[24:27], v[174:177], v[214:217], v[24:27]
	v_mfma_f32_16x16x32_bf16 v[12:15], v[144:147], v[222:225], v[12:15]
	v_mfma_f32_16x16x32_bf16 v[8:11], v[174:177], v[222:225], v[8:11]
	v_mfma_f32_16x16x32_bf16 v[60:63], v[170:173], v[202:205], v[60:63]
	v_mfma_f32_16x16x32_bf16 v[56:59], v[178:181], v[202:205], v[56:59]
	v_mfma_f32_16x16x32_bf16 v[44:47], v[170:173], v[210:213], v[44:47]
	v_mfma_f32_16x16x32_bf16 v[40:43], v[178:181], v[210:213], v[40:43]
	v_mfma_f32_16x16x32_bf16 v[28:31], v[170:173], v[218:221], v[28:31]
	v_mfma_f32_16x16x32_bf16 v[24:27], v[178:181], v[218:221], v[24:27]
	v_mfma_f32_16x16x32_bf16 v[12:15], v[170:173], v[226:229], v[12:15]
	v_mfma_f32_16x16x32_bf16 v[8:11], v[178:181], v[226:229], v[8:11]
	s_setprio 0
	s_setprio 1
	v_mfma_f32_16x16x32_bf16 v[52:55], v[182:185], v[198:201], v[52:55]
	v_mfma_f32_16x16x32_bf16 v[48:51], v[190:193], v[198:201], v[48:51]
	v_mfma_f32_16x16x32_bf16 v[36:39], v[182:185], v[206:209], v[36:39]
	v_mfma_f32_16x16x32_bf16 v[32:35], v[190:193], v[206:209], v[32:35]
	v_mfma_f32_16x16x32_bf16 v[20:23], v[182:185], v[214:217], v[20:23]
	v_mfma_f32_16x16x32_bf16 v[16:19], v[190:193], v[214:217], v[16:19]
	v_mfma_f32_16x16x32_bf16 v[4:7], v[182:185], v[222:225], v[4:7]
	v_mfma_f32_16x16x32_bf16 v[0:3], v[190:193], v[222:225], v[0:3]
	v_mfma_f32_16x16x32_bf16 v[52:55], v[186:189], v[202:205], v[52:55]
	v_mfma_f32_16x16x32_bf16 v[48:51], v[194:197], v[202:205], v[48:51]
	v_mfma_f32_16x16x32_bf16 v[36:39], v[186:189], v[210:213], v[36:39]
	v_mfma_f32_16x16x32_bf16 v[32:35], v[194:197], v[210:213], v[32:35]
	v_mfma_f32_16x16x32_bf16 v[20:23], v[186:189], v[218:221], v[20:23]
	v_mfma_f32_16x16x32_bf16 v[16:19], v[194:197], v[218:221], v[16:19]
	v_mfma_f32_16x16x32_bf16 v[4:7], v[186:189], v[226:229], v[4:7]
	v_mfma_f32_16x16x32_bf16 v[0:3], v[194:197], v[226:229], v[0:3]
	s_setprio 0
	s_barrier
	ds_read_b128 v[144:147], v159
	ds_read_b128 v[170:173], v160
	ds_read_b128 v[174:177], v161
	ds_read_b128 v[178:181], v164
	ds_read_b128 v[182:185], v165
	ds_read_b128 v[186:189], v166
	ds_read_b128 v[190:193], v167
	ds_read_b128 v[194:197], v168
	s_add_u32 s50, s50, s10
	s_addc_u32 s51, s51, s11
	s_mov_b32 m0, s33
	v_lshl_add_u64 v[242:243], s[50:51], 0, v[128:129]
	ds_read_b128 v[198:201], v150 offset:32768
	ds_read_b128 v[202:205], v150 offset:33792
	ds_read_b128 v[206:209], v150 offset:34816
	ds_read_b128 v[210:213], v150 offset:35840
	ds_read_b128 v[214:217], v150 offset:36864
	ds_read_b128 v[218:221], v150 offset:37888
	ds_read_b128 v[222:225], v150 offset:38912
	ds_read_b128 v[226:229], v150 offset:39936
	global_load_lds_dwordx4 v[242:243], off
	v_lshl_add_u64 v[242:243], s[50:51], 0, v[132:133]
	s_mov_b32 m0, s34
	s_nop 0
	global_load_lds_dwordx4 v[242:243], off
	s_waitcnt vmcnt(8)
	s_waitcnt lgkmcnt(0)
	s_barrier
	s_setprio 1
	s_waitcnt lgkmcnt(0)
	v_mfma_f32_16x16x32_bf16 v[124:127], v[144:147], v[198:201], v[124:127]
	v_mfma_f32_16x16x32_bf16 v[120:123], v[174:177], v[198:201], v[120:123]
	v_mfma_f32_16x16x32_bf16 v[108:111], v[144:147], v[206:209], v[108:111]
	v_mfma_f32_16x16x32_bf16 v[104:107], v[174:177], v[206:209], v[104:107]
	v_mfma_f32_16x16x32_bf16 v[92:95], v[144:147], v[214:217], v[92:95]
	v_mfma_f32_16x16x32_bf16 v[88:91], v[174:177], v[214:217], v[88:91]
	v_mfma_f32_16x16x32_bf16 v[76:79], v[144:147], v[222:225], v[76:79]
	v_mfma_f32_16x16x32_bf16 v[72:75], v[174:177], v[222:225], v[72:75]
	v_mfma_f32_16x16x32_bf16 v[124:127], v[170:173], v[202:205], v[124:127]
	v_mfma_f32_16x16x32_bf16 v[120:123], v[178:181], v[202:205], v[120:123]
	v_mfma_f32_16x16x32_bf16 v[108:111], v[170:173], v[210:213], v[108:111]
	v_mfma_f32_16x16x32_bf16 v[104:107], v[178:181], v[210:213], v[104:107]
	v_mfma_f32_16x16x32_bf16 v[92:95], v[170:173], v[218:221], v[92:95]
	v_mfma_f32_16x16x32_bf16 v[88:91], v[178:181], v[218:221], v[88:91]
	v_mfma_f32_16x16x32_bf16 v[76:79], v[170:173], v[226:229], v[76:79]
	v_mfma_f32_16x16x32_bf16 v[72:75], v[178:181], v[226:229], v[72:75]
	s_setprio 0
	s_setprio 1
	v_mfma_f32_16x16x32_bf16 v[116:119], v[182:185], v[198:201], v[116:119]
	v_mfma_f32_16x16x32_bf16 v[112:115], v[190:193], v[198:201], v[112:115]
	v_mfma_f32_16x16x32_bf16 v[100:103], v[182:185], v[206:209], v[100:103]
	v_mfma_f32_16x16x32_bf16 v[96:99], v[190:193], v[206:209], v[96:99]
	v_mfma_f32_16x16x32_bf16 v[84:87], v[182:185], v[214:217], v[84:87]
	v_mfma_f32_16x16x32_bf16 v[80:83], v[190:193], v[214:217], v[80:83]
	v_mfma_f32_16x16x32_bf16 v[68:71], v[182:185], v[222:225], v[68:71]
	v_mfma_f32_16x16x32_bf16 v[64:67], v[190:193], v[222:225], v[64:67]
	v_mfma_f32_16x16x32_bf16 v[116:119], v[186:189], v[202:205], v[116:119]
	v_mfma_f32_16x16x32_bf16 v[112:115], v[194:197], v[202:205], v[112:115]
	v_mfma_f32_16x16x32_bf16 v[100:103], v[186:189], v[210:213], v[100:103]
	v_mfma_f32_16x16x32_bf16 v[96:99], v[194:197], v[210:213], v[96:99]
	v_mfma_f32_16x16x32_bf16 v[84:87], v[186:189], v[218:221], v[84:87]
	v_mfma_f32_16x16x32_bf16 v[80:83], v[194:197], v[218:221], v[80:83]
	v_mfma_f32_16x16x32_bf16 v[68:71], v[186:189], v[226:229], v[68:71]
	v_mfma_f32_16x16x32_bf16 v[64:67], v[194:197], v[226:229], v[64:67]
	s_setprio 0
	s_barrier
	s_mov_b32 m0, s35
	v_lshl_add_u64 v[230:231], v[230:231], 0, s[24:25]
	ds_read_b128 v[198:201], v150 offset:49152
	ds_read_b128 v[202:205], v150 offset:50176
	ds_read_b128 v[206:209], v150 offset:51200
	ds_read_b128 v[210:213], v150 offset:52224
	ds_read_b128 v[214:217], v150 offset:53248
	ds_read_b128 v[218:221], v150 offset:54272
	ds_read_b128 v[222:225], v150 offset:55296
	ds_read_b128 v[226:229], v150 offset:56320
	global_load_lds_dwordx4 v[230:231], off
	v_lshl_add_u64 v[230:231], v[232:233], 0, s[24:25]
	s_mov_b32 m0, s78
	s_nop 0
	global_load_lds_dwordx4 v[230:231], off
	v_lshl_add_u64 v[230:231], v[234:235], 0, s[24:25]
	s_mov_b32 m0, s83
	s_nop 0
	global_load_lds_dwordx4 v[230:231], off
	v_lshl_add_u64 v[230:231], v[236:237], 0, s[24:25]
	s_mov_b32 m0, s84
	s_nop 0
	global_load_lds_dwordx4 v[230:231], off
	v_lshl_add_u64 v[230:231], v[238:239], 0, s[24:25]
	s_mov_b32 m0, s79
	s_nop 0
	global_load_lds_dwordx4 v[230:231], off
	v_lshl_add_u64 v[230:231], v[240:241], 0, s[24:25]
	s_mov_b32 m0, s82
	s_nop 0
	global_load_lds_dwordx4 v[230:231], off
	s_waitcnt vmcnt(8)
	s_waitcnt lgkmcnt(0)
	s_barrier
	s_setprio 1
	s_waitcnt lgkmcnt(0)
	v_mfma_f32_16x16x32_bf16 v[60:63], v[144:147], v[198:201], v[60:63]
	v_mfma_f32_16x16x32_bf16 v[56:59], v[174:177], v[198:201], v[56:59]
	v_mfma_f32_16x16x32_bf16 v[44:47], v[144:147], v[206:209], v[44:47]
	v_mfma_f32_16x16x32_bf16 v[40:43], v[174:177], v[206:209], v[40:43]
	v_mfma_f32_16x16x32_bf16 v[28:31], v[144:147], v[214:217], v[28:31]
	v_mfma_f32_16x16x32_bf16 v[24:27], v[174:177], v[214:217], v[24:27]
	v_mfma_f32_16x16x32_bf16 v[12:15], v[144:147], v[222:225], v[12:15]
	v_mfma_f32_16x16x32_bf16 v[8:11], v[174:177], v[222:225], v[8:11]
	v_mfma_f32_16x16x32_bf16 v[60:63], v[170:173], v[202:205], v[60:63]
	v_mfma_f32_16x16x32_bf16 v[56:59], v[178:181], v[202:205], v[56:59]
	v_mfma_f32_16x16x32_bf16 v[44:47], v[170:173], v[210:213], v[44:47]
	v_mfma_f32_16x16x32_bf16 v[40:43], v[178:181], v[210:213], v[40:43]
	v_mfma_f32_16x16x32_bf16 v[28:31], v[170:173], v[218:221], v[28:31]
	v_mfma_f32_16x16x32_bf16 v[24:27], v[178:181], v[218:221], v[24:27]
	v_mfma_f32_16x16x32_bf16 v[12:15], v[170:173], v[226:229], v[12:15]
	v_mfma_f32_16x16x32_bf16 v[8:11], v[178:181], v[226:229], v[8:11]
	s_setprio 0
	s_setprio 1
	v_mfma_f32_16x16x32_bf16 v[52:55], v[182:185], v[198:201], v[52:55]
	v_mfma_f32_16x16x32_bf16 v[48:51], v[190:193], v[198:201], v[48:51]
	v_mfma_f32_16x16x32_bf16 v[36:39], v[182:185], v[206:209], v[36:39]
	v_mfma_f32_16x16x32_bf16 v[32:35], v[190:193], v[206:209], v[32:35]
	v_mfma_f32_16x16x32_bf16 v[20:23], v[182:185], v[214:217], v[20:23]
	v_mfma_f32_16x16x32_bf16 v[16:19], v[190:193], v[214:217], v[16:19]
	v_mfma_f32_16x16x32_bf16 v[4:7], v[182:185], v[222:225], v[4:7]
	v_mfma_f32_16x16x32_bf16 v[0:3], v[190:193], v[222:225], v[0:3]
	v_mfma_f32_16x16x32_bf16 v[52:55], v[186:189], v[202:205], v[52:55]
	v_mfma_f32_16x16x32_bf16 v[48:51], v[194:197], v[202:205], v[48:51]
	v_mfma_f32_16x16x32_bf16 v[36:39], v[186:189], v[210:213], v[36:39]
	v_mfma_f32_16x16x32_bf16 v[32:35], v[194:197], v[210:213], v[32:35]
	v_mfma_f32_16x16x32_bf16 v[20:23], v[186:189], v[218:221], v[20:23]
	v_mfma_f32_16x16x32_bf16 v[16:19], v[194:197], v[218:221], v[16:19]
	v_mfma_f32_16x16x32_bf16 v[4:7], v[186:189], v[226:229], v[4:7]
	v_mfma_f32_16x16x32_bf16 v[0:3], v[194:197], v[226:229], v[0:3]
	s_setprio 0
	s_barrier
	s_add_u32 s48, s48, 0x100
	s_addc_u32 s49, s49, 0
	s_add_u32 s47, s47, 0x100
	s_addc_u32 s80, s80, 0
	s_cmp_ge_i32 s81, s85
	s_mov_b32 s50, s81
	s_cbranch_scc0 .LBB0_1513

.LBB0_1596:
	ds_read_b128 v[144:147], v151
	ds_read_b128 v[170:173], v152
	ds_read_b128 v[174:177], v153
	ds_read_b128 v[178:181], v154
	ds_read_b128 v[182:185], v155
	ds_read_b128 v[186:189], v156
	ds_read_b128 v[190:193], v157
	ds_read_b128 v[194:197], v158
	s_add_i32 s80, s54, 2
	s_add_u32 s60, s52, 0x80
	s_addc_u32 s55, s53, 0
	s_cmp_eq_u32 s68, s54
	s_cselect_b32 s54, s0, s60
	s_cselect_b32 s55, s1, s55
	s_cselect_b32 s61, s49, s79
	s_cselect_b32 s60, s48, s51
	s_mov_b32 m0, s73
	v_lshl_add_u64 v[230:231], s[52:53], 0, v[136:137]
	ds_read_b128 v[198:201], v150
	ds_read_b128 v[202:205], v150 offset:1024
	ds_read_b128 v[206:209], v150 offset:2048
	ds_read_b128 v[210:213], v150 offset:3072
	ds_read_b128 v[214:217], v150 offset:4096
	ds_read_b128 v[218:221], v150 offset:5120
	ds_read_b128 v[222:225], v150 offset:6144
	ds_read_b128 v[226:229], v150 offset:7168
	global_load_lds_dwordx4 v[230:231], off
	v_lshl_add_u64 v[230:231], s[52:53], 0, v[138:139]
	s_mov_b32 m0, s74
	s_nop 0
	global_load_lds_dwordx4 v[230:231], off
	s_waitcnt vmcnt(8)
	s_waitcnt lgkmcnt(0)
	s_barrier
	s_setprio 1
	s_waitcnt lgkmcnt(0)
	v_mfma_f32_16x16x32_bf16 v[124:127], v[144:147], v[198:201], v[124:127]
	v_mfma_f32_16x16x32_bf16 v[120:123], v[174:177], v[198:201], v[120:123]
	v_mfma_f32_16x16x32_bf16 v[108:111], v[144:147], v[206:209], v[108:111]
	v_mfma_f32_16x16x32_bf16 v[104:107], v[174:177], v[206:209], v[104:107]
	v_mfma_f32_16x16x32_bf16 v[92:95], v[144:147], v[214:217], v[92:95]
	v_mfma_f32_16x16x32_bf16 v[88:91], v[174:177], v[214:217], v[88:91]
	v_mfma_f32_16x16x32_bf16 v[76:79], v[144:147], v[222:225], v[76:79]
	v_mfma_f32_16x16x32_bf16 v[72:75], v[174:177], v[222:225], v[72:75]
	v_mfma_f32_16x16x32_bf16 v[124:127], v[170:173], v[202:205], v[124:127]
	v_mfma_f32_16x16x32_bf16 v[120:123], v[178:181], v[202:205], v[120:123]
	v_mfma_f32_16x16x32_bf16 v[108:111], v[170:173], v[210:213], v[108:111]
	v_mfma_f32_16x16x32_bf16 v[104:107], v[178:181], v[210:213], v[104:107]
	v_mfma_f32_16x16x32_bf16 v[92:95], v[170:173], v[218:221], v[92:95]
	v_mfma_f32_16x16x32_bf16 v[88:91], v[178:181], v[218:221], v[88:91]
	v_mfma_f32_16x16x32_bf16 v[76:79], v[170:173], v[226:229], v[76:79]
	v_mfma_f32_16x16x32_bf16 v[72:75], v[178:181], v[226:229], v[72:75]
	s_setprio 0
	s_setprio 1
	v_mfma_f32_16x16x32_bf16 v[116:119], v[182:185], v[198:201], v[116:119]
	v_mfma_f32_16x16x32_bf16 v[112:115], v[190:193], v[198:201], v[112:115]
	v_mfma_f32_16x16x32_bf16 v[100:103], v[182:185], v[206:209], v[100:103]
	v_mfma_f32_16x16x32_bf16 v[96:99], v[190:193], v[206:209], v[96:99]
	v_mfma_f32_16x16x32_bf16 v[84:87], v[182:185], v[214:217], v[84:87]
	v_mfma_f32_16x16x32_bf16 v[80:83], v[190:193], v[214:217], v[80:83]
	v_mfma_f32_16x16x32_bf16 v[68:71], v[182:185], v[222:225], v[68:71]
	v_mfma_f32_16x16x32_bf16 v[64:67], v[190:193], v[222:225], v[64:67]
	v_mfma_f32_16x16x32_bf16 v[116:119], v[186:189], v[202:205], v[116:119]
	v_mfma_f32_16x16x32_bf16 v[112:115], v[194:197], v[202:205], v[112:115]
	v_mfma_f32_16x16x32_bf16 v[100:103], v[186:189], v[210:213], v[100:103]
	v_mfma_f32_16x16x32_bf16 v[96:99], v[194:197], v[210:213], v[96:99]
	v_mfma_f32_16x16x32_bf16 v[84:87], v[186:189], v[218:221], v[84:87]
	v_mfma_f32_16x16x32_bf16 v[80:83], v[194:197], v[218:221], v[80:83]
	v_mfma_f32_16x16x32_bf16 v[68:71], v[186:189], v[226:229], v[68:71]
	v_mfma_f32_16x16x32_bf16 v[64:67], v[194:197], v[226:229], v[64:67]
	s_setprio 0
	s_barrier
	s_mov_b32 m0, s20
	v_lshl_add_u64 v[230:231], s[60:61], 0, v[130:131]
	v_lshl_add_u64 v[232:233], s[60:61], 0, v[134:135]
	s_add_u32 s60, s60, s14
	ds_read_b128 v[198:201], v150 offset:16384
	ds_read_b128 v[202:205], v150 offset:17408
	ds_read_b128 v[206:209], v150 offset:18432
	ds_read_b128 v[210:213], v150 offset:19456
	ds_read_b128 v[214:217], v150 offset:20480
	ds_read_b128 v[218:221], v150 offset:21504
	ds_read_b128 v[222:225], v150 offset:22528
	ds_read_b128 v[226:229], v150 offset:23552
	global_load_lds_dwordx4 v[230:231], off
	s_mov_b32 m0, s21
	s_addc_u32 s61, s61, s15
	global_load_lds_dwordx4 v[232:233], off
	v_lshl_add_u64 v[234:235], s[60:61], 0, v[130:131]
	s_mov_b32 m0, s28
	v_lshl_add_u64 v[236:237], s[60:61], 0, v[134:135]
	global_load_lds_dwordx4 v[234:235], off
	s_mov_b32 m0, s29
	v_lshl_add_u64 v[238:239], s[54:55], 0, v[128:129]
	global_load_lds_dwordx4 v[236:237], off
	s_mov_b32 m0, s3
	v_lshl_add_u64 v[240:241], s[54:55], 0, v[132:133]
	global_load_lds_dwordx4 v[238:239], off
	s_mov_b32 m0, s30
	s_nop 0
	global_load_lds_dwordx4 v[240:241], off
	s_waitcnt vmcnt(8)
	s_waitcnt lgkmcnt(0)
	s_barrier
	s_setprio 1
	s_waitcnt lgkmcnt(0)
	v_mfma_f32_16x16x32_bf16 v[60:63], v[144:147], v[198:201], v[60:63]
	v_mfma_f32_16x16x32_bf16 v[56:59], v[174:177], v[198:201], v[56:59]
	v_mfma_f32_16x16x32_bf16 v[44:47], v[144:147], v[206:209], v[44:47]
	v_mfma_f32_16x16x32_bf16 v[40:43], v[174:177], v[206:209], v[40:43]
	v_mfma_f32_16x16x32_bf16 v[28:31], v[144:147], v[214:217], v[28:31]
	v_mfma_f32_16x16x32_bf16 v[24:27], v[174:177], v[214:217], v[24:27]
	v_mfma_f32_16x16x32_bf16 v[12:15], v[144:147], v[222:225], v[12:15]
	v_mfma_f32_16x16x32_bf16 v[8:11], v[174:177], v[222:225], v[8:11]
	v_mfma_f32_16x16x32_bf16 v[60:63], v[170:173], v[202:205], v[60:63]
	v_mfma_f32_16x16x32_bf16 v[56:59], v[178:181], v[202:205], v[56:59]
	v_mfma_f32_16x16x32_bf16 v[44:47], v[170:173], v[210:213], v[44:47]
	v_mfma_f32_16x16x32_bf16 v[40:43], v[178:181], v[210:213], v[40:43]
	v_mfma_f32_16x16x32_bf16 v[28:31], v[170:173], v[218:221], v[28:31]
	v_mfma_f32_16x16x32_bf16 v[24:27], v[178:181], v[218:221], v[24:27]
	v_mfma_f32_16x16x32_bf16 v[12:15], v[170:173], v[226:229], v[12:15]
	v_mfma_f32_16x16x32_bf16 v[8:11], v[178:181], v[226:229], v[8:11]
	s_setprio 0
	s_setprio 1
	v_mfma_f32_16x16x32_bf16 v[52:55], v[182:185], v[198:201], v[52:55]
	v_mfma_f32_16x16x32_bf16 v[48:51], v[190:193], v[198:201], v[48:51]
	v_mfma_f32_16x16x32_bf16 v[36:39], v[182:185], v[206:209], v[36:39]
	v_mfma_f32_16x16x32_bf16 v[32:35], v[190:193], v[206:209], v[32:35]
	v_mfma_f32_16x16x32_bf16 v[20:23], v[182:185], v[214:217], v[20:23]
	v_mfma_f32_16x16x32_bf16 v[16:19], v[190:193], v[214:217], v[16:19]
	v_mfma_f32_16x16x32_bf16 v[4:7], v[182:185], v[222:225], v[4:7]
	v_mfma_f32_16x16x32_bf16 v[0:3], v[190:193], v[222:225], v[0:3]
	v_mfma_f32_16x16x32_bf16 v[52:55], v[186:189], v[202:205], v[52:55]
	v_mfma_f32_16x16x32_bf16 v[48:51], v[194:197], v[202:205], v[48:51]
	v_mfma_f32_16x16x32_bf16 v[36:39], v[186:189], v[210:213], v[36:39]
	v_mfma_f32_16x16x32_bf16 v[32:35], v[194:197], v[210:213], v[32:35]
	v_mfma_f32_16x16x32_bf16 v[20:23], v[186:189], v[218:221], v[20:23]
	v_mfma_f32_16x16x32_bf16 v[16:19], v[194:197], v[218:221], v[16:19]
	v_mfma_f32_16x16x32_bf16 v[4:7], v[186:189], v[226:229], v[4:7]
	v_mfma_f32_16x16x32_bf16 v[0:3], v[194:197], v[226:229], v[0:3]
	s_setprio 0
	s_barrier
	ds_read_b128 v[144:147], v159
	ds_read_b128 v[170:173], v160
	ds_read_b128 v[174:177], v161
	ds_read_b128 v[178:181], v164
	ds_read_b128 v[182:185], v165
	ds_read_b128 v[186:189], v166
	ds_read_b128 v[190:193], v167
	ds_read_b128 v[194:197], v168
	s_add_u32 s54, s54, s12
	s_addc_u32 s55, s55, s13
	s_mov_b32 m0, s31
	v_lshl_add_u64 v[242:243], s[54:55], 0, v[128:129]
	ds_read_b128 v[198:201], v150 offset:32768
	ds_read_b128 v[202:205], v150 offset:33792
	ds_read_b128 v[206:209], v150 offset:34816
	ds_read_b128 v[210:213], v150 offset:35840
	ds_read_b128 v[214:217], v150 offset:36864
	ds_read_b128 v[218:221], v150 offset:37888
	ds_read_b128 v[222:225], v150 offset:38912
	ds_read_b128 v[226:229], v150 offset:39936
	global_load_lds_dwordx4 v[242:243], off
	v_lshl_add_u64 v[242:243], s[54:55], 0, v[132:133]
	s_mov_b32 m0, s33
	s_nop 0
	global_load_lds_dwordx4 v[242:243], off
	s_waitcnt vmcnt(8)
	s_waitcnt lgkmcnt(0)
	s_barrier
	s_setprio 1
	s_waitcnt lgkmcnt(0)
	v_mfma_f32_16x16x32_bf16 v[124:127], v[144:147], v[198:201], v[124:127]
	v_mfma_f32_16x16x32_bf16 v[120:123], v[174:177], v[198:201], v[120:123]
	v_mfma_f32_16x16x32_bf16 v[108:111], v[144:147], v[206:209], v[108:111]
	v_mfma_f32_16x16x32_bf16 v[104:107], v[174:177], v[206:209], v[104:107]
	v_mfma_f32_16x16x32_bf16 v[92:95], v[144:147], v[214:217], v[92:95]
	v_mfma_f32_16x16x32_bf16 v[88:91], v[174:177], v[214:217], v[88:91]
	v_mfma_f32_16x16x32_bf16 v[76:79], v[144:147], v[222:225], v[76:79]
	v_mfma_f32_16x16x32_bf16 v[72:75], v[174:177], v[222:225], v[72:75]
	v_mfma_f32_16x16x32_bf16 v[124:127], v[170:173], v[202:205], v[124:127]
	v_mfma_f32_16x16x32_bf16 v[120:123], v[178:181], v[202:205], v[120:123]
	v_mfma_f32_16x16x32_bf16 v[108:111], v[170:173], v[210:213], v[108:111]
	v_mfma_f32_16x16x32_bf16 v[104:107], v[178:181], v[210:213], v[104:107]
	v_mfma_f32_16x16x32_bf16 v[92:95], v[170:173], v[218:221], v[92:95]
	v_mfma_f32_16x16x32_bf16 v[88:91], v[178:181], v[218:221], v[88:91]
	v_mfma_f32_16x16x32_bf16 v[76:79], v[170:173], v[226:229], v[76:79]
	v_mfma_f32_16x16x32_bf16 v[72:75], v[178:181], v[226:229], v[72:75]
	s_setprio 0
	s_setprio 1
	v_mfma_f32_16x16x32_bf16 v[116:119], v[182:185], v[198:201], v[116:119]
	v_mfma_f32_16x16x32_bf16 v[112:115], v[190:193], v[198:201], v[112:115]
	v_mfma_f32_16x16x32_bf16 v[100:103], v[182:185], v[206:209], v[100:103]
	v_mfma_f32_16x16x32_bf16 v[96:99], v[190:193], v[206:209], v[96:99]
	v_mfma_f32_16x16x32_bf16 v[84:87], v[182:185], v[214:217], v[84:87]
	v_mfma_f32_16x16x32_bf16 v[80:83], v[190:193], v[214:217], v[80:83]
	v_mfma_f32_16x16x32_bf16 v[68:71], v[182:185], v[222:225], v[68:71]
	v_mfma_f32_16x16x32_bf16 v[64:67], v[190:193], v[222:225], v[64:67]
	v_mfma_f32_16x16x32_bf16 v[116:119], v[186:189], v[202:205], v[116:119]
	v_mfma_f32_16x16x32_bf16 v[112:115], v[194:197], v[202:205], v[112:115]
	v_mfma_f32_16x16x32_bf16 v[100:103], v[186:189], v[210:213], v[100:103]
	v_mfma_f32_16x16x32_bf16 v[96:99], v[194:197], v[210:213], v[96:99]
	v_mfma_f32_16x16x32_bf16 v[84:87], v[186:189], v[218:221], v[84:87]
	v_mfma_f32_16x16x32_bf16 v[80:83], v[194:197], v[218:221], v[80:83]
	v_mfma_f32_16x16x32_bf16 v[68:71], v[186:189], v[226:229], v[68:71]
	v_mfma_f32_16x16x32_bf16 v[64:67], v[194:197], v[226:229], v[64:67]
	s_setprio 0
	s_barrier
	s_mov_b32 m0, s34
	v_lshl_add_u64 v[230:231], v[230:231], 0, s[26:27]
	ds_read_b128 v[198:201], v150 offset:49152
	ds_read_b128 v[202:205], v150 offset:50176
	ds_read_b128 v[206:209], v150 offset:51200
	ds_read_b128 v[210:213], v150 offset:52224
	ds_read_b128 v[214:217], v150 offset:53248
	ds_read_b128 v[218:221], v150 offset:54272
	ds_read_b128 v[222:225], v150 offset:55296
	ds_read_b128 v[226:229], v150 offset:56320
	global_load_lds_dwordx4 v[230:231], off
	v_lshl_add_u64 v[230:231], v[232:233], 0, s[26:27]
	s_mov_b32 m0, s35
	s_nop 0
	global_load_lds_dwordx4 v[230:231], off
	v_lshl_add_u64 v[230:231], v[234:235], 0, s[26:27]
	s_mov_b32 m0, s88
	s_nop 0
	global_load_lds_dwordx4 v[230:231], off
	v_lshl_add_u64 v[230:231], v[236:237], 0, s[26:27]
	s_mov_b32 m0, s89
	s_nop 0
	global_load_lds_dwordx4 v[230:231], off
	v_lshl_add_u64 v[230:231], v[238:239], 0, s[26:27]
	s_mov_b32 m0, s84
	s_nop 0
	global_load_lds_dwordx4 v[230:231], off
	v_lshl_add_u64 v[230:231], v[240:241], 0, s[26:27]
	s_mov_b32 m0, s85
	s_nop 0
	global_load_lds_dwordx4 v[230:231], off
	s_waitcnt vmcnt(8)
	s_waitcnt lgkmcnt(0)
	s_barrier
	s_setprio 1
	s_waitcnt lgkmcnt(0)
	v_mfma_f32_16x16x32_bf16 v[60:63], v[144:147], v[198:201], v[60:63]
	v_mfma_f32_16x16x32_bf16 v[56:59], v[174:177], v[198:201], v[56:59]
	v_mfma_f32_16x16x32_bf16 v[44:47], v[144:147], v[206:209], v[44:47]
	v_mfma_f32_16x16x32_bf16 v[40:43], v[174:177], v[206:209], v[40:43]
	v_mfma_f32_16x16x32_bf16 v[28:31], v[144:147], v[214:217], v[28:31]
	v_mfma_f32_16x16x32_bf16 v[24:27], v[174:177], v[214:217], v[24:27]
	v_mfma_f32_16x16x32_bf16 v[12:15], v[144:147], v[222:225], v[12:15]
	v_mfma_f32_16x16x32_bf16 v[8:11], v[174:177], v[222:225], v[8:11]
	v_mfma_f32_16x16x32_bf16 v[60:63], v[170:173], v[202:205], v[60:63]
	v_mfma_f32_16x16x32_bf16 v[56:59], v[178:181], v[202:205], v[56:59]
	v_mfma_f32_16x16x32_bf16 v[44:47], v[170:173], v[210:213], v[44:47]
	v_mfma_f32_16x16x32_bf16 v[40:43], v[178:181], v[210:213], v[40:43]
	v_mfma_f32_16x16x32_bf16 v[28:31], v[170:173], v[218:221], v[28:31]
	v_mfma_f32_16x16x32_bf16 v[24:27], v[178:181], v[218:221], v[24:27]
	v_mfma_f32_16x16x32_bf16 v[12:15], v[170:173], v[226:229], v[12:15]
	v_mfma_f32_16x16x32_bf16 v[8:11], v[178:181], v[226:229], v[8:11]
	s_setprio 0
	s_setprio 1
	v_mfma_f32_16x16x32_bf16 v[52:55], v[182:185], v[198:201], v[52:55]
	v_mfma_f32_16x16x32_bf16 v[48:51], v[190:193], v[198:201], v[48:51]
	v_mfma_f32_16x16x32_bf16 v[36:39], v[182:185], v[206:209], v[36:39]
	v_mfma_f32_16x16x32_bf16 v[32:35], v[190:193], v[206:209], v[32:35]
	v_mfma_f32_16x16x32_bf16 v[20:23], v[182:185], v[214:217], v[20:23]
	v_mfma_f32_16x16x32_bf16 v[16:19], v[190:193], v[214:217], v[16:19]
	v_mfma_f32_16x16x32_bf16 v[4:7], v[182:185], v[222:225], v[4:7]
	v_mfma_f32_16x16x32_bf16 v[0:3], v[190:193], v[222:225], v[0:3]
	v_mfma_f32_16x16x32_bf16 v[52:55], v[186:189], v[202:205], v[52:55]
	v_mfma_f32_16x16x32_bf16 v[48:51], v[194:197], v[202:205], v[48:51]
	v_mfma_f32_16x16x32_bf16 v[36:39], v[186:189], v[210:213], v[36:39]
	v_mfma_f32_16x16x32_bf16 v[32:35], v[194:197], v[210:213], v[32:35]
	v_mfma_f32_16x16x32_bf16 v[20:23], v[186:189], v[218:221], v[20:23]
	v_mfma_f32_16x16x32_bf16 v[16:19], v[194:197], v[218:221], v[16:19]
	v_mfma_f32_16x16x32_bf16 v[4:7], v[186:189], v[226:229], v[4:7]
	v_mfma_f32_16x16x32_bf16 v[0:3], v[194:197], v[226:229], v[0:3]
	s_setprio 0
	s_barrier
	s_add_u32 s52, s52, 0x100
	s_addc_u32 s53, s53, 0
	s_add_u32 s51, s51, 0x100
	s_addc_u32 s79, s79, 0
	s_cmp_ge_i32 s80, s90
	s_mov_b32 s54, s80
	s_cbranch_scc0 .LBB0_1596

.LBB0_1749:
	ds_read_b128 v[166:169], v147
	ds_read_b128 v[170:173], v148
	ds_read_b128 v[174:177], v149
	ds_read_b128 v[178:181], v150
	ds_read_b128 v[182:185], v151
	ds_read_b128 v[186:189], v152
	ds_read_b128 v[190:193], v153
	ds_read_b128 v[194:197], v154
	s_add_i32 s80, s48, 2
	s_add_u32 s62, s46, 0x80
	s_addc_u32 s49, s47, 0
	s_cmp_eq_u32 s96, s48
	s_cselect_b32 s48, s0, s62
	s_cselect_b32 s49, s1, s49
	s_cselect_b32 s63, s37, s79
	s_cselect_b32 s62, s36, s43
	s_mov_b32 m0, s90
	v_lshl_add_u64 v[230:231], s[46:47], 0, v[136:137]
	ds_read_b128 v[198:201], v146
	ds_read_b128 v[202:205], v146 offset:1024
	ds_read_b128 v[206:209], v146 offset:2048
	ds_read_b128 v[210:213], v146 offset:3072
	ds_read_b128 v[214:217], v146 offset:4096
	ds_read_b128 v[218:221], v146 offset:5120
	ds_read_b128 v[222:225], v146 offset:6144
	ds_read_b128 v[226:229], v146 offset:7168
	global_load_lds_dwordx4 v[230:231], off
	v_lshl_add_u64 v[230:231], s[46:47], 0, v[138:139]
	s_mov_b32 m0, s68
	s_nop 0
	global_load_lds_dwordx4 v[230:231], off
	s_waitcnt vmcnt(8)
	s_waitcnt lgkmcnt(0)
	s_barrier
	s_setprio 1
	s_waitcnt lgkmcnt(0)
	v_mfma_f32_16x16x32_bf16 v[124:127], v[166:169], v[198:201], v[124:127]
	v_mfma_f32_16x16x32_bf16 v[116:119], v[174:177], v[198:201], v[116:119]
	v_mfma_f32_16x16x32_bf16 v[108:111], v[166:169], v[206:209], v[108:111]
	v_mfma_f32_16x16x32_bf16 v[100:103], v[174:177], v[206:209], v[100:103]
	v_mfma_f32_16x16x32_bf16 v[92:95], v[166:169], v[214:217], v[92:95]
	v_mfma_f32_16x16x32_bf16 v[84:87], v[174:177], v[214:217], v[84:87]
	v_mfma_f32_16x16x32_bf16 v[76:79], v[166:169], v[222:225], v[76:79]
	v_mfma_f32_16x16x32_bf16 v[68:71], v[174:177], v[222:225], v[68:71]
	v_mfma_f32_16x16x32_bf16 v[124:127], v[170:173], v[202:205], v[124:127]
	v_mfma_f32_16x16x32_bf16 v[116:119], v[178:181], v[202:205], v[116:119]
	v_mfma_f32_16x16x32_bf16 v[108:111], v[170:173], v[210:213], v[108:111]
	v_mfma_f32_16x16x32_bf16 v[100:103], v[178:181], v[210:213], v[100:103]
	v_mfma_f32_16x16x32_bf16 v[92:95], v[170:173], v[218:221], v[92:95]
	v_mfma_f32_16x16x32_bf16 v[84:87], v[178:181], v[218:221], v[84:87]
	v_mfma_f32_16x16x32_bf16 v[76:79], v[170:173], v[226:229], v[76:79]
	v_mfma_f32_16x16x32_bf16 v[68:71], v[178:181], v[226:229], v[68:71]
	s_setprio 0
	s_setprio 1
	v_mfma_f32_16x16x32_bf16 v[120:123], v[182:185], v[198:201], v[120:123]
	v_mfma_f32_16x16x32_bf16 v[112:115], v[190:193], v[198:201], v[112:115]
	v_mfma_f32_16x16x32_bf16 v[104:107], v[182:185], v[206:209], v[104:107]
	v_mfma_f32_16x16x32_bf16 v[96:99], v[190:193], v[206:209], v[96:99]
	v_mfma_f32_16x16x32_bf16 v[88:91], v[182:185], v[214:217], v[88:91]
	v_mfma_f32_16x16x32_bf16 v[80:83], v[190:193], v[214:217], v[80:83]
	v_mfma_f32_16x16x32_bf16 v[72:75], v[182:185], v[222:225], v[72:75]
	v_mfma_f32_16x16x32_bf16 v[64:67], v[190:193], v[222:225], v[64:67]
	v_mfma_f32_16x16x32_bf16 v[120:123], v[186:189], v[202:205], v[120:123]
	v_mfma_f32_16x16x32_bf16 v[112:115], v[194:197], v[202:205], v[112:115]
	v_mfma_f32_16x16x32_bf16 v[104:107], v[186:189], v[210:213], v[104:107]
	v_mfma_f32_16x16x32_bf16 v[96:99], v[194:197], v[210:213], v[96:99]
	v_mfma_f32_16x16x32_bf16 v[88:91], v[186:189], v[218:221], v[88:91]
	v_mfma_f32_16x16x32_bf16 v[80:83], v[194:197], v[218:221], v[80:83]
	v_mfma_f32_16x16x32_bf16 v[72:75], v[186:189], v[226:229], v[72:75]
	v_mfma_f32_16x16x32_bf16 v[64:67], v[194:197], v[226:229], v[64:67]
	s_setprio 0
	s_barrier
	s_mov_b32 m0, s28
	v_lshl_add_u64 v[230:231], s[62:63], 0, v[132:133]
	v_lshl_add_u64 v[232:233], s[62:63], 0, v[128:129]
	s_add_u32 s62, s62, s10
	ds_read_b128 v[198:201], v146 offset:16384
	ds_read_b128 v[202:205], v146 offset:17408
	ds_read_b128 v[206:209], v146 offset:18432
	ds_read_b128 v[210:213], v146 offset:19456
	ds_read_b128 v[214:217], v146 offset:20480
	ds_read_b128 v[218:221], v146 offset:21504
	ds_read_b128 v[222:225], v146 offset:22528
	ds_read_b128 v[226:229], v146 offset:23552
	global_load_lds_dwordx4 v[230:231], off
	s_mov_b32 m0, s29
	s_addc_u32 s63, s63, s11
	global_load_lds_dwordx4 v[232:233], off
	v_lshl_add_u64 v[234:235], s[62:63], 0, v[132:133]
	s_mov_b32 m0, s30
	v_lshl_add_u64 v[236:237], s[62:63], 0, v[128:129]
	global_load_lds_dwordx4 v[234:235], off
	s_mov_b32 m0, s31
	v_lshl_add_u64 v[238:239], s[48:49], 0, v[134:135]
	global_load_lds_dwordx4 v[236:237], off
	s_mov_b32 m0, s3
	v_lshl_add_u64 v[240:241], s[48:49], 0, v[130:131]
	global_load_lds_dwordx4 v[238:239], off
	s_mov_b32 m0, s33
	s_nop 0
	global_load_lds_dwordx4 v[240:241], off
	s_waitcnt vmcnt(8)
	s_waitcnt lgkmcnt(0)
	s_barrier
	s_setprio 1
	s_waitcnt lgkmcnt(0)
	v_mfma_f32_16x16x32_bf16 v[60:63], v[166:169], v[198:201], v[60:63]
	v_mfma_f32_16x16x32_bf16 v[52:55], v[174:177], v[198:201], v[52:55]
	v_mfma_f32_16x16x32_bf16 v[44:47], v[166:169], v[206:209], v[44:47]
	v_mfma_f32_16x16x32_bf16 v[36:39], v[174:177], v[206:209], v[36:39]
	v_mfma_f32_16x16x32_bf16 v[28:31], v[166:169], v[214:217], v[28:31]
	v_mfma_f32_16x16x32_bf16 v[20:23], v[174:177], v[214:217], v[20:23]
	v_mfma_f32_16x16x32_bf16 v[12:15], v[166:169], v[222:225], v[12:15]
	v_mfma_f32_16x16x32_bf16 v[4:7], v[174:177], v[222:225], v[4:7]
	v_mfma_f32_16x16x32_bf16 v[60:63], v[170:173], v[202:205], v[60:63]
	v_mfma_f32_16x16x32_bf16 v[52:55], v[178:181], v[202:205], v[52:55]
	v_mfma_f32_16x16x32_bf16 v[44:47], v[170:173], v[210:213], v[44:47]
	v_mfma_f32_16x16x32_bf16 v[36:39], v[178:181], v[210:213], v[36:39]
	v_mfma_f32_16x16x32_bf16 v[28:31], v[170:173], v[218:221], v[28:31]
	v_mfma_f32_16x16x32_bf16 v[20:23], v[178:181], v[218:221], v[20:23]
	v_mfma_f32_16x16x32_bf16 v[12:15], v[170:173], v[226:229], v[12:15]
	v_mfma_f32_16x16x32_bf16 v[4:7], v[178:181], v[226:229], v[4:7]
	s_setprio 0
	s_setprio 1
	v_mfma_f32_16x16x32_bf16 v[56:59], v[182:185], v[198:201], v[56:59]
	v_mfma_f32_16x16x32_bf16 v[48:51], v[190:193], v[198:201], v[48:51]
	v_mfma_f32_16x16x32_bf16 v[40:43], v[182:185], v[206:209], v[40:43]
	v_mfma_f32_16x16x32_bf16 v[32:35], v[190:193], v[206:209], v[32:35]
	v_mfma_f32_16x16x32_bf16 v[24:27], v[182:185], v[214:217], v[24:27]
	v_mfma_f32_16x16x32_bf16 v[16:19], v[190:193], v[214:217], v[16:19]
	v_mfma_f32_16x16x32_bf16 v[8:11], v[182:185], v[222:225], v[8:11]
	v_mfma_f32_16x16x32_bf16 v[0:3], v[190:193], v[222:225], v[0:3]
	v_mfma_f32_16x16x32_bf16 v[56:59], v[186:189], v[202:205], v[56:59]
	v_mfma_f32_16x16x32_bf16 v[48:51], v[194:197], v[202:205], v[48:51]
	v_mfma_f32_16x16x32_bf16 v[40:43], v[186:189], v[210:213], v[40:43]
	v_mfma_f32_16x16x32_bf16 v[32:35], v[194:197], v[210:213], v[32:35]
	v_mfma_f32_16x16x32_bf16 v[24:27], v[186:189], v[218:221], v[24:27]
	v_mfma_f32_16x16x32_bf16 v[16:19], v[194:197], v[218:221], v[16:19]
	v_mfma_f32_16x16x32_bf16 v[8:11], v[186:189], v[226:229], v[8:11]
	v_mfma_f32_16x16x32_bf16 v[0:3], v[194:197], v[226:229], v[0:3]
	s_setprio 0
	s_barrier
	ds_read_b128 v[166:169], v155
	ds_read_b128 v[170:173], v156
	ds_read_b128 v[174:177], v157
	ds_read_b128 v[178:181], v158
	ds_read_b128 v[182:185], v159
	ds_read_b128 v[186:189], v160
	ds_read_b128 v[190:193], v161
	ds_read_b128 v[194:197], v164
	s_add_u32 s48, s48, s8
	s_addc_u32 s49, s49, s9
	s_mov_b32 m0, s34
	v_lshl_add_u64 v[242:243], s[48:49], 0, v[134:135]
	ds_read_b128 v[198:201], v146 offset:32768
	ds_read_b128 v[202:205], v146 offset:33792
	ds_read_b128 v[206:209], v146 offset:34816
	ds_read_b128 v[210:213], v146 offset:35840
	ds_read_b128 v[214:217], v146 offset:36864
	ds_read_b128 v[218:221], v146 offset:37888
	ds_read_b128 v[222:225], v146 offset:38912
	ds_read_b128 v[226:229], v146 offset:39936
	global_load_lds_dwordx4 v[242:243], off
	v_lshl_add_u64 v[242:243], s[48:49], 0, v[130:131]
	s_mov_b32 m0, s35
	s_nop 0
	global_load_lds_dwordx4 v[242:243], off
	s_waitcnt vmcnt(8)
	s_waitcnt lgkmcnt(0)
	s_barrier
	s_setprio 1
	s_waitcnt lgkmcnt(0)
	v_mfma_f32_16x16x32_bf16 v[124:127], v[166:169], v[198:201], v[124:127]
	v_mfma_f32_16x16x32_bf16 v[116:119], v[174:177], v[198:201], v[116:119]
	v_mfma_f32_16x16x32_bf16 v[108:111], v[166:169], v[206:209], v[108:111]
	v_mfma_f32_16x16x32_bf16 v[100:103], v[174:177], v[206:209], v[100:103]
	v_mfma_f32_16x16x32_bf16 v[92:95], v[166:169], v[214:217], v[92:95]
	v_mfma_f32_16x16x32_bf16 v[84:87], v[174:177], v[214:217], v[84:87]
	v_mfma_f32_16x16x32_bf16 v[76:79], v[166:169], v[222:225], v[76:79]
	v_mfma_f32_16x16x32_bf16 v[68:71], v[174:177], v[222:225], v[68:71]
	v_mfma_f32_16x16x32_bf16 v[124:127], v[170:173], v[202:205], v[124:127]
	v_mfma_f32_16x16x32_bf16 v[116:119], v[178:181], v[202:205], v[116:119]
	v_mfma_f32_16x16x32_bf16 v[108:111], v[170:173], v[210:213], v[108:111]
	v_mfma_f32_16x16x32_bf16 v[100:103], v[178:181], v[210:213], v[100:103]
	v_mfma_f32_16x16x32_bf16 v[92:95], v[170:173], v[218:221], v[92:95]
	v_mfma_f32_16x16x32_bf16 v[84:87], v[178:181], v[218:221], v[84:87]
	v_mfma_f32_16x16x32_bf16 v[76:79], v[170:173], v[226:229], v[76:79]
	v_mfma_f32_16x16x32_bf16 v[68:71], v[178:181], v[226:229], v[68:71]
	s_setprio 0
	s_setprio 1
	v_mfma_f32_16x16x32_bf16 v[120:123], v[182:185], v[198:201], v[120:123]
	v_mfma_f32_16x16x32_bf16 v[112:115], v[190:193], v[198:201], v[112:115]
	v_mfma_f32_16x16x32_bf16 v[104:107], v[182:185], v[206:209], v[104:107]
	v_mfma_f32_16x16x32_bf16 v[96:99], v[190:193], v[206:209], v[96:99]
	v_mfma_f32_16x16x32_bf16 v[88:91], v[182:185], v[214:217], v[88:91]
	v_mfma_f32_16x16x32_bf16 v[80:83], v[190:193], v[214:217], v[80:83]
	v_mfma_f32_16x16x32_bf16 v[72:75], v[182:185], v[222:225], v[72:75]
	v_mfma_f32_16x16x32_bf16 v[64:67], v[190:193], v[222:225], v[64:67]
	v_mfma_f32_16x16x32_bf16 v[120:123], v[186:189], v[202:205], v[120:123]
	v_mfma_f32_16x16x32_bf16 v[112:115], v[194:197], v[202:205], v[112:115]
	v_mfma_f32_16x16x32_bf16 v[104:107], v[186:189], v[210:213], v[104:107]
	v_mfma_f32_16x16x32_bf16 v[96:99], v[194:197], v[210:213], v[96:99]
	v_mfma_f32_16x16x32_bf16 v[88:91], v[186:189], v[218:221], v[88:91]
	v_mfma_f32_16x16x32_bf16 v[80:83], v[194:197], v[218:221], v[80:83]
	v_mfma_f32_16x16x32_bf16 v[72:75], v[186:189], v[226:229], v[72:75]
	v_mfma_f32_16x16x32_bf16 v[64:67], v[194:197], v[226:229], v[64:67]
	s_setprio 0
	s_barrier
	s_mov_b32 m0, s51
	v_lshl_add_u64 v[230:231], v[230:231], 0, s[24:25]
	ds_read_b128 v[198:201], v146 offset:49152
	ds_read_b128 v[202:205], v146 offset:50176
	ds_read_b128 v[206:209], v146 offset:51200
	ds_read_b128 v[210:213], v146 offset:52224
	ds_read_b128 v[214:217], v146 offset:53248
	ds_read_b128 v[218:221], v146 offset:54272
	ds_read_b128 v[222:225], v146 offset:55296
	ds_read_b128 v[226:229], v146 offset:56320
	global_load_lds_dwordx4 v[230:231], off
	v_lshl_add_u64 v[230:231], v[232:233], 0, s[24:25]
	s_mov_b32 m0, s81
	s_nop 0
	global_load_lds_dwordx4 v[230:231], off
	v_lshl_add_u64 v[230:231], v[234:235], 0, s[24:25]
	s_mov_b32 m0, s88
	s_nop 0
	global_load_lds_dwordx4 v[230:231], off
	v_lshl_add_u64 v[230:231], v[236:237], 0, s[24:25]
	s_mov_b32 m0, s89
	s_nop 0
	global_load_lds_dwordx4 v[230:231], off
	v_lshl_add_u64 v[230:231], v[238:239], 0, s[24:25]
	s_mov_b32 m0, s84
	s_nop 0
	global_load_lds_dwordx4 v[230:231], off
	v_lshl_add_u64 v[230:231], v[240:241], 0, s[24:25]
	s_mov_b32 m0, s85
	s_nop 0
	global_load_lds_dwordx4 v[230:231], off
	s_waitcnt vmcnt(8)
	s_waitcnt lgkmcnt(0)
	s_barrier
	s_setprio 1
	s_waitcnt lgkmcnt(0)
	v_mfma_f32_16x16x32_bf16 v[60:63], v[166:169], v[198:201], v[60:63]
	v_mfma_f32_16x16x32_bf16 v[52:55], v[174:177], v[198:201], v[52:55]
	v_mfma_f32_16x16x32_bf16 v[44:47], v[166:169], v[206:209], v[44:47]
	v_mfma_f32_16x16x32_bf16 v[36:39], v[174:177], v[206:209], v[36:39]
	v_mfma_f32_16x16x32_bf16 v[28:31], v[166:169], v[214:217], v[28:31]
	v_mfma_f32_16x16x32_bf16 v[20:23], v[174:177], v[214:217], v[20:23]
	v_mfma_f32_16x16x32_bf16 v[12:15], v[166:169], v[222:225], v[12:15]
	v_mfma_f32_16x16x32_bf16 v[4:7], v[174:177], v[222:225], v[4:7]
	v_mfma_f32_16x16x32_bf16 v[60:63], v[170:173], v[202:205], v[60:63]
	v_mfma_f32_16x16x32_bf16 v[52:55], v[178:181], v[202:205], v[52:55]
	v_mfma_f32_16x16x32_bf16 v[44:47], v[170:173], v[210:213], v[44:47]
	v_mfma_f32_16x16x32_bf16 v[36:39], v[178:181], v[210:213], v[36:39]
	v_mfma_f32_16x16x32_bf16 v[28:31], v[170:173], v[218:221], v[28:31]
	v_mfma_f32_16x16x32_bf16 v[20:23], v[178:181], v[218:221], v[20:23]
	v_mfma_f32_16x16x32_bf16 v[12:15], v[170:173], v[226:229], v[12:15]
	v_mfma_f32_16x16x32_bf16 v[4:7], v[178:181], v[226:229], v[4:7]
	s_setprio 0
	s_setprio 1
	v_mfma_f32_16x16x32_bf16 v[56:59], v[182:185], v[198:201], v[56:59]
	v_mfma_f32_16x16x32_bf16 v[48:51], v[190:193], v[198:201], v[48:51]
	v_mfma_f32_16x16x32_bf16 v[40:43], v[182:185], v[206:209], v[40:43]
	v_mfma_f32_16x16x32_bf16 v[32:35], v[190:193], v[206:209], v[32:35]
	v_mfma_f32_16x16x32_bf16 v[24:27], v[182:185], v[214:217], v[24:27]
	v_mfma_f32_16x16x32_bf16 v[16:19], v[190:193], v[214:217], v[16:19]
	v_mfma_f32_16x16x32_bf16 v[8:11], v[182:185], v[222:225], v[8:11]
	v_mfma_f32_16x16x32_bf16 v[0:3], v[190:193], v[222:225], v[0:3]
	v_mfma_f32_16x16x32_bf16 v[56:59], v[186:189], v[202:205], v[56:59]
	v_mfma_f32_16x16x32_bf16 v[48:51], v[194:197], v[202:205], v[48:51]
	v_mfma_f32_16x16x32_bf16 v[40:43], v[186:189], v[210:213], v[40:43]
	v_mfma_f32_16x16x32_bf16 v[32:35], v[194:197], v[210:213], v[32:35]
	v_mfma_f32_16x16x32_bf16 v[24:27], v[186:189], v[218:221], v[24:27]
	v_mfma_f32_16x16x32_bf16 v[16:19], v[194:197], v[218:221], v[16:19]
	v_mfma_f32_16x16x32_bf16 v[8:11], v[186:189], v[226:229], v[8:11]
	v_mfma_f32_16x16x32_bf16 v[0:3], v[194:197], v[226:229], v[0:3]
	s_setprio 0
	s_barrier
	s_add_u32 s46, s46, 0x100
	s_addc_u32 s47, s47, 0
	s_add_u32 s43, s43, 0x100
	s_addc_u32 s79, s79, 0
	s_cmp_ge_i32 s80, s91
	s_mov_b32 s48, s80
	s_cbranch_scc0 .LBB0_1749

.LBB0_1832:
	ds_read_b128 v[144:147], v151
	ds_read_b128 v[170:173], v152
	ds_read_b128 v[174:177], v153
	ds_read_b128 v[178:181], v154
	ds_read_b128 v[182:185], v155
	ds_read_b128 v[186:189], v156
	ds_read_b128 v[190:193], v157
	ds_read_b128 v[194:197], v158
	s_add_i32 s78, s54, 2
	s_add_u32 s64, s52, 0x80
	s_addc_u32 s55, s53, 0
	s_cmp_eq_u32 s92, s54
	s_cselect_b32 s54, s0, s64
	s_cselect_b32 s55, s1, s55
	s_cselect_b32 s65, s49, s77
	s_cselect_b32 s64, s48, s51
	s_mov_b32 m0, s71
	v_lshl_add_u64 v[230:231], s[52:53], 0, v[136:137]
	ds_read_b128 v[198:201], v150
	ds_read_b128 v[202:205], v150 offset:1024
	ds_read_b128 v[206:209], v150 offset:2048
	ds_read_b128 v[210:213], v150 offset:3072
	ds_read_b128 v[214:217], v150 offset:4096
	ds_read_b128 v[218:221], v150 offset:5120
	ds_read_b128 v[222:225], v150 offset:6144
	ds_read_b128 v[226:229], v150 offset:7168
	global_load_lds_dwordx4 v[230:231], off
	v_lshl_add_u64 v[230:231], s[52:53], 0, v[138:139]
	s_mov_b32 m0, s72
	s_nop 0
	global_load_lds_dwordx4 v[230:231], off
	s_waitcnt vmcnt(8)
	s_waitcnt lgkmcnt(0)
	s_barrier
	s_setprio 1
	s_waitcnt lgkmcnt(0)
	v_mfma_f32_16x16x32_bf16 v[124:127], v[144:147], v[198:201], v[124:127]
	v_mfma_f32_16x16x32_bf16 v[120:123], v[174:177], v[198:201], v[120:123]
	v_mfma_f32_16x16x32_bf16 v[108:111], v[144:147], v[206:209], v[108:111]
	v_mfma_f32_16x16x32_bf16 v[104:107], v[174:177], v[206:209], v[104:107]
	v_mfma_f32_16x16x32_bf16 v[92:95], v[144:147], v[214:217], v[92:95]
	v_mfma_f32_16x16x32_bf16 v[88:91], v[174:177], v[214:217], v[88:91]
	v_mfma_f32_16x16x32_bf16 v[76:79], v[144:147], v[222:225], v[76:79]
	v_mfma_f32_16x16x32_bf16 v[72:75], v[174:177], v[222:225], v[72:75]
	v_mfma_f32_16x16x32_bf16 v[124:127], v[170:173], v[202:205], v[124:127]
	v_mfma_f32_16x16x32_bf16 v[120:123], v[178:181], v[202:205], v[120:123]
	v_mfma_f32_16x16x32_bf16 v[108:111], v[170:173], v[210:213], v[108:111]
	v_mfma_f32_16x16x32_bf16 v[104:107], v[178:181], v[210:213], v[104:107]
	v_mfma_f32_16x16x32_bf16 v[92:95], v[170:173], v[218:221], v[92:95]
	v_mfma_f32_16x16x32_bf16 v[88:91], v[178:181], v[218:221], v[88:91]
	v_mfma_f32_16x16x32_bf16 v[76:79], v[170:173], v[226:229], v[76:79]
	v_mfma_f32_16x16x32_bf16 v[72:75], v[178:181], v[226:229], v[72:75]
	s_setprio 0
	s_setprio 1
	v_mfma_f32_16x16x32_bf16 v[116:119], v[182:185], v[198:201], v[116:119]
	v_mfma_f32_16x16x32_bf16 v[112:115], v[190:193], v[198:201], v[112:115]
	v_mfma_f32_16x16x32_bf16 v[100:103], v[182:185], v[206:209], v[100:103]
	v_mfma_f32_16x16x32_bf16 v[96:99], v[190:193], v[206:209], v[96:99]
	v_mfma_f32_16x16x32_bf16 v[84:87], v[182:185], v[214:217], v[84:87]
	v_mfma_f32_16x16x32_bf16 v[80:83], v[190:193], v[214:217], v[80:83]
	v_mfma_f32_16x16x32_bf16 v[68:71], v[182:185], v[222:225], v[68:71]
	v_mfma_f32_16x16x32_bf16 v[64:67], v[190:193], v[222:225], v[64:67]
	v_mfma_f32_16x16x32_bf16 v[116:119], v[186:189], v[202:205], v[116:119]
	v_mfma_f32_16x16x32_bf16 v[112:115], v[194:197], v[202:205], v[112:115]
	v_mfma_f32_16x16x32_bf16 v[100:103], v[186:189], v[210:213], v[100:103]
	v_mfma_f32_16x16x32_bf16 v[96:99], v[194:197], v[210:213], v[96:99]
	v_mfma_f32_16x16x32_bf16 v[84:87], v[186:189], v[218:221], v[84:87]
	v_mfma_f32_16x16x32_bf16 v[80:83], v[194:197], v[218:221], v[80:83]
	v_mfma_f32_16x16x32_bf16 v[68:71], v[186:189], v[226:229], v[68:71]
	v_mfma_f32_16x16x32_bf16 v[64:67], v[194:197], v[226:229], v[64:67]
	s_setprio 0
	s_barrier
	s_mov_b32 m0, s28
	v_lshl_add_u64 v[230:231], s[64:65], 0, v[130:131]
	v_lshl_add_u64 v[232:233], s[64:65], 0, v[134:135]
	s_add_u32 s64, s64, s12
	ds_read_b128 v[198:201], v150 offset:16384
	ds_read_b128 v[202:205], v150 offset:17408
	ds_read_b128 v[206:209], v150 offset:18432
	ds_read_b128 v[210:213], v150 offset:19456
	ds_read_b128 v[214:217], v150 offset:20480
	ds_read_b128 v[218:221], v150 offset:21504
	ds_read_b128 v[222:225], v150 offset:22528
	ds_read_b128 v[226:229], v150 offset:23552
	global_load_lds_dwordx4 v[230:231], off
	s_mov_b32 m0, s29
	s_addc_u32 s65, s65, s13
	global_load_lds_dwordx4 v[232:233], off
	v_lshl_add_u64 v[234:235], s[64:65], 0, v[130:131]
	s_mov_b32 m0, s30
	v_lshl_add_u64 v[236:237], s[64:65], 0, v[134:135]
	global_load_lds_dwordx4 v[234:235], off
	s_mov_b32 m0, s31
	v_lshl_add_u64 v[238:239], s[54:55], 0, v[128:129]
	global_load_lds_dwordx4 v[236:237], off
	s_mov_b32 m0, s3
	v_lshl_add_u64 v[240:241], s[54:55], 0, v[132:133]
	global_load_lds_dwordx4 v[238:239], off
	s_mov_b32 m0, s33
	s_nop 0
	global_load_lds_dwordx4 v[240:241], off
	s_waitcnt vmcnt(8)
	s_waitcnt lgkmcnt(0)
	s_barrier
	s_setprio 1
	s_waitcnt lgkmcnt(0)
	v_mfma_f32_16x16x32_bf16 v[60:63], v[144:147], v[198:201], v[60:63]
	v_mfma_f32_16x16x32_bf16 v[56:59], v[174:177], v[198:201], v[56:59]
	v_mfma_f32_16x16x32_bf16 v[44:47], v[144:147], v[206:209], v[44:47]
	v_mfma_f32_16x16x32_bf16 v[40:43], v[174:177], v[206:209], v[40:43]
	v_mfma_f32_16x16x32_bf16 v[28:31], v[144:147], v[214:217], v[28:31]
	v_mfma_f32_16x16x32_bf16 v[24:27], v[174:177], v[214:217], v[24:27]
	v_mfma_f32_16x16x32_bf16 v[12:15], v[144:147], v[222:225], v[12:15]
	v_mfma_f32_16x16x32_bf16 v[8:11], v[174:177], v[222:225], v[8:11]
	v_mfma_f32_16x16x32_bf16 v[60:63], v[170:173], v[202:205], v[60:63]
	v_mfma_f32_16x16x32_bf16 v[56:59], v[178:181], v[202:205], v[56:59]
	v_mfma_f32_16x16x32_bf16 v[44:47], v[170:173], v[210:213], v[44:47]
	v_mfma_f32_16x16x32_bf16 v[40:43], v[178:181], v[210:213], v[40:43]
	v_mfma_f32_16x16x32_bf16 v[28:31], v[170:173], v[218:221], v[28:31]
	v_mfma_f32_16x16x32_bf16 v[24:27], v[178:181], v[218:221], v[24:27]
	v_mfma_f32_16x16x32_bf16 v[12:15], v[170:173], v[226:229], v[12:15]
	v_mfma_f32_16x16x32_bf16 v[8:11], v[178:181], v[226:229], v[8:11]
	s_setprio 0
	s_setprio 1
	v_mfma_f32_16x16x32_bf16 v[52:55], v[182:185], v[198:201], v[52:55]
	v_mfma_f32_16x16x32_bf16 v[48:51], v[190:193], v[198:201], v[48:51]
	v_mfma_f32_16x16x32_bf16 v[36:39], v[182:185], v[206:209], v[36:39]
	v_mfma_f32_16x16x32_bf16 v[32:35], v[190:193], v[206:209], v[32:35]
	v_mfma_f32_16x16x32_bf16 v[20:23], v[182:185], v[214:217], v[20:23]
	v_mfma_f32_16x16x32_bf16 v[16:19], v[190:193], v[214:217], v[16:19]
	v_mfma_f32_16x16x32_bf16 v[4:7], v[182:185], v[222:225], v[4:7]
	v_mfma_f32_16x16x32_bf16 v[0:3], v[190:193], v[222:225], v[0:3]
	v_mfma_f32_16x16x32_bf16 v[52:55], v[186:189], v[202:205], v[52:55]
	v_mfma_f32_16x16x32_bf16 v[48:51], v[194:197], v[202:205], v[48:51]
	v_mfma_f32_16x16x32_bf16 v[36:39], v[186:189], v[210:213], v[36:39]
	v_mfma_f32_16x16x32_bf16 v[32:35], v[194:197], v[210:213], v[32:35]
	v_mfma_f32_16x16x32_bf16 v[20:23], v[186:189], v[218:221], v[20:23]
	v_mfma_f32_16x16x32_bf16 v[16:19], v[194:197], v[218:221], v[16:19]
	v_mfma_f32_16x16x32_bf16 v[4:7], v[186:189], v[226:229], v[4:7]
	v_mfma_f32_16x16x32_bf16 v[0:3], v[194:197], v[226:229], v[0:3]
	s_setprio 0
	s_barrier
	ds_read_b128 v[144:147], v159
	ds_read_b128 v[170:173], v160
	ds_read_b128 v[174:177], v161
	ds_read_b128 v[178:181], v164
	ds_read_b128 v[182:185], v165
	ds_read_b128 v[186:189], v166
	ds_read_b128 v[190:193], v167
	ds_read_b128 v[194:197], v168
	s_add_u32 s54, s54, s10
	s_addc_u32 s55, s55, s11
	s_mov_b32 m0, s34
	v_lshl_add_u64 v[242:243], s[54:55], 0, v[128:129]
	ds_read_b128 v[198:201], v150 offset:32768
	ds_read_b128 v[202:205], v150 offset:33792
	ds_read_b128 v[206:209], v150 offset:34816
	ds_read_b128 v[210:213], v150 offset:35840
	ds_read_b128 v[214:217], v150 offset:36864
	ds_read_b128 v[218:221], v150 offset:37888
	ds_read_b128 v[222:225], v150 offset:38912
	ds_read_b128 v[226:229], v150 offset:39936
	global_load_lds_dwordx4 v[242:243], off
	v_lshl_add_u64 v[242:243], s[54:55], 0, v[132:133]
	s_mov_b32 m0, s35
	s_nop 0
	global_load_lds_dwordx4 v[242:243], off
	s_waitcnt vmcnt(8)
	s_waitcnt lgkmcnt(0)
	s_barrier
	s_setprio 1
	s_waitcnt lgkmcnt(0)
	v_mfma_f32_16x16x32_bf16 v[124:127], v[144:147], v[198:201], v[124:127]
	v_mfma_f32_16x16x32_bf16 v[120:123], v[174:177], v[198:201], v[120:123]
	v_mfma_f32_16x16x32_bf16 v[108:111], v[144:147], v[206:209], v[108:111]
	v_mfma_f32_16x16x32_bf16 v[104:107], v[174:177], v[206:209], v[104:107]
	v_mfma_f32_16x16x32_bf16 v[92:95], v[144:147], v[214:217], v[92:95]
	v_mfma_f32_16x16x32_bf16 v[88:91], v[174:177], v[214:217], v[88:91]
	v_mfma_f32_16x16x32_bf16 v[76:79], v[144:147], v[222:225], v[76:79]
	v_mfma_f32_16x16x32_bf16 v[72:75], v[174:177], v[222:225], v[72:75]
	v_mfma_f32_16x16x32_bf16 v[124:127], v[170:173], v[202:205], v[124:127]
	v_mfma_f32_16x16x32_bf16 v[120:123], v[178:181], v[202:205], v[120:123]
	v_mfma_f32_16x16x32_bf16 v[108:111], v[170:173], v[210:213], v[108:111]
	v_mfma_f32_16x16x32_bf16 v[104:107], v[178:181], v[210:213], v[104:107]
	v_mfma_f32_16x16x32_bf16 v[92:95], v[170:173], v[218:221], v[92:95]
	v_mfma_f32_16x16x32_bf16 v[88:91], v[178:181], v[218:221], v[88:91]
	v_mfma_f32_16x16x32_bf16 v[76:79], v[170:173], v[226:229], v[76:79]
	v_mfma_f32_16x16x32_bf16 v[72:75], v[178:181], v[226:229], v[72:75]
	s_setprio 0
	s_setprio 1
	v_mfma_f32_16x16x32_bf16 v[116:119], v[182:185], v[198:201], v[116:119]
	v_mfma_f32_16x16x32_bf16 v[112:115], v[190:193], v[198:201], v[112:115]
	v_mfma_f32_16x16x32_bf16 v[100:103], v[182:185], v[206:209], v[100:103]
	v_mfma_f32_16x16x32_bf16 v[96:99], v[190:193], v[206:209], v[96:99]
	v_mfma_f32_16x16x32_bf16 v[84:87], v[182:185], v[214:217], v[84:87]
	v_mfma_f32_16x16x32_bf16 v[80:83], v[190:193], v[214:217], v[80:83]
	v_mfma_f32_16x16x32_bf16 v[68:71], v[182:185], v[222:225], v[68:71]
	v_mfma_f32_16x16x32_bf16 v[64:67], v[190:193], v[222:225], v[64:67]
	v_mfma_f32_16x16x32_bf16 v[116:119], v[186:189], v[202:205], v[116:119]
	v_mfma_f32_16x16x32_bf16 v[112:115], v[194:197], v[202:205], v[112:115]
	v_mfma_f32_16x16x32_bf16 v[100:103], v[186:189], v[210:213], v[100:103]
	v_mfma_f32_16x16x32_bf16 v[96:99], v[194:197], v[210:213], v[96:99]
	v_mfma_f32_16x16x32_bf16 v[84:87], v[186:189], v[218:221], v[84:87]
	v_mfma_f32_16x16x32_bf16 v[80:83], v[194:197], v[218:221], v[80:83]
	v_mfma_f32_16x16x32_bf16 v[68:71], v[186:189], v[226:229], v[68:71]
	v_mfma_f32_16x16x32_bf16 v[64:67], v[194:197], v[226:229], v[64:67]
	s_setprio 0
	s_barrier
	s_mov_b32 m0, s84
	v_lshl_add_u64 v[230:231], v[230:231], 0, s[20:21]
	ds_read_b128 v[198:201], v150 offset:49152
	ds_read_b128 v[202:205], v150 offset:50176
	ds_read_b128 v[206:209], v150 offset:51200
	ds_read_b128 v[210:213], v150 offset:52224
	ds_read_b128 v[214:217], v150 offset:53248
	ds_read_b128 v[218:221], v150 offset:54272
	ds_read_b128 v[222:225], v150 offset:55296
	ds_read_b128 v[226:229], v150 offset:56320
	global_load_lds_dwordx4 v[230:231], off
	v_lshl_add_u64 v[230:231], v[232:233], 0, s[20:21]
	s_mov_b32 m0, s85
	s_nop 0
	global_load_lds_dwordx4 v[230:231], off
	v_lshl_add_u64 v[230:231], v[234:235], 0, s[20:21]
	s_mov_b32 m0, s88
	s_nop 0
	global_load_lds_dwordx4 v[230:231], off
	v_lshl_add_u64 v[230:231], v[236:237], 0, s[20:21]
	s_mov_b32 m0, s89
	s_nop 0
	global_load_lds_dwordx4 v[230:231], off
	v_lshl_add_u64 v[230:231], v[238:239], 0, s[20:21]
	s_mov_b32 m0, s86
	s_nop 0
	global_load_lds_dwordx4 v[230:231], off
	v_lshl_add_u64 v[230:231], v[240:241], 0, s[20:21]
	s_mov_b32 m0, s87
	s_nop 0
	global_load_lds_dwordx4 v[230:231], off
	s_waitcnt vmcnt(8)
	s_waitcnt lgkmcnt(0)
	s_barrier
	s_setprio 1
	s_waitcnt lgkmcnt(0)
	v_mfma_f32_16x16x32_bf16 v[60:63], v[144:147], v[198:201], v[60:63]
	v_mfma_f32_16x16x32_bf16 v[56:59], v[174:177], v[198:201], v[56:59]
	v_mfma_f32_16x16x32_bf16 v[44:47], v[144:147], v[206:209], v[44:47]
	v_mfma_f32_16x16x32_bf16 v[40:43], v[174:177], v[206:209], v[40:43]
	v_mfma_f32_16x16x32_bf16 v[28:31], v[144:147], v[214:217], v[28:31]
	v_mfma_f32_16x16x32_bf16 v[24:27], v[174:177], v[214:217], v[24:27]
	v_mfma_f32_16x16x32_bf16 v[12:15], v[144:147], v[222:225], v[12:15]
	v_mfma_f32_16x16x32_bf16 v[8:11], v[174:177], v[222:225], v[8:11]
	v_mfma_f32_16x16x32_bf16 v[60:63], v[170:173], v[202:205], v[60:63]
	v_mfma_f32_16x16x32_bf16 v[56:59], v[178:181], v[202:205], v[56:59]
	v_mfma_f32_16x16x32_bf16 v[44:47], v[170:173], v[210:213], v[44:47]
	v_mfma_f32_16x16x32_bf16 v[40:43], v[178:181], v[210:213], v[40:43]
	v_mfma_f32_16x16x32_bf16 v[28:31], v[170:173], v[218:221], v[28:31]
	v_mfma_f32_16x16x32_bf16 v[24:27], v[178:181], v[218:221], v[24:27]
	v_mfma_f32_16x16x32_bf16 v[12:15], v[170:173], v[226:229], v[12:15]
	v_mfma_f32_16x16x32_bf16 v[8:11], v[178:181], v[226:229], v[8:11]
	s_setprio 0
	s_setprio 1
	v_mfma_f32_16x16x32_bf16 v[52:55], v[182:185], v[198:201], v[52:55]
	v_mfma_f32_16x16x32_bf16 v[48:51], v[190:193], v[198:201], v[48:51]
	v_mfma_f32_16x16x32_bf16 v[36:39], v[182:185], v[206:209], v[36:39]
	v_mfma_f32_16x16x32_bf16 v[32:35], v[190:193], v[206:209], v[32:35]
	v_mfma_f32_16x16x32_bf16 v[20:23], v[182:185], v[214:217], v[20:23]
	v_mfma_f32_16x16x32_bf16 v[16:19], v[190:193], v[214:217], v[16:19]
	v_mfma_f32_16x16x32_bf16 v[4:7], v[182:185], v[222:225], v[4:7]
	v_mfma_f32_16x16x32_bf16 v[0:3], v[190:193], v[222:225], v[0:3]
	v_mfma_f32_16x16x32_bf16 v[52:55], v[186:189], v[202:205], v[52:55]
	v_mfma_f32_16x16x32_bf16 v[48:51], v[194:197], v[202:205], v[48:51]
	v_mfma_f32_16x16x32_bf16 v[36:39], v[186:189], v[210:213], v[36:39]
	v_mfma_f32_16x16x32_bf16 v[32:35], v[194:197], v[210:213], v[32:35]
	v_mfma_f32_16x16x32_bf16 v[20:23], v[186:189], v[218:221], v[20:23]
	v_mfma_f32_16x16x32_bf16 v[16:19], v[194:197], v[218:221], v[16:19]
	v_mfma_f32_16x16x32_bf16 v[4:7], v[186:189], v[226:229], v[4:7]
	v_mfma_f32_16x16x32_bf16 v[0:3], v[194:197], v[226:229], v[0:3]
	s_setprio 0
	s_barrier
	s_add_u32 s52, s52, 0x100
	s_addc_u32 s53, s53, 0
	s_add_u32 s51, s51, 0x100
	s_addc_u32 s77, s77, 0
	s_cmp_ge_i32 s78, s90
	s_mov_b32 s54, s78
	s_cbranch_scc0 .LBB0_1832
	s_mov_b64 s[64:65], s[82:83]
